# combination: static K-loop priority + back-edge hoist + saddr LDS-DMA addresses + P7 16-byte merged stores
# speedup vs baseline: 1.0083x; 1.0083x over previous
.Lsprio_p2:
.LBB0_212:
	ds_read_b128 v[128:131], v175
	ds_read_b128 v[132:135], v175 offset:1024
	ds_read_b128 v[136:139], v175 offset:2048
	ds_read_b128 v[140:143], v175 offset:3072
	ds_read_b128 v[166:169], v176
	ds_read_b128 v[182:185], v176 offset:1024
	ds_read_b128 v[186:189], v176 offset:2048
	ds_read_b128 v[190:193], v176 offset:3072
	s_add_u32 s36, s0, 0xfffc0080
	s_addc_u32 s37, s1, -1
	s_cmp_eq_u32 s45, 12
	s_cselect_b32 s39, s40, s37
	s_cselect_b32 s38, s41, s36
	s_cselect_b32 s37, s27, s44
	s_cselect_b32 s36, s42, s43
	s_add_i32 m0, s35, 0xc000
	ds_read_b128 v[194:197], v177
	ds_read_b128 v[198:201], v177 offset:1024
	ds_read_b128 v[202:205], v177 offset:2048
	ds_read_b128 v[210:213], v177 offset:3072
	ds_read_b128 v[214:217], v177 offset:4096
	ds_read_b128 v[218:221], v177 offset:5120
	ds_read_b128 v[222:225], v177 offset:6144
	ds_read_b128 v[226:229], v177 offset:7168
	global_load_lds_dwordx4 v156, s[0:1]
	s_add_i32 m0, s35, 0xe000
	s_nop 0
	global_load_lds_dwordx4 v158, s[0:1]
	s_waitcnt vmcnt(8)
	s_waitcnt lgkmcnt(0)
	s_barrier
	s_waitcnt lgkmcnt(0)
	v_mfma_f32_16x16x32_bf16 v[124:127], v[128:131], v[194:197], v[124:127]
	v_mfma_f32_16x16x32_bf16 v[120:123], v[136:139], v[194:197], v[120:123]
	v_mfma_f32_16x16x32_bf16 v[112:115], v[128:131], v[202:205], v[112:115]
	v_mfma_f32_16x16x32_bf16 v[104:107], v[136:139], v[202:205], v[104:107]
	v_mfma_f32_16x16x32_bf16 v[96:99], v[128:131], v[214:217], v[96:99]
	v_mfma_f32_16x16x32_bf16 v[88:91], v[136:139], v[214:217], v[88:91]
	v_mfma_f32_16x16x32_bf16 v[80:83], v[128:131], v[222:225], v[80:83]
	v_mfma_f32_16x16x32_bf16 v[72:75], v[136:139], v[222:225], v[72:75]
	v_mfma_f32_16x16x32_bf16 v[124:127], v[132:135], v[198:201], v[124:127]
	v_mfma_f32_16x16x32_bf16 v[120:123], v[140:143], v[198:201], v[120:123]
	v_mfma_f32_16x16x32_bf16 v[112:115], v[132:135], v[210:213], v[112:115]
	v_mfma_f32_16x16x32_bf16 v[104:107], v[140:143], v[210:213], v[104:107]
	v_mfma_f32_16x16x32_bf16 v[96:99], v[132:135], v[218:221], v[96:99]
	v_mfma_f32_16x16x32_bf16 v[88:91], v[140:143], v[218:221], v[88:91]
	v_mfma_f32_16x16x32_bf16 v[80:83], v[132:135], v[226:229], v[80:83]
	v_mfma_f32_16x16x32_bf16 v[72:75], v[140:143], v[226:229], v[72:75]
	v_mfma_f32_16x16x32_bf16 v[116:119], v[166:169], v[194:197], v[116:119]
	v_mfma_f32_16x16x32_bf16 v[108:111], v[186:189], v[194:197], v[108:111]
	v_mfma_f32_16x16x32_bf16 v[100:103], v[166:169], v[202:205], v[100:103]
	v_mfma_f32_16x16x32_bf16 v[92:95], v[186:189], v[202:205], v[92:95]
	v_mfma_f32_16x16x32_bf16 v[84:87], v[166:169], v[214:217], v[84:87]
	v_mfma_f32_16x16x32_bf16 v[76:79], v[186:189], v[214:217], v[76:79]
	v_mfma_f32_16x16x32_bf16 v[68:71], v[166:169], v[222:225], v[68:71]
	v_mfma_f32_16x16x32_bf16 v[64:67], v[186:189], v[222:225], v[64:67]
	v_mfma_f32_16x16x32_bf16 v[116:119], v[182:185], v[198:201], v[116:119]
	v_mfma_f32_16x16x32_bf16 v[108:111], v[190:193], v[198:201], v[108:111]
	v_mfma_f32_16x16x32_bf16 v[100:103], v[182:185], v[210:213], v[100:103]
	v_mfma_f32_16x16x32_bf16 v[92:95], v[190:193], v[210:213], v[92:95]
	v_mfma_f32_16x16x32_bf16 v[84:87], v[182:185], v[218:221], v[84:87]
	v_mfma_f32_16x16x32_bf16 v[76:79], v[190:193], v[218:221], v[76:79]
	v_mfma_f32_16x16x32_bf16 v[68:71], v[182:185], v[226:229], v[68:71]
	v_mfma_f32_16x16x32_bf16 v[64:67], v[190:193], v[226:229], v[64:67]
	s_barrier
	s_add_i32 s73, s64, s3
	v_lshl_add_u64 v[170:171], s[36:37], 0, v[146:147]
	s_mov_b32 m0, s73
	ds_read_b128 v[194:197], v177 offset:16384
	ds_read_b128 v[198:201], v177 offset:17408
	ds_read_b128 v[202:205], v177 offset:18432
	ds_read_b128 v[210:213], v177 offset:19456
	ds_read_b128 v[214:217], v177 offset:20480
	ds_read_b128 v[218:221], v177 offset:21504
	ds_read_b128 v[222:225], v177 offset:22528
	ds_read_b128 v[226:229], v177 offset:23552
	global_load_lds_dwordx4 v146, s[36:37]
	s_add_i32 m0, s73, 0x2000
	s_add_u32 s74, s36, 0x40000
	v_lshl_add_u64 v[206:207], s[36:37], 0, v[150:151]
	s_addc_u32 s75, s37, 0
	s_add_i32 s73, s65, s3
	global_load_lds_dwordx4 v150, s[36:37]
	s_mov_b32 m0, s73
	v_lshl_add_u64 v[232:233], s[38:39], 0, v[148:149]
	global_load_lds_dwordx4 v146, s[74:75]
	s_add_i32 m0, s73, 0x2000
	s_nop 0
	global_load_lds_dwordx4 v150, s[74:75]
	v_lshl_add_u64 v[230:231], s[38:39], 0, v[144:145]
	s_mov_b32 m0, s35
	s_nop 0
	global_load_lds_dwordx4 v144, s[38:39]
	s_mov_b32 m0, s46
	s_nop 0
	global_load_lds_dwordx4 v148, s[38:39]
	s_waitcnt vmcnt(8)
	s_waitcnt lgkmcnt(0)
	s_barrier
	s_waitcnt lgkmcnt(0)
	v_mfma_f32_16x16x32_bf16 v[60:63], v[128:131], v[194:197], v[60:63]
	v_mfma_f32_16x16x32_bf16 v[56:59], v[136:139], v[194:197], v[56:59]
	v_mfma_f32_16x16x32_bf16 v[48:51], v[128:131], v[202:205], v[48:51]
	v_mfma_f32_16x16x32_bf16 v[44:47], v[136:139], v[202:205], v[44:47]
	v_mfma_f32_16x16x32_bf16 v[32:35], v[128:131], v[214:217], v[32:35]
	v_mfma_f32_16x16x32_bf16 v[28:31], v[136:139], v[214:217], v[28:31]
	v_mfma_f32_16x16x32_bf16 v[16:19], v[128:131], v[222:225], v[16:19]
	v_mfma_f32_16x16x32_bf16 v[12:15], v[136:139], v[222:225], v[12:15]
	v_mfma_f32_16x16x32_bf16 v[60:63], v[132:135], v[198:201], v[60:63]
	v_mfma_f32_16x16x32_bf16 v[56:59], v[140:143], v[198:201], v[56:59]
	v_mfma_f32_16x16x32_bf16 v[48:51], v[132:135], v[210:213], v[48:51]
	v_mfma_f32_16x16x32_bf16 v[44:47], v[140:143], v[210:213], v[44:47]
	v_mfma_f32_16x16x32_bf16 v[32:35], v[132:135], v[218:221], v[32:35]
	v_mfma_f32_16x16x32_bf16 v[28:31], v[140:143], v[218:221], v[28:31]
	v_mfma_f32_16x16x32_bf16 v[16:19], v[132:135], v[226:229], v[16:19]
	v_mfma_f32_16x16x32_bf16 v[12:15], v[140:143], v[226:229], v[12:15]
	v_mfma_f32_16x16x32_bf16 v[52:55], v[166:169], v[194:197], v[52:55]
	v_mfma_f32_16x16x32_bf16 v[40:43], v[186:189], v[194:197], v[40:43]
	v_mfma_f32_16x16x32_bf16 v[36:39], v[166:169], v[202:205], v[36:39]
	v_mfma_f32_16x16x32_bf16 v[24:27], v[186:189], v[202:205], v[24:27]
	v_mfma_f32_16x16x32_bf16 v[20:23], v[166:169], v[214:217], v[20:23]
	v_mfma_f32_16x16x32_bf16 v[8:11], v[186:189], v[214:217], v[8:11]
	v_mfma_f32_16x16x32_bf16 v[4:7], v[166:169], v[222:225], v[4:7]
	v_mfma_f32_16x16x32_bf16 v[0:3], v[186:189], v[222:225], v[0:3]
	v_mfma_f32_16x16x32_bf16 v[52:55], v[182:185], v[198:201], v[52:55]
	v_mfma_f32_16x16x32_bf16 v[40:43], v[190:193], v[198:201], v[40:43]
	v_mfma_f32_16x16x32_bf16 v[36:39], v[182:185], v[210:213], v[36:39]
	v_mfma_f32_16x16x32_bf16 v[24:27], v[190:193], v[210:213], v[24:27]
	v_mfma_f32_16x16x32_bf16 v[20:23], v[182:185], v[218:221], v[20:23]
	v_mfma_f32_16x16x32_bf16 v[8:11], v[190:193], v[218:221], v[8:11]
	v_mfma_f32_16x16x32_bf16 v[4:7], v[182:185], v[226:229], v[4:7]
	v_mfma_f32_16x16x32_bf16 v[0:3], v[190:193], v[226:229], v[0:3]
	s_barrier
	s_add_i32 s73, 0, 0x18000
	s_add_i32 s74, 0, 0x1c000
	v_add_u32_e32 v140, s73, v173
	v_add_u32_e32 v152, s74, v173
	ds_read_b128 v[128:131], v140
	ds_read_b128 v[132:135], v140 offset:1024
	ds_read_b128 v[136:139], v140 offset:2048
	ds_read_b128 v[140:143], v140 offset:3072
	ds_read_b128 v[166:169], v152
	ds_read_b128 v[182:185], v152 offset:1024
	ds_read_b128 v[186:189], v152 offset:2048
	ds_read_b128 v[190:193], v152 offset:3072
	s_add_u32 s38, s38, 0x40000
	s_addc_u32 s39, s39, 0
	s_mov_b32 m0, s47
	ds_read_b128 v[194:197], v177 offset:32768
	ds_read_b128 v[198:201], v177 offset:33792
	ds_read_b128 v[202:205], v177 offset:34816
	ds_read_b128 v[210:213], v177 offset:35840
	ds_read_b128 v[214:217], v177 offset:36864
	ds_read_b128 v[218:221], v177 offset:37888
	ds_read_b128 v[222:225], v177 offset:38912
	ds_read_b128 v[226:229], v177 offset:39936
	global_load_lds_dwordx4 v144, s[38:39]
	s_mov_b32 m0, s48
	s_nop 0
	global_load_lds_dwordx4 v148, s[38:39]
	s_waitcnt vmcnt(8)
	s_waitcnt lgkmcnt(0)
	s_barrier
	s_waitcnt lgkmcnt(0)
	v_mfma_f32_16x16x32_bf16 v[124:127], v[128:131], v[194:197], v[124:127]
	v_mfma_f32_16x16x32_bf16 v[120:123], v[136:139], v[194:197], v[120:123]
	v_mfma_f32_16x16x32_bf16 v[112:115], v[128:131], v[202:205], v[112:115]
	v_mfma_f32_16x16x32_bf16 v[104:107], v[136:139], v[202:205], v[104:107]
	v_mfma_f32_16x16x32_bf16 v[96:99], v[128:131], v[214:217], v[96:99]
	v_mfma_f32_16x16x32_bf16 v[88:91], v[136:139], v[214:217], v[88:91]
	v_mfma_f32_16x16x32_bf16 v[80:83], v[128:131], v[222:225], v[80:83]
	v_mfma_f32_16x16x32_bf16 v[72:75], v[136:139], v[222:225], v[72:75]
	v_mfma_f32_16x16x32_bf16 v[124:127], v[132:135], v[198:201], v[124:127]
	v_mfma_f32_16x16x32_bf16 v[120:123], v[140:143], v[198:201], v[120:123]
	v_mfma_f32_16x16x32_bf16 v[112:115], v[132:135], v[210:213], v[112:115]
	v_mfma_f32_16x16x32_bf16 v[104:107], v[140:143], v[210:213], v[104:107]
	v_mfma_f32_16x16x32_bf16 v[96:99], v[132:135], v[218:221], v[96:99]
	v_mfma_f32_16x16x32_bf16 v[88:91], v[140:143], v[218:221], v[88:91]
	v_mfma_f32_16x16x32_bf16 v[80:83], v[132:135], v[226:229], v[80:83]
	v_mfma_f32_16x16x32_bf16 v[72:75], v[140:143], v[226:229], v[72:75]
	v_mfma_f32_16x16x32_bf16 v[116:119], v[166:169], v[194:197], v[116:119]
	v_mfma_f32_16x16x32_bf16 v[108:111], v[186:189], v[194:197], v[108:111]
	v_mfma_f32_16x16x32_bf16 v[100:103], v[166:169], v[202:205], v[100:103]
	v_mfma_f32_16x16x32_bf16 v[92:95], v[186:189], v[202:205], v[92:95]
	v_mfma_f32_16x16x32_bf16 v[84:87], v[166:169], v[214:217], v[84:87]
	v_mfma_f32_16x16x32_bf16 v[76:79], v[186:189], v[214:217], v[76:79]
	v_mfma_f32_16x16x32_bf16 v[68:71], v[166:169], v[222:225], v[68:71]
	v_mfma_f32_16x16x32_bf16 v[64:67], v[186:189], v[222:225], v[64:67]
	v_mfma_f32_16x16x32_bf16 v[116:119], v[182:185], v[198:201], v[116:119]
	v_mfma_f32_16x16x32_bf16 v[108:111], v[190:193], v[198:201], v[108:111]
	v_mfma_f32_16x16x32_bf16 v[100:103], v[182:185], v[210:213], v[100:103]
	v_mfma_f32_16x16x32_bf16 v[92:95], v[190:193], v[210:213], v[92:95]
	v_mfma_f32_16x16x32_bf16 v[84:87], v[182:185], v[218:221], v[84:87]
	v_mfma_f32_16x16x32_bf16 v[76:79], v[190:193], v[218:221], v[76:79]
	v_mfma_f32_16x16x32_bf16 v[68:71], v[182:185], v[226:229], v[68:71]
	v_mfma_f32_16x16x32_bf16 v[64:67], v[190:193], v[226:229], v[64:67]
	s_barrier
	s_add_i32 s38, s73, s3
	v_lshl_add_u64 v[170:171], v[170:171], 0, s[18:19]
	s_mov_b32 m0, s38
	ds_read_b128 v[194:197], v177 offset:49152
	ds_read_b128 v[198:201], v177 offset:50176
	ds_read_b128 v[202:205], v177 offset:51200
	ds_read_b128 v[210:213], v177 offset:52224
	ds_read_b128 v[214:217], v177 offset:53248
	ds_read_b128 v[218:221], v177 offset:54272
	ds_read_b128 v[222:225], v177 offset:55296
	ds_read_b128 v[226:229], v177 offset:56320
	global_load_lds_dwordx4 v[170:171], off
	s_add_i32 m0, s38, 0x2000
	s_add_u32 s36, s36, 0x40080
	v_lshl_add_u64 v[206:207], v[206:207], 0, s[18:19]
	s_addc_u32 s37, s37, 0
	s_add_i32 s38, s74, s3
	global_load_lds_dwordx4 v[206:207], off
	s_mov_b32 m0, s38
	s_nop 0
	global_load_lds_dwordx4 v146, s[36:37]
	s_add_i32 m0, s38, 0x2000
	s_nop 0
	global_load_lds_dwordx4 v150, s[36:37]
	v_lshl_add_u64 v[230:231], v[230:231], 0, s[18:19]
	s_mov_b32 m0, s50
	s_nop 0
	global_load_lds_dwordx4 v[230:231], off
	v_lshl_add_u64 v[232:233], v[232:233], 0, s[18:19]
	s_mov_b32 m0, s51
	s_nop 0
	global_load_lds_dwordx4 v[232:233], off
	s_waitcnt vmcnt(8)
	s_waitcnt lgkmcnt(0)
	s_barrier
	s_waitcnt lgkmcnt(0)
	v_mfma_f32_16x16x32_bf16 v[60:63], v[128:131], v[194:197], v[60:63]
	v_mfma_f32_16x16x32_bf16 v[56:59], v[136:139], v[194:197], v[56:59]
	v_mfma_f32_16x16x32_bf16 v[48:51], v[128:131], v[202:205], v[48:51]
	v_mfma_f32_16x16x32_bf16 v[44:47], v[136:139], v[202:205], v[44:47]
	v_mfma_f32_16x16x32_bf16 v[32:35], v[128:131], v[214:217], v[32:35]
	v_mfma_f32_16x16x32_bf16 v[28:31], v[136:139], v[214:217], v[28:31]
	v_mfma_f32_16x16x32_bf16 v[16:19], v[128:131], v[222:225], v[16:19]
	v_mfma_f32_16x16x32_bf16 v[12:15], v[136:139], v[222:225], v[12:15]
	v_mfma_f32_16x16x32_bf16 v[60:63], v[132:135], v[198:201], v[60:63]
	s_add_i32 s45, s45, 2
	s_add_u32 s0, s0, 0x100
	s_addc_u32 s1, s1, 0
	s_add_u32 s43, s43, 0x100
	s_addc_u32 s44, s44, 0
	s_cmp_gt_u32 s45, 13
	v_mfma_f32_16x16x32_bf16 v[56:59], v[140:143], v[198:201], v[56:59]
	v_mfma_f32_16x16x32_bf16 v[48:51], v[132:135], v[210:213], v[48:51]
	v_mfma_f32_16x16x32_bf16 v[44:47], v[140:143], v[210:213], v[44:47]
	v_mfma_f32_16x16x32_bf16 v[32:35], v[132:135], v[218:221], v[32:35]
	v_mfma_f32_16x16x32_bf16 v[28:31], v[140:143], v[218:221], v[28:31]
	v_mfma_f32_16x16x32_bf16 v[16:19], v[132:135], v[226:229], v[16:19]
	v_mfma_f32_16x16x32_bf16 v[12:15], v[140:143], v[226:229], v[12:15]
	v_mfma_f32_16x16x32_bf16 v[52:55], v[166:169], v[194:197], v[52:55]
	v_mfma_f32_16x16x32_bf16 v[40:43], v[186:189], v[194:197], v[40:43]
	v_mfma_f32_16x16x32_bf16 v[36:39], v[166:169], v[202:205], v[36:39]
	v_mfma_f32_16x16x32_bf16 v[24:27], v[186:189], v[202:205], v[24:27]
	v_mfma_f32_16x16x32_bf16 v[20:23], v[166:169], v[214:217], v[20:23]
	v_mfma_f32_16x16x32_bf16 v[8:11], v[186:189], v[214:217], v[8:11]
	v_mfma_f32_16x16x32_bf16 v[4:7], v[166:169], v[222:225], v[4:7]
	v_mfma_f32_16x16x32_bf16 v[0:3], v[186:189], v[222:225], v[0:3]
	v_mfma_f32_16x16x32_bf16 v[52:55], v[182:185], v[198:201], v[52:55]
	v_mfma_f32_16x16x32_bf16 v[40:43], v[190:193], v[198:201], v[40:43]
	v_mfma_f32_16x16x32_bf16 v[36:39], v[182:185], v[210:213], v[36:39]
	v_mfma_f32_16x16x32_bf16 v[24:27], v[190:193], v[210:213], v[24:27]
	v_mfma_f32_16x16x32_bf16 v[20:23], v[182:185], v[218:221], v[20:23]
	v_mfma_f32_16x16x32_bf16 v[8:11], v[190:193], v[218:221], v[8:11]
	v_mfma_f32_16x16x32_bf16 v[4:7], v[182:185], v[226:229], v[4:7]
	v_mfma_f32_16x16x32_bf16 v[0:3], v[190:193], v[226:229], v[0:3]
	s_barrier
	s_cbranch_scc0 .LBB0_212
	s_setprio 0
	s_and_b64 vcc, exec, s[20:21]
	s_cbranch_vccz .LBB0_215
	s_barrier

.LBB0_502:
	v_add_u32_e32 v1, s65, v181
	ds_read_b128 v[132:135], v1
	ds_read_b128 v[136:139], v1 offset:1024
	ds_read_b128 v[140:143], v1 offset:2048
	ds_read_b128 v[144:147], v1 offset:3072
	v_add_u32_e32 v1, s66, v181
	s_add_u32 s42, s38, s40
	ds_read_b128 v[148:151], v1
	ds_read_b128 v[152:155], v1 offset:1024
	ds_read_b128 v[184:187], v1 offset:2048
	ds_read_b128 v[188:191], v1 offset:3072
	s_addc_u32 s43, s39, s41
	s_add_u32 s42, s42, 0x100
	s_addc_u32 s43, s43, 0
	s_add_u32 s74, s71, s40
	s_addc_u32 s75, s72, s41
	s_cmpk_eq_i32 s40, 0x700
	s_cselect_b32 s45, s68, s43
	s_cselect_b32 s44, s69, s42
	s_cselect_b32 s43, s31, s75
	s_cselect_b32 s42, s70, s74
	v_lshl_add_u64 v[2:3], v[176:177], 0, s[40:41]
	s_add_i32 m0, s47, 0xc000
	ds_read_b128 v[192:195], v183
	ds_read_b128 v[196:199], v183 offset:1024
	ds_read_b128 v[200:203], v183 offset:2048
	ds_read_b128 v[204:207], v183 offset:3072
	ds_read_b128 v[210:213], v183 offset:4096
	ds_read_b128 v[214:217], v183 offset:5120
	ds_read_b128 v[218:221], v183 offset:6144
	ds_read_b128 v[222:225], v183 offset:7168
	global_load_lds_dwordx4 v[2:3], off
	v_lshl_add_u64 v[2:3], v[178:179], 0, s[40:41]
	s_add_i32 m0, s47, 0xe000
	s_nop 0
	global_load_lds_dwordx4 v[2:3], off
	s_waitcnt vmcnt(8)
	s_waitcnt lgkmcnt(0)
	s_barrier
	s_waitcnt lgkmcnt(0)
	v_mfma_f32_16x16x32_bf16 v[128:131], v[132:135], v[192:195], v[128:131]
	v_mfma_f32_16x16x32_bf16 v[124:127], v[140:143], v[192:195], v[124:127]
	v_mfma_f32_16x16x32_bf16 v[112:115], v[132:135], v[200:203], v[112:115]
	v_mfma_f32_16x16x32_bf16 v[108:111], v[140:143], v[200:203], v[108:111]
	v_mfma_f32_16x16x32_bf16 v[96:99], v[132:135], v[210:213], v[96:99]
	v_mfma_f32_16x16x32_bf16 v[92:95], v[140:143], v[210:213], v[92:95]
	v_mfma_f32_16x16x32_bf16 v[80:83], v[132:135], v[218:221], v[80:83]
	v_mfma_f32_16x16x32_bf16 v[76:79], v[140:143], v[218:221], v[76:79]
	v_mfma_f32_16x16x32_bf16 v[128:131], v[136:139], v[196:199], v[128:131]
	v_mfma_f32_16x16x32_bf16 v[124:127], v[144:147], v[196:199], v[124:127]
	v_mfma_f32_16x16x32_bf16 v[112:115], v[136:139], v[204:207], v[112:115]
	v_mfma_f32_16x16x32_bf16 v[108:111], v[144:147], v[204:207], v[108:111]
	v_mfma_f32_16x16x32_bf16 v[96:99], v[136:139], v[214:217], v[96:99]
	v_mfma_f32_16x16x32_bf16 v[92:95], v[144:147], v[214:217], v[92:95]
	v_mfma_f32_16x16x32_bf16 v[80:83], v[136:139], v[222:225], v[80:83]
	v_mfma_f32_16x16x32_bf16 v[76:79], v[144:147], v[222:225], v[76:79]
	v_mfma_f32_16x16x32_bf16 v[120:123], v[148:151], v[192:195], v[120:123]
	v_mfma_f32_16x16x32_bf16 v[116:119], v[184:187], v[192:195], v[116:119]
	v_mfma_f32_16x16x32_bf16 v[104:107], v[148:151], v[200:203], v[104:107]
	v_mfma_f32_16x16x32_bf16 v[100:103], v[184:187], v[200:203], v[100:103]
	v_mfma_f32_16x16x32_bf16 v[88:91], v[148:151], v[210:213], v[88:91]
	v_mfma_f32_16x16x32_bf16 v[84:87], v[184:187], v[210:213], v[84:87]
	v_mfma_f32_16x16x32_bf16 v[72:75], v[148:151], v[218:221], v[72:75]
	v_mfma_f32_16x16x32_bf16 v[68:71], v[184:187], v[218:221], v[68:71]
	v_mfma_f32_16x16x32_bf16 v[120:123], v[152:155], v[196:199], v[120:123]
	v_mfma_f32_16x16x32_bf16 v[116:119], v[188:191], v[196:199], v[116:119]
	v_mfma_f32_16x16x32_bf16 v[104:107], v[152:155], v[204:207], v[104:107]
	v_mfma_f32_16x16x32_bf16 v[100:103], v[188:191], v[204:207], v[100:103]
	v_mfma_f32_16x16x32_bf16 v[88:91], v[152:155], v[214:217], v[88:91]
	v_mfma_f32_16x16x32_bf16 v[84:87], v[188:191], v[214:217], v[84:87]
	v_mfma_f32_16x16x32_bf16 v[72:75], v[152:155], v[222:225], v[72:75]
	v_mfma_f32_16x16x32_bf16 v[68:71], v[188:191], v[222:225], v[68:71]
	s_barrier
	s_add_i32 s74, s65, s46
	v_lshl_add_u64 v[226:227], s[42:43], 0, v[158:159]
	s_mov_b32 m0, s74
	ds_read_b128 v[192:195], v183 offset:16384
	ds_read_b128 v[196:199], v183 offset:17408
	ds_read_b128 v[200:203], v183 offset:18432
	ds_read_b128 v[204:207], v183 offset:19456
	ds_read_b128 v[210:213], v183 offset:20480
	ds_read_b128 v[214:217], v183 offset:21504
	ds_read_b128 v[218:221], v183 offset:22528
	ds_read_b128 v[222:225], v183 offset:23552
	global_load_lds_dwordx4 v158, s[42:43]
	s_add_i32 m0, s74, 0x2000
	s_add_u32 s74, s42, 0x40000
	v_lshl_add_u64 v[228:229], s[42:43], 0, v[162:163]
	s_addc_u32 s75, s43, 0
	s_add_i32 s76, s66, s46
	global_load_lds_dwordx4 v162, s[42:43]
	s_mov_b32 m0, s76
	v_lshl_add_u64 v[230:231], s[44:45], 0, v[156:157]
	global_load_lds_dwordx4 v158, s[74:75]
	s_add_i32 m0, s76, 0x2000
	v_lshl_add_u64 v[232:233], s[44:45], 0, v[160:161]
	global_load_lds_dwordx4 v162, s[74:75]
	s_mov_b32 m0, s47
	s_nop 0
	global_load_lds_dwordx4 v156, s[44:45]
	s_mov_b32 m0, s48
	s_nop 0
	global_load_lds_dwordx4 v160, s[44:45]
	s_waitcnt vmcnt(8)
	s_waitcnt lgkmcnt(0)
	s_barrier
	s_waitcnt lgkmcnt(0)
	v_mfma_f32_16x16x32_bf16 v[64:67], v[132:135], v[192:195], v[64:67]
	v_mfma_f32_16x16x32_bf16 v[60:63], v[140:143], v[192:195], v[60:63]
	v_mfma_f32_16x16x32_bf16 v[48:51], v[132:135], v[200:203], v[48:51]
	v_mfma_f32_16x16x32_bf16 v[44:47], v[140:143], v[200:203], v[44:47]
	v_mfma_f32_16x16x32_bf16 v[32:35], v[132:135], v[210:213], v[32:35]
	v_mfma_f32_16x16x32_bf16 v[28:31], v[140:143], v[210:213], v[28:31]
	v_mfma_f32_16x16x32_bf16 v[16:19], v[132:135], v[218:221], v[16:19]
	v_mfma_f32_16x16x32_bf16 v[12:15], v[140:143], v[218:221], v[12:15]
	v_mfma_f32_16x16x32_bf16 v[64:67], v[136:139], v[196:199], v[64:67]
	v_mfma_f32_16x16x32_bf16 v[60:63], v[144:147], v[196:199], v[60:63]
	v_mfma_f32_16x16x32_bf16 v[48:51], v[136:139], v[204:207], v[48:51]
	v_mfma_f32_16x16x32_bf16 v[44:47], v[144:147], v[204:207], v[44:47]
	v_mfma_f32_16x16x32_bf16 v[32:35], v[136:139], v[214:217], v[32:35]
	v_mfma_f32_16x16x32_bf16 v[28:31], v[144:147], v[214:217], v[28:31]
	v_mfma_f32_16x16x32_bf16 v[16:19], v[136:139], v[222:225], v[16:19]
	v_mfma_f32_16x16x32_bf16 v[12:15], v[144:147], v[222:225], v[12:15]
	v_mfma_f32_16x16x32_bf16 v[56:59], v[148:151], v[192:195], v[56:59]
	v_mfma_f32_16x16x32_bf16 v[52:55], v[184:187], v[192:195], v[52:55]
	v_mfma_f32_16x16x32_bf16 v[40:43], v[148:151], v[200:203], v[40:43]
	v_mfma_f32_16x16x32_bf16 v[36:39], v[184:187], v[200:203], v[36:39]
	v_mfma_f32_16x16x32_bf16 v[24:27], v[148:151], v[210:213], v[24:27]
	v_mfma_f32_16x16x32_bf16 v[20:23], v[184:187], v[210:213], v[20:23]
	v_mfma_f32_16x16x32_bf16 v[8:11], v[148:151], v[218:221], v[8:11]
	v_mfma_f32_16x16x32_bf16 v[2:5], v[184:187], v[218:221], v[4:7]
	v_mfma_f32_16x16x32_bf16 v[56:59], v[152:155], v[196:199], v[56:59]
	v_mfma_f32_16x16x32_bf16 v[52:55], v[188:191], v[196:199], v[52:55]
	v_mfma_f32_16x16x32_bf16 v[40:43], v[152:155], v[204:207], v[40:43]
	v_mfma_f32_16x16x32_bf16 v[36:39], v[188:191], v[204:207], v[36:39]
	v_mfma_f32_16x16x32_bf16 v[24:27], v[152:155], v[214:217], v[24:27]
	v_mfma_f32_16x16x32_bf16 v[20:23], v[188:191], v[214:217], v[20:23]
	v_mfma_f32_16x16x32_bf16 v[8:11], v[152:155], v[222:225], v[8:11]
	v_mfma_f32_16x16x32_bf16 v[2:5], v[188:191], v[222:225], v[2:5]
	s_barrier
	s_add_i32 s74, 0, 0x18000
	v_add_u32_e32 v1, s74, v181
	s_add_i32 s75, 0, 0x1c000
	ds_read_b128 v[132:135], v1
	ds_read_b128 v[136:139], v1 offset:1024
	ds_read_b128 v[140:143], v1 offset:2048
	ds_read_b128 v[144:147], v1 offset:3072
	v_add_u32_e32 v1, s75, v181
	ds_read_b128 v[148:151], v1
	ds_read_b128 v[152:155], v1 offset:1024
	ds_read_b128 v[184:187], v1 offset:2048
	ds_read_b128 v[188:191], v1 offset:3072
	s_add_u32 s44, s44, 0x40000
	s_addc_u32 s45, s45, 0
	s_mov_b32 m0, s49
	ds_read_b128 v[192:195], v183 offset:32768
	ds_read_b128 v[196:199], v183 offset:33792
	ds_read_b128 v[200:203], v183 offset:34816
	ds_read_b128 v[204:207], v183 offset:35840
	ds_read_b128 v[210:213], v183 offset:36864
	ds_read_b128 v[214:217], v183 offset:37888
	ds_read_b128 v[218:221], v183 offset:38912
	ds_read_b128 v[222:225], v183 offset:39936
	global_load_lds_dwordx4 v156, s[44:45]
	s_mov_b32 m0, s50
	s_nop 0
	global_load_lds_dwordx4 v160, s[44:45]
	s_waitcnt vmcnt(8)
	s_waitcnt lgkmcnt(0)
	s_barrier
	s_waitcnt lgkmcnt(0)
	v_mfma_f32_16x16x32_bf16 v[128:131], v[132:135], v[192:195], v[128:131]
	v_mfma_f32_16x16x32_bf16 v[124:127], v[140:143], v[192:195], v[124:127]
	v_mfma_f32_16x16x32_bf16 v[112:115], v[132:135], v[200:203], v[112:115]
	v_mfma_f32_16x16x32_bf16 v[108:111], v[140:143], v[200:203], v[108:111]
	v_mfma_f32_16x16x32_bf16 v[96:99], v[132:135], v[210:213], v[96:99]
	v_mfma_f32_16x16x32_bf16 v[92:95], v[140:143], v[210:213], v[92:95]
	v_mfma_f32_16x16x32_bf16 v[80:83], v[132:135], v[218:221], v[80:83]
	v_mfma_f32_16x16x32_bf16 v[76:79], v[140:143], v[218:221], v[76:79]
	v_mfma_f32_16x16x32_bf16 v[128:131], v[136:139], v[196:199], v[128:131]
	v_mfma_f32_16x16x32_bf16 v[124:127], v[144:147], v[196:199], v[124:127]
	v_mfma_f32_16x16x32_bf16 v[112:115], v[136:139], v[204:207], v[112:115]
	v_mfma_f32_16x16x32_bf16 v[108:111], v[144:147], v[204:207], v[108:111]
	v_mfma_f32_16x16x32_bf16 v[96:99], v[136:139], v[214:217], v[96:99]
	v_mfma_f32_16x16x32_bf16 v[92:95], v[144:147], v[214:217], v[92:95]
	v_mfma_f32_16x16x32_bf16 v[80:83], v[136:139], v[222:225], v[80:83]
	v_mfma_f32_16x16x32_bf16 v[76:79], v[144:147], v[222:225], v[76:79]
	v_mfma_f32_16x16x32_bf16 v[120:123], v[148:151], v[192:195], v[120:123]
	v_mfma_f32_16x16x32_bf16 v[116:119], v[184:187], v[192:195], v[116:119]
	v_mfma_f32_16x16x32_bf16 v[104:107], v[148:151], v[200:203], v[104:107]
	v_mfma_f32_16x16x32_bf16 v[100:103], v[184:187], v[200:203], v[100:103]
	v_mfma_f32_16x16x32_bf16 v[88:91], v[148:151], v[210:213], v[88:91]
	v_mfma_f32_16x16x32_bf16 v[84:87], v[184:187], v[210:213], v[84:87]
	v_mfma_f32_16x16x32_bf16 v[72:75], v[148:151], v[218:221], v[72:75]
	v_mfma_f32_16x16x32_bf16 v[68:71], v[184:187], v[218:221], v[68:71]
	v_mfma_f32_16x16x32_bf16 v[120:123], v[152:155], v[196:199], v[120:123]
	v_mfma_f32_16x16x32_bf16 v[116:119], v[188:191], v[196:199], v[116:119]
	v_mfma_f32_16x16x32_bf16 v[104:107], v[152:155], v[204:207], v[104:107]
	v_mfma_f32_16x16x32_bf16 v[100:103], v[188:191], v[204:207], v[100:103]
	v_mfma_f32_16x16x32_bf16 v[88:91], v[152:155], v[214:217], v[88:91]
	v_mfma_f32_16x16x32_bf16 v[84:87], v[188:191], v[214:217], v[84:87]
	v_mfma_f32_16x16x32_bf16 v[72:75], v[152:155], v[222:225], v[72:75]
	v_mfma_f32_16x16x32_bf16 v[68:71], v[188:191], v[222:225], v[68:71]
	s_barrier
	s_add_i32 s44, s74, s46
	v_lshl_add_u64 v[226:227], v[226:227], 0, s[14:15]
	s_mov_b32 m0, s44
	ds_read_b128 v[192:195], v183 offset:49152
	ds_read_b128 v[196:199], v183 offset:50176
	ds_read_b128 v[200:203], v183 offset:51200
	ds_read_b128 v[204:207], v183 offset:52224
	ds_read_b128 v[210:213], v183 offset:53248
	ds_read_b128 v[214:217], v183 offset:54272
	ds_read_b128 v[218:221], v183 offset:55296
	ds_read_b128 v[222:225], v183 offset:56320
	global_load_lds_dwordx4 v[226:227], off
	s_add_i32 m0, s44, 0x2000
	s_add_u32 s42, s42, 0x40080
	v_lshl_add_u64 v[228:229], v[228:229], 0, s[14:15]
	s_addc_u32 s43, s43, 0
	s_add_i32 s44, s75, s46
	global_load_lds_dwordx4 v[228:229], off
	s_mov_b32 m0, s44
	s_nop 0
	global_load_lds_dwordx4 v158, s[42:43]
	s_add_i32 m0, s44, 0x2000
	s_nop 0
	global_load_lds_dwordx4 v162, s[42:43]
	v_lshl_add_u64 v[230:231], v[230:231], 0, s[14:15]
	s_mov_b32 m0, s62
	s_nop 0
	global_load_lds_dwordx4 v[230:231], off
	v_lshl_add_u64 v[232:233], v[232:233], 0, s[14:15]
	s_mov_b32 m0, s63
	s_nop 0
	global_load_lds_dwordx4 v[232:233], off
	s_waitcnt vmcnt(8)
	s_waitcnt lgkmcnt(0)
	s_barrier
	s_waitcnt lgkmcnt(0)
	v_mfma_f32_16x16x32_bf16 v[64:67], v[132:135], v[192:195], v[64:67]
	v_mfma_f32_16x16x32_bf16 v[60:63], v[140:143], v[192:195], v[60:63]
	v_mfma_f32_16x16x32_bf16 v[48:51], v[132:135], v[200:203], v[48:51]
	v_mfma_f32_16x16x32_bf16 v[44:47], v[140:143], v[200:203], v[44:47]
	v_mfma_f32_16x16x32_bf16 v[32:35], v[132:135], v[210:213], v[32:35]
	v_mfma_f32_16x16x32_bf16 v[28:31], v[140:143], v[210:213], v[28:31]
	v_mfma_f32_16x16x32_bf16 v[16:19], v[132:135], v[218:221], v[16:19]
	v_mfma_f32_16x16x32_bf16 v[12:15], v[140:143], v[218:221], v[12:15]
	v_mfma_f32_16x16x32_bf16 v[64:67], v[136:139], v[196:199], v[64:67]
	v_mfma_f32_16x16x32_bf16 v[60:63], v[144:147], v[196:199], v[60:63]
	v_mfma_f32_16x16x32_bf16 v[48:51], v[136:139], v[204:207], v[48:51]
	v_mfma_f32_16x16x32_bf16 v[44:47], v[144:147], v[204:207], v[44:47]
	v_mfma_f32_16x16x32_bf16 v[32:35], v[136:139], v[214:217], v[32:35]
	v_mfma_f32_16x16x32_bf16 v[28:31], v[144:147], v[214:217], v[28:31]
	v_mfma_f32_16x16x32_bf16 v[16:19], v[136:139], v[222:225], v[16:19]
	v_mfma_f32_16x16x32_bf16 v[12:15], v[144:147], v[222:225], v[12:15]
	v_mfma_f32_16x16x32_bf16 v[56:59], v[148:151], v[192:195], v[56:59]
	v_mfma_f32_16x16x32_bf16 v[52:55], v[184:187], v[192:195], v[52:55]
	v_mfma_f32_16x16x32_bf16 v[40:43], v[148:151], v[200:203], v[40:43]
	v_mfma_f32_16x16x32_bf16 v[36:39], v[184:187], v[200:203], v[36:39]
	v_mfma_f32_16x16x32_bf16 v[24:27], v[148:151], v[210:213], v[24:27]
	v_mfma_f32_16x16x32_bf16 v[20:23], v[184:187], v[210:213], v[20:23]
	v_mfma_f32_16x16x32_bf16 v[6:9], v[148:151], v[218:221], v[8:11]
	v_mfma_f32_16x16x32_bf16 v[2:5], v[184:187], v[218:221], v[2:5]
	v_mfma_f32_16x16x32_bf16 v[56:59], v[152:155], v[196:199], v[56:59]
	v_mfma_f32_16x16x32_bf16 v[52:55], v[188:191], v[196:199], v[52:55]
	v_mfma_f32_16x16x32_bf16 v[40:43], v[152:155], v[204:207], v[40:43]
	v_mfma_f32_16x16x32_bf16 v[36:39], v[188:191], v[204:207], v[36:39]
	v_mfma_f32_16x16x32_bf16 v[24:27], v[152:155], v[214:217], v[24:27]
	v_mfma_f32_16x16x32_bf16 v[20:23], v[188:191], v[214:217], v[20:23]
	v_mfma_f32_16x16x32_bf16 v[8:11], v[152:155], v[222:225], v[6:9]
	v_mfma_f32_16x16x32_bf16 v[4:7], v[188:191], v[222:225], v[2:5]
	s_barrier
	s_add_i32 s73, s73, 2
	s_add_u32 s40, s40, 0x100
	s_addc_u32 s41, s41, 0
	s_cmp_gt_u32 s73, 13
	s_cbranch_scc1 .LBB0_505

.Lsprio_p5:
.LBB0_586:
	ds_read_b128 v[144:147], v175
	ds_read_b128 v[148:151], v175 offset:1024
	ds_read_b128 v[152:155], v175 offset:2048
	ds_read_b128 v[156:159], v175 offset:3072
	ds_read_b128 v[160:163], v176
	ds_read_b128 v[164:167], v176 offset:1024
	ds_read_b128 v[168:171], v176 offset:2048
	ds_read_b128 v[180:183], v176 offset:3072
	s_add_u32 s28, s26, 0xfffc0080
	s_addc_u32 s29, s27, -1
	s_cmp_eq_u32 s63, 12
	s_cselect_b32 s31, s25, s29
	s_cselect_b32 s30, s51, s28
	s_cselect_b32 s29, s19, s62
	s_cselect_b32 s28, s54, s55
	s_add_i32 m0, s34, 0xc000
	ds_read_b128 v[184:187], v177
	ds_read_b128 v[188:191], v177 offset:1024
	ds_read_b128 v[192:195], v177 offset:2048
	ds_read_b128 v[196:199], v177 offset:3072
	ds_read_b128 v[200:203], v177 offset:4096
	ds_read_b128 v[204:207], v177 offset:5120
	ds_read_b128 v[210:213], v177 offset:6144
	ds_read_b128 v[214:217], v177 offset:7168
	global_load_lds_dwordx4 v136, s[26:27]
	s_add_i32 m0, s34, 0xe000
	s_nop 0
	global_load_lds_dwordx4 v138, s[26:27]
	s_waitcnt vmcnt(8)
	s_waitcnt lgkmcnt(0)
	s_barrier
	s_waitcnt lgkmcnt(0)
	v_mfma_f32_16x16x32_bf16 v[124:127], v[144:147], v[184:187], v[124:127]
	v_mfma_f32_16x16x32_bf16 v[120:123], v[152:155], v[184:187], v[120:123]
	v_mfma_f32_16x16x32_bf16 v[108:111], v[144:147], v[192:195], v[108:111]
	v_mfma_f32_16x16x32_bf16 v[104:107], v[152:155], v[192:195], v[104:107]
	v_mfma_f32_16x16x32_bf16 v[92:95], v[144:147], v[200:203], v[92:95]
	v_mfma_f32_16x16x32_bf16 v[88:91], v[152:155], v[200:203], v[88:91]
	v_mfma_f32_16x16x32_bf16 v[76:79], v[144:147], v[210:213], v[76:79]
	v_mfma_f32_16x16x32_bf16 v[72:75], v[152:155], v[210:213], v[72:75]
	v_mfma_f32_16x16x32_bf16 v[124:127], v[148:151], v[188:191], v[124:127]
	v_mfma_f32_16x16x32_bf16 v[120:123], v[156:159], v[188:191], v[120:123]
	v_mfma_f32_16x16x32_bf16 v[108:111], v[148:151], v[196:199], v[108:111]
	v_mfma_f32_16x16x32_bf16 v[104:107], v[156:159], v[196:199], v[104:107]
	v_mfma_f32_16x16x32_bf16 v[92:95], v[148:151], v[204:207], v[92:95]
	v_mfma_f32_16x16x32_bf16 v[88:91], v[156:159], v[204:207], v[88:91]
	v_mfma_f32_16x16x32_bf16 v[76:79], v[148:151], v[214:217], v[76:79]
	v_mfma_f32_16x16x32_bf16 v[72:75], v[156:159], v[214:217], v[72:75]
	v_mfma_f32_16x16x32_bf16 v[116:119], v[160:163], v[184:187], v[116:119]
	v_mfma_f32_16x16x32_bf16 v[112:115], v[168:171], v[184:187], v[112:115]
	v_mfma_f32_16x16x32_bf16 v[100:103], v[160:163], v[192:195], v[100:103]
	v_mfma_f32_16x16x32_bf16 v[96:99], v[168:171], v[192:195], v[96:99]
	v_mfma_f32_16x16x32_bf16 v[84:87], v[160:163], v[200:203], v[84:87]
	v_mfma_f32_16x16x32_bf16 v[80:83], v[168:171], v[200:203], v[80:83]
	v_mfma_f32_16x16x32_bf16 v[68:71], v[160:163], v[210:213], v[68:71]
	v_mfma_f32_16x16x32_bf16 v[64:67], v[168:171], v[210:213], v[64:67]
	v_mfma_f32_16x16x32_bf16 v[116:119], v[164:167], v[188:191], v[116:119]
	v_mfma_f32_16x16x32_bf16 v[112:115], v[180:183], v[188:191], v[112:115]
	v_mfma_f32_16x16x32_bf16 v[100:103], v[164:167], v[196:199], v[100:103]
	v_mfma_f32_16x16x32_bf16 v[96:99], v[180:183], v[196:199], v[96:99]
	v_mfma_f32_16x16x32_bf16 v[84:87], v[164:167], v[204:207], v[84:87]
	v_mfma_f32_16x16x32_bf16 v[80:83], v[180:183], v[204:207], v[80:83]
	v_mfma_f32_16x16x32_bf16 v[68:71], v[164:167], v[214:217], v[68:71]
	v_mfma_f32_16x16x32_bf16 v[64:67], v[180:183], v[214:217], v[64:67]
	s_barrier
	s_add_i32 s64, s47, s3
	v_lshl_add_u64 v[218:219], s[28:29], 0, v[130:131]
	s_mov_b32 m0, s64
	ds_read_b128 v[184:187], v177 offset:16384
	ds_read_b128 v[188:191], v177 offset:17408
	ds_read_b128 v[192:195], v177 offset:18432
	ds_read_b128 v[196:199], v177 offset:19456
	ds_read_b128 v[200:203], v177 offset:20480
	ds_read_b128 v[204:207], v177 offset:21504
	ds_read_b128 v[210:213], v177 offset:22528
	ds_read_b128 v[214:217], v177 offset:23552
	global_load_lds_dwordx4 v130, s[28:29]
	s_add_i32 m0, s64, 0x2000
	s_add_u32 s64, s28, 0x40000
	v_lshl_add_u64 v[220:221], s[28:29], 0, v[134:135]
	s_addc_u32 s65, s29, 0
	s_add_i32 s66, s48, s3
	global_load_lds_dwordx4 v134, s[28:29]
	s_mov_b32 m0, s66
	v_lshl_add_u64 v[224:225], s[30:31], 0, v[132:133]
	global_load_lds_dwordx4 v130, s[64:65]
	s_add_i32 m0, s66, 0x2000
	s_nop 0
	global_load_lds_dwordx4 v134, s[64:65]
	v_lshl_add_u64 v[222:223], s[30:31], 0, v[128:129]
	s_mov_b32 m0, s34
	s_nop 0
	global_load_lds_dwordx4 v128, s[30:31]
	s_mov_b32 m0, s35
	s_nop 0
	global_load_lds_dwordx4 v132, s[30:31]
	s_waitcnt vmcnt(8)
	s_waitcnt lgkmcnt(0)
	s_barrier
	s_waitcnt lgkmcnt(0)
	v_mfma_f32_16x16x32_bf16 v[60:63], v[144:147], v[184:187], v[60:63]
	v_mfma_f32_16x16x32_bf16 v[56:59], v[152:155], v[184:187], v[56:59]
	v_mfma_f32_16x16x32_bf16 v[44:47], v[144:147], v[192:195], v[44:47]
	v_mfma_f32_16x16x32_bf16 v[40:43], v[152:155], v[192:195], v[40:43]
	v_mfma_f32_16x16x32_bf16 v[28:31], v[144:147], v[200:203], v[28:31]
	v_mfma_f32_16x16x32_bf16 v[24:27], v[152:155], v[200:203], v[24:27]
	v_mfma_f32_16x16x32_bf16 v[12:15], v[144:147], v[210:213], v[12:15]
	v_mfma_f32_16x16x32_bf16 v[8:11], v[152:155], v[210:213], v[8:11]
	v_mfma_f32_16x16x32_bf16 v[60:63], v[148:151], v[188:191], v[60:63]
	v_mfma_f32_16x16x32_bf16 v[56:59], v[156:159], v[188:191], v[56:59]
	v_mfma_f32_16x16x32_bf16 v[44:47], v[148:151], v[196:199], v[44:47]
	v_mfma_f32_16x16x32_bf16 v[40:43], v[156:159], v[196:199], v[40:43]
	v_mfma_f32_16x16x32_bf16 v[28:31], v[148:151], v[204:207], v[28:31]
	v_mfma_f32_16x16x32_bf16 v[24:27], v[156:159], v[204:207], v[24:27]
	v_mfma_f32_16x16x32_bf16 v[12:15], v[148:151], v[214:217], v[12:15]
	v_mfma_f32_16x16x32_bf16 v[8:11], v[156:159], v[214:217], v[8:11]
	v_mfma_f32_16x16x32_bf16 v[52:55], v[160:163], v[184:187], v[52:55]
	v_mfma_f32_16x16x32_bf16 v[48:51], v[168:171], v[184:187], v[48:51]
	v_mfma_f32_16x16x32_bf16 v[36:39], v[160:163], v[192:195], v[36:39]
	v_mfma_f32_16x16x32_bf16 v[32:35], v[168:171], v[192:195], v[32:35]
	v_mfma_f32_16x16x32_bf16 v[20:23], v[160:163], v[200:203], v[20:23]
	v_mfma_f32_16x16x32_bf16 v[16:19], v[168:171], v[200:203], v[16:19]
	v_mfma_f32_16x16x32_bf16 v[4:7], v[160:163], v[210:213], v[4:7]
	v_mfma_f32_16x16x32_bf16 v[0:3], v[168:171], v[210:213], v[0:3]
	v_mfma_f32_16x16x32_bf16 v[52:55], v[164:167], v[188:191], v[52:55]
	v_mfma_f32_16x16x32_bf16 v[48:51], v[180:183], v[188:191], v[48:51]
	v_mfma_f32_16x16x32_bf16 v[36:39], v[164:167], v[196:199], v[36:39]
	v_mfma_f32_16x16x32_bf16 v[32:35], v[180:183], v[196:199], v[32:35]
	v_mfma_f32_16x16x32_bf16 v[20:23], v[164:167], v[204:207], v[20:23]
	v_mfma_f32_16x16x32_bf16 v[16:19], v[180:183], v[204:207], v[16:19]
	v_mfma_f32_16x16x32_bf16 v[4:7], v[164:167], v[214:217], v[4:7]
	v_mfma_f32_16x16x32_bf16 v[0:3], v[180:183], v[214:217], v[0:3]
	s_barrier
	s_add_i32 s64, 0, 0x18000
	s_add_i32 s65, 0, 0x1c000
	v_add_u32_e32 v156, s64, v173
	v_add_u32_e32 v179, s65, v173
	ds_read_b128 v[144:147], v156
	ds_read_b128 v[148:151], v156 offset:1024
	ds_read_b128 v[152:155], v156 offset:2048
	ds_read_b128 v[156:159], v156 offset:3072
	ds_read_b128 v[160:163], v179
	ds_read_b128 v[164:167], v179 offset:1024
	ds_read_b128 v[168:171], v179 offset:2048
	ds_read_b128 v[180:183], v179 offset:3072
	s_add_u32 s30, s30, 0x40000
	s_addc_u32 s31, s31, 0
	s_mov_b32 m0, s36
	ds_read_b128 v[184:187], v177 offset:32768
	ds_read_b128 v[188:191], v177 offset:33792
	ds_read_b128 v[192:195], v177 offset:34816
	ds_read_b128 v[196:199], v177 offset:35840
	ds_read_b128 v[200:203], v177 offset:36864
	ds_read_b128 v[204:207], v177 offset:37888
	ds_read_b128 v[210:213], v177 offset:38912
	ds_read_b128 v[214:217], v177 offset:39936
	global_load_lds_dwordx4 v128, s[30:31]
	s_mov_b32 m0, s37
	s_nop 0
	global_load_lds_dwordx4 v132, s[30:31]
	s_waitcnt vmcnt(8)
	s_waitcnt lgkmcnt(0)
	s_barrier
	s_waitcnt lgkmcnt(0)
	v_mfma_f32_16x16x32_bf16 v[124:127], v[144:147], v[184:187], v[124:127]
	v_mfma_f32_16x16x32_bf16 v[120:123], v[152:155], v[184:187], v[120:123]
	v_mfma_f32_16x16x32_bf16 v[108:111], v[144:147], v[192:195], v[108:111]
	v_mfma_f32_16x16x32_bf16 v[104:107], v[152:155], v[192:195], v[104:107]
	v_mfma_f32_16x16x32_bf16 v[92:95], v[144:147], v[200:203], v[92:95]
	v_mfma_f32_16x16x32_bf16 v[88:91], v[152:155], v[200:203], v[88:91]
	v_mfma_f32_16x16x32_bf16 v[76:79], v[144:147], v[210:213], v[76:79]
	v_mfma_f32_16x16x32_bf16 v[72:75], v[152:155], v[210:213], v[72:75]
	v_mfma_f32_16x16x32_bf16 v[124:127], v[148:151], v[188:191], v[124:127]
	v_mfma_f32_16x16x32_bf16 v[120:123], v[156:159], v[188:191], v[120:123]
	v_mfma_f32_16x16x32_bf16 v[108:111], v[148:151], v[196:199], v[108:111]
	v_mfma_f32_16x16x32_bf16 v[104:107], v[156:159], v[196:199], v[104:107]
	v_mfma_f32_16x16x32_bf16 v[92:95], v[148:151], v[204:207], v[92:95]
	v_mfma_f32_16x16x32_bf16 v[88:91], v[156:159], v[204:207], v[88:91]
	v_mfma_f32_16x16x32_bf16 v[76:79], v[148:151], v[214:217], v[76:79]
	v_mfma_f32_16x16x32_bf16 v[72:75], v[156:159], v[214:217], v[72:75]
	v_mfma_f32_16x16x32_bf16 v[116:119], v[160:163], v[184:187], v[116:119]
	v_mfma_f32_16x16x32_bf16 v[112:115], v[168:171], v[184:187], v[112:115]
	v_mfma_f32_16x16x32_bf16 v[100:103], v[160:163], v[192:195], v[100:103]
	v_mfma_f32_16x16x32_bf16 v[96:99], v[168:171], v[192:195], v[96:99]
	v_mfma_f32_16x16x32_bf16 v[84:87], v[160:163], v[200:203], v[84:87]
	v_mfma_f32_16x16x32_bf16 v[80:83], v[168:171], v[200:203], v[80:83]
	v_mfma_f32_16x16x32_bf16 v[68:71], v[160:163], v[210:213], v[68:71]
	v_mfma_f32_16x16x32_bf16 v[64:67], v[168:171], v[210:213], v[64:67]
	v_mfma_f32_16x16x32_bf16 v[116:119], v[164:167], v[188:191], v[116:119]
	v_mfma_f32_16x16x32_bf16 v[112:115], v[180:183], v[188:191], v[112:115]
	v_mfma_f32_16x16x32_bf16 v[100:103], v[164:167], v[196:199], v[100:103]
	v_mfma_f32_16x16x32_bf16 v[96:99], v[180:183], v[196:199], v[96:99]
	v_mfma_f32_16x16x32_bf16 v[84:87], v[164:167], v[204:207], v[84:87]
	v_mfma_f32_16x16x32_bf16 v[80:83], v[180:183], v[204:207], v[80:83]
	v_mfma_f32_16x16x32_bf16 v[68:71], v[164:167], v[214:217], v[68:71]
	v_mfma_f32_16x16x32_bf16 v[64:67], v[180:183], v[214:217], v[64:67]
	s_barrier
	s_add_i32 s30, s64, s3
	v_lshl_add_u64 v[218:219], v[218:219], 0, s[12:13]
	s_mov_b32 m0, s30
	ds_read_b128 v[184:187], v177 offset:49152
	ds_read_b128 v[188:191], v177 offset:50176
	ds_read_b128 v[192:195], v177 offset:51200
	ds_read_b128 v[196:199], v177 offset:52224
	ds_read_b128 v[200:203], v177 offset:53248
	ds_read_b128 v[204:207], v177 offset:54272
	ds_read_b128 v[210:213], v177 offset:55296
	ds_read_b128 v[214:217], v177 offset:56320
	global_load_lds_dwordx4 v[218:219], off
	s_add_i32 m0, s30, 0x2000
	s_add_u32 s28, s28, 0x40080
	v_lshl_add_u64 v[220:221], v[220:221], 0, s[12:13]
	s_addc_u32 s29, s29, 0
	s_add_i32 s30, s65, s3
	global_load_lds_dwordx4 v[220:221], off
	s_mov_b32 m0, s30
	s_nop 0
	global_load_lds_dwordx4 v130, s[28:29]
	s_add_i32 m0, s30, 0x2000
	s_nop 0
	global_load_lds_dwordx4 v134, s[28:29]
	v_lshl_add_u64 v[222:223], v[222:223], 0, s[12:13]
	s_mov_b32 m0, s43
	s_nop 0
	global_load_lds_dwordx4 v[222:223], off
	v_lshl_add_u64 v[224:225], v[224:225], 0, s[12:13]
	s_mov_b32 m0, s44
	s_nop 0
	global_load_lds_dwordx4 v[224:225], off
	s_waitcnt vmcnt(8)
	s_waitcnt lgkmcnt(0)
	s_barrier
	s_waitcnt lgkmcnt(0)
	v_mfma_f32_16x16x32_bf16 v[60:63], v[144:147], v[184:187], v[60:63]
	v_mfma_f32_16x16x32_bf16 v[56:59], v[152:155], v[184:187], v[56:59]
	v_mfma_f32_16x16x32_bf16 v[44:47], v[144:147], v[192:195], v[44:47]
	v_mfma_f32_16x16x32_bf16 v[40:43], v[152:155], v[192:195], v[40:43]
	v_mfma_f32_16x16x32_bf16 v[28:31], v[144:147], v[200:203], v[28:31]
	v_mfma_f32_16x16x32_bf16 v[24:27], v[152:155], v[200:203], v[24:27]
	v_mfma_f32_16x16x32_bf16 v[12:15], v[144:147], v[210:213], v[12:15]
	v_mfma_f32_16x16x32_bf16 v[8:11], v[152:155], v[210:213], v[8:11]
	v_mfma_f32_16x16x32_bf16 v[60:63], v[148:151], v[188:191], v[60:63]
	s_add_i32 s63, s63, 2
	s_add_u32 s26, s26, 0x100
	s_addc_u32 s27, s27, 0
	s_add_u32 s55, s55, 0x100
	s_addc_u32 s62, s62, 0
	s_cmp_gt_u32 s63, 13
	v_mfma_f32_16x16x32_bf16 v[56:59], v[156:159], v[188:191], v[56:59]
	v_mfma_f32_16x16x32_bf16 v[44:47], v[148:151], v[196:199], v[44:47]
	v_mfma_f32_16x16x32_bf16 v[40:43], v[156:159], v[196:199], v[40:43]
	v_mfma_f32_16x16x32_bf16 v[28:31], v[148:151], v[204:207], v[28:31]
	v_mfma_f32_16x16x32_bf16 v[24:27], v[156:159], v[204:207], v[24:27]
	v_mfma_f32_16x16x32_bf16 v[12:15], v[148:151], v[214:217], v[12:15]
	v_mfma_f32_16x16x32_bf16 v[8:11], v[156:159], v[214:217], v[8:11]
	v_mfma_f32_16x16x32_bf16 v[52:55], v[160:163], v[184:187], v[52:55]
	v_mfma_f32_16x16x32_bf16 v[48:51], v[168:171], v[184:187], v[48:51]
	v_mfma_f32_16x16x32_bf16 v[36:39], v[160:163], v[192:195], v[36:39]
	v_mfma_f32_16x16x32_bf16 v[32:35], v[168:171], v[192:195], v[32:35]
	v_mfma_f32_16x16x32_bf16 v[20:23], v[160:163], v[200:203], v[20:23]
	v_mfma_f32_16x16x32_bf16 v[16:19], v[168:171], v[200:203], v[16:19]
	v_mfma_f32_16x16x32_bf16 v[4:7], v[160:163], v[210:213], v[4:7]
	v_mfma_f32_16x16x32_bf16 v[0:3], v[168:171], v[210:213], v[0:3]
	v_mfma_f32_16x16x32_bf16 v[52:55], v[164:167], v[188:191], v[52:55]
	v_mfma_f32_16x16x32_bf16 v[48:51], v[180:183], v[188:191], v[48:51]
	v_mfma_f32_16x16x32_bf16 v[36:39], v[164:167], v[196:199], v[36:39]
	v_mfma_f32_16x16x32_bf16 v[32:35], v[180:183], v[196:199], v[32:35]
	v_mfma_f32_16x16x32_bf16 v[20:23], v[164:167], v[204:207], v[20:23]
	v_mfma_f32_16x16x32_bf16 v[16:19], v[180:183], v[204:207], v[16:19]
	v_mfma_f32_16x16x32_bf16 v[4:7], v[164:167], v[214:217], v[4:7]
	v_mfma_f32_16x16x32_bf16 v[0:3], v[180:183], v[214:217], v[0:3]
	s_barrier
	s_cbranch_scc0 .LBB0_586
	s_setprio 0
	s_and_b64 vcc, exec, s[16:17]
	s_cbranch_vccz .LBB0_589
	s_barrier

.Lsprio_p7:
.LBB0_685:
	ds_read_b128 v[40:43], v212
	ds_read_b128 v[44:47], v212 offset:1024
	ds_read_b128 v[120:123], v212 offset:2048
	ds_read_b128 v[124:127], v212 offset:3072
	ds_read_b128 v[128:131], v213
	ds_read_b128 v[132:135], v213 offset:1024
	ds_read_b128 v[136:139], v213 offset:2048
	ds_read_b128 v[140:143], v213 offset:3072
	s_add_u32 s16, s0, 0xfffc0080
	s_addc_u32 s17, s1, -1
	s_cmp_eq_u32 s24, 12
	s_cselect_b32 s19, s43, s17
	s_cselect_b32 s18, s42, s16
	s_cselect_b32 s17, s13, s23
	s_cselect_b32 s16, s21, s22
	s_add_i32 m0, s48, 0xc000
	ds_read_b128 v[160:163], v214
	ds_read_b128 v[164:167], v214 offset:1024
	ds_read_b128 v[168:171], v214 offset:2048
	ds_read_b128 v[172:175], v214 offset:3072
	ds_read_b128 v[192:195], v214 offset:4096
	ds_read_b128 v[196:199], v214 offset:5120
	ds_read_b128 v[218:221], v214 offset:6144
	ds_read_b128 v[222:225], v214 offset:7168
	global_load_lds_dwordx4 v184, s[0:1]
	s_add_i32 m0, s48, 0xe000
	s_nop 0
	global_load_lds_dwordx4 v186, s[0:1]
	s_waitcnt vmcnt(8)
	s_waitcnt lgkmcnt(0)
	s_barrier
	s_waitcnt lgkmcnt(0)
	v_mfma_f32_16x16x32_bf16 v[156:159], v[40:43], v[160:163], v[156:159]
	v_mfma_f32_16x16x32_bf16 v[60:63], v[120:123], v[160:163], v[60:63]
	v_mfma_f32_16x16x32_bf16 v[148:151], v[40:43], v[168:171], v[148:151]
	v_mfma_f32_16x16x32_bf16 v[52:55], v[120:123], v[168:171], v[52:55]
	v_mfma_f32_16x16x32_bf16 v[108:111], v[40:43], v[192:195], v[108:111]
	v_mfma_f32_16x16x32_bf16 v[32:35], v[120:123], v[192:195], v[32:35]
	v_mfma_f32_16x16x32_bf16 v[116:119], v[40:43], v[218:221], v[116:119]
	v_mfma_f32_16x16x32_bf16 v[64:67], v[120:123], v[218:221], v[64:67]
	v_mfma_f32_16x16x32_bf16 v[156:159], v[44:47], v[164:167], v[156:159]
	v_mfma_f32_16x16x32_bf16 v[60:63], v[124:127], v[164:167], v[60:63]
	v_mfma_f32_16x16x32_bf16 v[148:151], v[44:47], v[172:175], v[148:151]
	v_mfma_f32_16x16x32_bf16 v[52:55], v[124:127], v[172:175], v[52:55]
	v_mfma_f32_16x16x32_bf16 v[108:111], v[44:47], v[196:199], v[108:111]
	v_mfma_f32_16x16x32_bf16 v[32:35], v[124:127], v[196:199], v[32:35]
	v_mfma_f32_16x16x32_bf16 v[116:119], v[44:47], v[222:225], v[116:119]
	v_mfma_f32_16x16x32_bf16 v[64:67], v[124:127], v[222:225], v[64:67]
	v_mfma_f32_16x16x32_bf16 v[152:155], v[128:131], v[160:163], v[152:155]
	v_mfma_f32_16x16x32_bf16 v[56:59], v[136:139], v[160:163], v[56:59]
	v_mfma_f32_16x16x32_bf16 v[144:147], v[128:131], v[168:171], v[144:147]
	v_mfma_f32_16x16x32_bf16 v[48:51], v[136:139], v[168:171], v[48:51]
	v_mfma_f32_16x16x32_bf16 v[100:103], v[128:131], v[192:195], v[100:103]
	v_mfma_f32_16x16x32_bf16 v[28:31], v[136:139], v[192:195], v[28:31]
	v_mfma_f32_16x16x32_bf16 v[112:115], v[128:131], v[218:221], v[112:115]
	v_mfma_f32_16x16x32_bf16 v[68:71], v[136:139], v[218:221], v[68:71]
	v_mfma_f32_16x16x32_bf16 v[152:155], v[132:135], v[164:167], v[152:155]
	v_mfma_f32_16x16x32_bf16 v[56:59], v[140:143], v[164:167], v[56:59]
	v_mfma_f32_16x16x32_bf16 v[144:147], v[132:135], v[172:175], v[144:147]
	v_mfma_f32_16x16x32_bf16 v[48:51], v[140:143], v[172:175], v[48:51]
	v_mfma_f32_16x16x32_bf16 v[100:103], v[132:135], v[196:199], v[100:103]
	v_mfma_f32_16x16x32_bf16 v[28:31], v[140:143], v[196:199], v[28:31]
	v_mfma_f32_16x16x32_bf16 v[112:115], v[132:135], v[222:225], v[112:115]
	v_mfma_f32_16x16x32_bf16 v[68:71], v[140:143], v[222:225], v[68:71]
	s_barrier
	s_add_i32 s25, s65, s3
	v_lshl_add_u64 v[226:227], s[16:17], 0, v[178:179]
	s_mov_b32 m0, s25
	ds_read_b128 v[160:163], v214 offset:16384
	ds_read_b128 v[164:167], v214 offset:17408
	ds_read_b128 v[168:171], v214 offset:18432
	ds_read_b128 v[172:175], v214 offset:19456
	ds_read_b128 v[192:195], v214 offset:20480
	ds_read_b128 v[196:199], v214 offset:21504
	ds_read_b128 v[218:221], v214 offset:22528
	ds_read_b128 v[222:225], v214 offset:23552
	global_load_lds_dwordx4 v178, s[16:17]
	s_add_i32 m0, s25, 0x2000
	s_add_u32 s26, s16, 0x40000
	v_lshl_add_u64 v[228:229], s[16:17], 0, v[182:183]
	s_addc_u32 s27, s17, 0
	s_add_i32 s25, s66, s3
	global_load_lds_dwordx4 v182, s[16:17]
	s_mov_b32 m0, s25
	v_lshl_add_u64 v[232:233], s[18:19], 0, v[180:181]
	global_load_lds_dwordx4 v178, s[26:27]
	s_add_i32 m0, s25, 0x2000
	s_nop 0
	global_load_lds_dwordx4 v182, s[26:27]
	v_lshl_add_u64 v[230:231], s[18:19], 0, v[176:177]
	s_mov_b32 m0, s48
	s_nop 0
	global_load_lds_dwordx4 v176, s[18:19]
	s_mov_b32 m0, s49
	s_nop 0
	global_load_lds_dwordx4 v180, s[18:19]
	s_waitcnt vmcnt(8)
	s_waitcnt lgkmcnt(0)
	s_barrier
	s_waitcnt lgkmcnt(0)
	v_mfma_f32_16x16x32_bf16 v[92:95], v[40:43], v[160:163], v[92:95]
	v_mfma_f32_16x16x32_bf16 v[20:23], v[120:123], v[160:163], v[20:23]
	v_mfma_f32_16x16x32_bf16 v[84:87], v[40:43], v[168:171], v[84:87]
	v_mfma_f32_16x16x32_bf16 v[12:15], v[120:123], v[168:171], v[12:15]
	v_mfma_f32_16x16x32_bf16 v[76:79], v[40:43], v[192:195], v[76:79]
	v_mfma_f32_16x16x32_bf16 v[4:7], v[120:123], v[192:195], v[4:7]
	v_mfma_f32_16x16x32_bf16 v[24:27], v[120:123], v[218:221], v[24:27]
	v_mfma_f32_16x16x32_bf16 v[92:95], v[44:47], v[164:167], v[92:95]
	v_mfma_f32_16x16x32_bf16 v[20:23], v[124:127], v[164:167], v[20:23]
	v_mfma_f32_16x16x32_bf16 v[84:87], v[44:47], v[172:175], v[84:87]
	v_mfma_f32_16x16x32_bf16 v[12:15], v[124:127], v[172:175], v[12:15]
	v_mfma_f32_16x16x32_bf16 v[76:79], v[44:47], v[196:199], v[76:79]
	v_mfma_f32_16x16x32_bf16 v[4:7], v[124:127], v[196:199], v[4:7]
	v_mfma_f32_16x16x32_bf16 v[40:43], v[40:43], v[218:221], v[96:99]
	v_mfma_f32_16x16x32_bf16 v[24:27], v[124:127], v[222:225], v[24:27]
	v_mfma_f32_16x16x32_bf16 v[40:43], v[44:47], v[222:225], v[40:43]
	v_mfma_f32_16x16x32_bf16 v[44:47], v[128:131], v[160:163], v[88:91]
	v_mfma_f32_16x16x32_bf16 v[16:19], v[136:139], v[160:163], v[16:19]
	v_mfma_f32_16x16x32_bf16 v[80:83], v[128:131], v[168:171], v[80:83]
	v_mfma_f32_16x16x32_bf16 v[8:11], v[136:139], v[168:171], v[8:11]
	v_mfma_f32_16x16x32_bf16 v[72:75], v[128:131], v[192:195], v[72:75]
	v_mfma_f32_16x16x32_bf16 v[0:3], v[136:139], v[192:195], v[0:3]
	v_mfma_f32_16x16x32_bf16 v[88:91], v[128:131], v[218:221], v[104:107]
	v_mfma_f32_16x16x32_bf16 v[36:39], v[136:139], v[218:221], v[36:39]
	v_mfma_f32_16x16x32_bf16 v[16:19], v[140:143], v[164:167], v[16:19]
	v_mfma_f32_16x16x32_bf16 v[80:83], v[132:135], v[172:175], v[80:83]
	v_mfma_f32_16x16x32_bf16 v[8:11], v[140:143], v[172:175], v[8:11]
	v_mfma_f32_16x16x32_bf16 v[72:75], v[132:135], v[196:199], v[72:75]
	v_mfma_f32_16x16x32_bf16 v[0:3], v[140:143], v[196:199], v[0:3]
	v_mfma_f32_16x16x32_bf16 v[104:107], v[132:135], v[222:225], v[88:91]
	v_mfma_f32_16x16x32_bf16 v[36:39], v[140:143], v[222:225], v[36:39]
	v_mfma_f32_16x16x32_bf16 v[44:47], v[132:135], v[164:167], v[44:47]
	s_barrier
	s_add_i32 s25, 0, 0x18000
	s_add_i32 s26, 0, 0x1c000
	v_add_u32_e32 v124, s25, v201
	v_add_u32_e32 v140, s26, v201
	ds_read_b128 v[88:91], v124
	ds_read_b128 v[96:99], v124 offset:1024
	ds_read_b128 v[120:123], v124 offset:2048
	ds_read_b128 v[124:127], v124 offset:3072
	ds_read_b128 v[128:131], v140
	ds_read_b128 v[132:135], v140 offset:1024
	ds_read_b128 v[136:139], v140 offset:2048
	ds_read_b128 v[140:143], v140 offset:3072
	s_add_u32 s18, s18, 0x40000
	s_addc_u32 s19, s19, 0
	s_mov_b32 m0, s50
	ds_read_b128 v[160:163], v214 offset:32768
	ds_read_b128 v[164:167], v214 offset:33792
	ds_read_b128 v[168:171], v214 offset:34816
	ds_read_b128 v[172:175], v214 offset:35840
	ds_read_b128 v[192:195], v214 offset:36864
	ds_read_b128 v[196:199], v214 offset:37888
	ds_read_b128 v[218:221], v214 offset:38912
	ds_read_b128 v[222:225], v214 offset:39936
	global_load_lds_dwordx4 v176, s[18:19]
	s_mov_b32 m0, s51
	s_nop 0
	global_load_lds_dwordx4 v180, s[18:19]
	s_waitcnt vmcnt(8)
	s_waitcnt lgkmcnt(0)
	s_barrier
	s_waitcnt lgkmcnt(0)
	v_mfma_f32_16x16x32_bf16 v[156:159], v[88:91], v[160:163], v[156:159]
	v_mfma_f32_16x16x32_bf16 v[60:63], v[120:123], v[160:163], v[60:63]
	v_mfma_f32_16x16x32_bf16 v[148:151], v[88:91], v[168:171], v[148:151]
	v_mfma_f32_16x16x32_bf16 v[52:55], v[120:123], v[168:171], v[52:55]
	v_mfma_f32_16x16x32_bf16 v[108:111], v[88:91], v[192:195], v[108:111]
	v_mfma_f32_16x16x32_bf16 v[32:35], v[120:123], v[192:195], v[32:35]
	v_mfma_f32_16x16x32_bf16 v[116:119], v[88:91], v[218:221], v[116:119]
	v_mfma_f32_16x16x32_bf16 v[64:67], v[120:123], v[218:221], v[64:67]
	v_mfma_f32_16x16x32_bf16 v[156:159], v[96:99], v[164:167], v[156:159]
	v_mfma_f32_16x16x32_bf16 v[60:63], v[124:127], v[164:167], v[60:63]
	v_mfma_f32_16x16x32_bf16 v[148:151], v[96:99], v[172:175], v[148:151]
	v_mfma_f32_16x16x32_bf16 v[52:55], v[124:127], v[172:175], v[52:55]
	v_mfma_f32_16x16x32_bf16 v[108:111], v[96:99], v[196:199], v[108:111]
	v_mfma_f32_16x16x32_bf16 v[32:35], v[124:127], v[196:199], v[32:35]
	v_mfma_f32_16x16x32_bf16 v[116:119], v[96:99], v[222:225], v[116:119]
	v_mfma_f32_16x16x32_bf16 v[64:67], v[124:127], v[222:225], v[64:67]
	v_mfma_f32_16x16x32_bf16 v[152:155], v[128:131], v[160:163], v[152:155]
	v_mfma_f32_16x16x32_bf16 v[56:59], v[136:139], v[160:163], v[56:59]
	v_mfma_f32_16x16x32_bf16 v[144:147], v[128:131], v[168:171], v[144:147]
	v_mfma_f32_16x16x32_bf16 v[48:51], v[136:139], v[168:171], v[48:51]
	v_mfma_f32_16x16x32_bf16 v[100:103], v[128:131], v[192:195], v[100:103]
	v_mfma_f32_16x16x32_bf16 v[28:31], v[136:139], v[192:195], v[28:31]
	v_mfma_f32_16x16x32_bf16 v[112:115], v[128:131], v[218:221], v[112:115]
	v_mfma_f32_16x16x32_bf16 v[68:71], v[136:139], v[218:221], v[68:71]
	v_mfma_f32_16x16x32_bf16 v[152:155], v[132:135], v[164:167], v[152:155]
	v_mfma_f32_16x16x32_bf16 v[56:59], v[140:143], v[164:167], v[56:59]
	v_mfma_f32_16x16x32_bf16 v[144:147], v[132:135], v[172:175], v[144:147]
	v_mfma_f32_16x16x32_bf16 v[48:51], v[140:143], v[172:175], v[48:51]
	v_mfma_f32_16x16x32_bf16 v[100:103], v[132:135], v[196:199], v[100:103]
	v_mfma_f32_16x16x32_bf16 v[28:31], v[140:143], v[196:199], v[28:31]
	v_mfma_f32_16x16x32_bf16 v[112:115], v[132:135], v[222:225], v[112:115]
	v_mfma_f32_16x16x32_bf16 v[68:71], v[140:143], v[222:225], v[68:71]
	s_barrier
	s_add_i32 s18, s25, s3
	v_lshl_add_u64 v[226:227], v[226:227], 0, s[36:37]
	s_mov_b32 m0, s18
	ds_read_b128 v[160:163], v214 offset:49152
	ds_read_b128 v[164:167], v214 offset:50176
	ds_read_b128 v[168:171], v214 offset:51200
	ds_read_b128 v[172:175], v214 offset:52224
	ds_read_b128 v[192:195], v214 offset:53248
	ds_read_b128 v[196:199], v214 offset:54272
	ds_read_b128 v[218:221], v214 offset:55296
	ds_read_b128 v[222:225], v214 offset:56320
	s_cmp_lg_u32 s24, 12
	s_cbranch_scc1 .Lp7_nopf
	s_mul_hi_i32 s46, s20, 0x3e0f83e1
	s_lshr_b32 s47, s46, 31
	s_ashr_i32 s46, s46, 3
	s_add_i32 s46, s46, s47
	s_mul_i32 s47, s46, 33
	s_sub_i32 s47, s20, s47
	s_mul_i32 s47, s47, 0xfe
	s_min_i32 s47, s47, 0x1f00
	s_lshl_b32 s41, s46, 13
	s_add_i32 s41, s41, s47
	s_mulk_i32 s46, 0x1600
	s_lshl_b32 s46, s46, 2
	s_add_u32 s46, s53, s46
	s_addc_u32 s47, s54, 0
	v_lshl_or_b32 v209, s12, 8, v211
	v_lshlrev_b32_e32 v209, 2, v209
	v_add_u32_e32 v210, s41, v200
	v_lshlrev_b32_e32 v210, 2, v210
	global_load_dwordx4 v[236:239], v209, s[46:47] offset:16
	global_load_dwordx4 v[240:243], v209, s[46:47]
	global_load_dwordx4 v[246:249], v209, s[46:47] offset:528
	global_load_dwordx4 v[250:253], v209, s[46:47] offset:512
	global_load_dword v244, v210, s[96:97] offset:192
	global_load_dword v245, v210, s[96:97] offset:704
	global_load_dword v208, v210, s[96:97]
	global_load_dword v203, v210, s[96:97] offset:64
	global_load_dword v204, v210, s[96:97] offset:128
	global_load_dword v205, v210, s[96:97] offset:512
	global_load_dword v206, v210, s[96:97] offset:576
	global_load_dword v207, v210, s[96:97] offset:640
.Lp7_nopf:
	global_load_lds_dwordx4 v[226:227], off
	s_add_i32 m0, s18, 0x2000
	s_add_u32 s16, s16, 0x40080
	v_lshl_add_u64 v[228:229], v[228:229], 0, s[36:37]
	s_addc_u32 s17, s17, 0
	s_add_i32 s18, s26, s3
	global_load_lds_dwordx4 v[228:229], off
	s_mov_b32 m0, s18
	s_nop 0
	global_load_lds_dwordx4 v178, s[16:17]
	s_add_i32 m0, s18, 0x2000
	s_nop 0
	global_load_lds_dwordx4 v182, s[16:17]
	v_lshl_add_u64 v[230:231], v[230:231], 0, s[36:37]
	s_mov_b32 m0, s55
	s_nop 0
	global_load_lds_dwordx4 v[230:231], off
	v_lshl_add_u64 v[232:233], v[232:233], 0, s[36:37]
	s_mov_b32 m0, s60
	s_nop 0
	global_load_lds_dwordx4 v[232:233], off
	s_cmp_lg_u32 s24, 12
	s_cbranch_scc1 .Lp7_w8
	s_waitcnt vmcnt(20)
	s_branch .Lp7_wdone

.LBB0_692:
	s_waitcnt vmcnt(0)
	v_fmamk_f32 v198, v198, 0x3a800000, v215
	v_rsq_f32_e32 v198, v198
	s_cmp_lt_i32 s16, 32
	s_cselect_b32 s0, 2, 0xc2
	s_cmp_lg_u32 s16, 0
	v_pk_fma_f32 v[158:159], v[158:159], v[198:199], v[142:143] op_sel_hi:[1,0,1]
	v_pk_fma_f32 v[156:157], v[156:157], v[198:199], v[140:141] op_sel_hi:[1,0,1]
	v_pk_fma_f32 v[154:155], v[154:155], v[198:199], v[138:139] op_sel_hi:[1,0,1]
	v_pk_fma_f32 v[152:153], v[152:153], v[198:199], v[136:137] op_sel_hi:[1,0,1]
	s_cselect_b32 s46, s0, 0
	s_nop 1
	v_mov_b32_dpp v222, v156 row_ror:1 row_mask:0xf bank_mask:0xf
	v_mov_b32_dpp v226, v156 row_ror:2 row_mask:0xf bank_mask:0xf
	v_mov_b32_dpp v223, v157 row_ror:1 row_mask:0xf bank_mask:0xf
	v_mov_b32_dpp v227, v157 row_ror:2 row_mask:0xf bank_mask:0xf
	v_mov_b32_dpp v224, v158 row_ror:1 row_mask:0xf bank_mask:0xf
	v_mov_b32_dpp v228, v158 row_ror:2 row_mask:0xf bank_mask:0xf
	v_mov_b32_dpp v225, v159 row_ror:1 row_mask:0xf bank_mask:0xf
	v_mov_b32_dpp v229, v159 row_ror:2 row_mask:0xf bank_mask:0xf
	v_mov_b32_dpp v230, v152 row_ror:1 row_mask:0xf bank_mask:0xf
	v_mov_b32_dpp v233, v152 row_ror:2 row_mask:0xf bank_mask:0xf
	v_mov_b32_dpp v231, v153 row_ror:1 row_mask:0xf bank_mask:0xf
	v_mov_b32_dpp v236, v153 row_ror:2 row_mask:0xf bank_mask:0xf
	v_mov_b32_dpp v234, v154 row_ror:1 row_mask:0xf bank_mask:0xf
	v_mov_b32_dpp v239, v154 row_ror:2 row_mask:0xf bank_mask:0xf
	v_mov_b32_dpp v237, v155 row_ror:1 row_mask:0xf bank_mask:0xf
	v_mov_b32_dpp v240, v155 row_ror:2 row_mask:0xf bank_mask:0xf
	v_cmp_le_u32_e64 s[0:1], s46, v200
	s_and_saveexec_b64 s[16:17], s[0:1]
	s_cbranch_execz .LBB0_694
	v_cndmask_b32_e64 v244, v244, v239, s[8:9]
	v_cndmask_b32_e64 v245, v245, v240, s[8:9]
	v_cndmask_b32_e64 v174, v234, v174, s[6:7]
	v_cndmask_b32_e64 v175, v237, v175, s[6:7]
	s_waitcnt vmcnt(4)
	v_pk_mul_f32 v[244:245], v[126:127], v[244:245]
	v_cndmask_b32_e64 v170, v224, v170, s[6:7]
	s_waitcnt vmcnt(2)
	v_pk_fma_f32 v[174:175], v[130:131], v[174:175], v[244:245]
	v_cndmask_b32_e64 v171, v225, v171, s[6:7]
	s_waitcnt vmcnt(0)
	v_pk_fma_f32 v[154:155], v[154:155], v[134:135], v[174:175]
	v_cndmask_b32_e64 v174, v238, v228, s[8:9]
	v_cndmask_b32_e64 v175, v241, v229, s[8:9]
	v_pk_mul_f32 v[174:175], v[122:123], v[174:175]
	v_cndmask_b32_e64 v242, v242, v233, s[8:9]
	v_pk_fma_f32 v[170:171], v[114:115], v[170:171], v[174:175]
	v_cndmask_b32_e64 v243, v243, v236, s[8:9]
	v_pk_fma_f32 v[158:159], v[158:159], v[118:119], v[170:171]
	v_cndmask_b32_e64 v172, v230, v172, s[6:7]
	v_mul_f32_e32 v170, 0xbfb8aa3b, v159
	v_exp_f32_e32 v170, v170
	v_cndmask_b32_e64 v173, v231, v173, s[6:7]
	v_pk_mul_f32 v[242:243], v[124:125], v[242:243]
	v_mul_f32_e32 v171, 0xbfb8aa3b, v158
	v_add_f32_e32 v170, 1.0, v170
	v_pk_fma_f32 v[172:173], v[128:129], v[172:173], v[242:243]
	v_rcp_f32_e32 v170, v170
	v_pk_fma_f32 v[152:153], v[152:153], v[132:133], v[172:173]
	v_cndmask_b32_e64 v172, v232, v226, s[8:9]
	v_cndmask_b32_e64 v173, v235, v227, s[8:9]
	v_exp_f32_e32 v171, v171
	v_pk_mul_f32 v[172:173], v[120:121], v[172:173]
	v_cndmask_b32_e64 v168, v222, v168, s[6:7]
	v_cndmask_b32_e64 v169, v223, v169, s[6:7]
	v_pk_fma_f32 v[168:169], v[112:113], v[168:169], v[172:173]
	v_mul_f32_e32 v159, v159, v170
	v_pk_fma_f32 v[156:157], v[156:157], v[116:117], v[168:169]
	v_mul_f32_e32 v155, v159, v155
	v_add_f32_e32 v159, 1.0, v171
	v_mul_f32_e32 v168, 0xbfb8aa3b, v157
	v_mul_f32_e32 v169, 0xbfb8aa3b, v156
	v_rcp_f32_e32 v159, v159
	v_exp_f32_e32 v168, v168
	v_exp_f32_e32 v169, v169
	v_mul_f32_e32 v158, v158, v159
	v_add_f32_e32 v159, 1.0, v168
	v_add_f32_e32 v168, 1.0, v169
	v_rcp_f32_e32 v159, v159
	v_rcp_f32_e32 v168, v168
	v_mul_f32_e32 v154, v158, v154
	v_mul_f32_e32 v157, v157, v159
	v_mul_f32_e32 v156, v156, v168
	v_mul_f32_e32 v153, v157, v153
	v_mul_f32_e32 v152, v156, v152
	v_cvt_pk_bf16_f32 v246, v152, v153
	v_cvt_pk_bf16_f32 v247, v154, v155
.LBB0_694:
	s_or_b64 exec, exec, s[16:17]
	v_fmamk_f32 v152, v221, 0x3a800000, v215
	v_rsq_f32_e32 v152, v152
	s_nop 0
	v_pk_fma_f32 v[150:151], v[150:151], v[152:153], v[142:143] op_sel_hi:[1,0,1]
	v_pk_fma_f32 v[148:149], v[148:149], v[152:153], v[140:141] op_sel_hi:[1,0,1]
	v_pk_fma_f32 v[146:147], v[146:147], v[152:153], v[138:139] op_sel_hi:[1,0,1]
	v_pk_fma_f32 v[144:145], v[144:145], v[152:153], v[136:137] op_sel_hi:[1,0,1]
	s_nop 1
	v_mov_b32_dpp v153, v148 row_ror:1 row_mask:0xf bank_mask:0xf
	v_mov_b32_dpp v158, v148 row_ror:2 row_mask:0xf bank_mask:0xf
	v_mov_b32_dpp v155, v149 row_ror:1 row_mask:0xf bank_mask:0xf
	v_mov_b32_dpp v159, v149 row_ror:2 row_mask:0xf bank_mask:0xf
	v_mov_b32_dpp v156, v150 row_ror:1 row_mask:0xf bank_mask:0xf
	v_mov_b32_dpp v168, v150 row_ror:2 row_mask:0xf bank_mask:0xf
	v_mov_b32_dpp v157, v151 row_ror:1 row_mask:0xf bank_mask:0xf
	v_mov_b32_dpp v169, v151 row_ror:2 row_mask:0xf bank_mask:0xf
	v_mov_b32_dpp v172, v144 row_ror:1 row_mask:0xf bank_mask:0xf
	v_mov_b32_dpp v174, v144 row_ror:2 row_mask:0xf bank_mask:0xf
	v_mov_b32_dpp v173, v145 row_ror:1 row_mask:0xf bank_mask:0xf
	v_mov_b32_dpp v221, v145 row_ror:2 row_mask:0xf bank_mask:0xf
	v_mov_b32_dpp v175, v146 row_ror:1 row_mask:0xf bank_mask:0xf
	v_mov_b32_dpp v235, v146 row_ror:2 row_mask:0xf bank_mask:0xf
	v_mov_b32_dpp v232, v147 row_ror:1 row_mask:0xf bank_mask:0xf
	v_mov_b32_dpp v238, v147 row_ror:2 row_mask:0xf bank_mask:0xf
	v_or_b32_e32 v203, 16, v200
	v_cmp_le_u32_e64 s[16:17], s46, v203
	v_add_u32_e32 v154, s41, v203
	s_and_saveexec_b64 s[18:19], s[16:17]
	s_cbranch_execz .LBB0_696
	v_cndmask_b32_e64 v170, v233, v174, s[8:9]
	v_cndmask_b32_e64 v171, v236, v221, s[8:9]
	v_cndmask_b32_e64 v230, v172, v230, s[6:7]
	v_cndmask_b32_e64 v231, v173, v231, s[6:7]
	s_waitcnt vmcnt(4)
	v_pk_mul_f32 v[170:171], v[124:125], v[170:171]
	v_cndmask_b32_e64 v224, v156, v224, s[6:7]
	s_waitcnt vmcnt(2)
	v_pk_fma_f32 v[170:171], v[128:129], v[230:231], v[170:171]
	v_cndmask_b32_e64 v225, v157, v225, s[6:7]
	s_waitcnt vmcnt(0)
	v_pk_fma_f32 v[144:145], v[144:145], v[132:133], v[170:171]
	v_cndmask_b32_e64 v170, v226, v158, s[8:9]
	v_cndmask_b32_e64 v171, v227, v159, s[8:9]
	v_cndmask_b32_e64 v226, v228, v168, s[8:9]
	v_cndmask_b32_e64 v227, v229, v169, s[8:9]
	v_pk_mul_f32 v[226:227], v[122:123], v[226:227]
	v_pk_mul_f32 v[170:171], v[120:121], v[170:171]
	v_pk_fma_f32 v[224:225], v[114:115], v[224:225], v[226:227]
	v_cndmask_b32_e64 v222, v153, v222, s[6:7]
	v_pk_fma_f32 v[150:151], v[150:151], v[118:119], v[224:225]
	v_cndmask_b32_e64 v223, v155, v223, s[6:7]
	v_mul_f32_e32 v208, 0xbfb8aa3b, v151
	v_exp_f32_e32 v208, v208
	v_pk_fma_f32 v[170:171], v[112:113], v[222:223], v[170:171]
	v_mul_f32_e32 v222, 0xbfb8aa3b, v150
	v_cndmask_b32_e64 v242, v239, v235, s[8:9]
	v_add_f32_e32 v208, 1.0, v208
	v_rcp_f32_e32 v208, v208
	v_cndmask_b32_e64 v243, v240, v238, s[8:9]
	v_exp_f32_e32 v222, v222
	v_cndmask_b32_e64 v236, v175, v234, s[6:7]
	v_cndmask_b32_e64 v237, v232, v237, s[6:7]
	v_pk_mul_f32 v[240:241], v[126:127], v[242:243]
	v_pk_fma_f32 v[148:149], v[148:149], v[116:117], v[170:171]
	v_pk_fma_f32 v[236:237], v[130:131], v[236:237], v[240:241]
	v_mul_f32_e32 v151, v151, v208
	v_pk_fma_f32 v[146:147], v[146:147], v[134:135], v[236:237]
	v_mul_f32_e32 v170, 0xbfb8aa3b, v149
	v_mul_f32_e32 v147, v151, v147
	v_add_f32_e32 v151, 1.0, v222
	v_mul_f32_e32 v171, 0xbfb8aa3b, v148
	v_rcp_f32_e32 v151, v151
	v_exp_f32_e32 v170, v170
	v_exp_f32_e32 v171, v171
	v_mul_f32_e32 v150, v150, v151
	v_add_f32_e32 v151, 1.0, v170
	v_add_f32_e32 v170, 1.0, v171
	v_rcp_f32_e32 v151, v151
	v_rcp_f32_e32 v170, v170
	v_mul_f32_e32 v146, v150, v146
	v_mul_f32_e32 v149, v149, v151
	v_mul_f32_e32 v148, v148, v170
	v_mul_f32_e32 v145, v149, v145
	v_mul_f32_e32 v144, v148, v144
	v_cvt_pk_bf16_f32 v248, v144, v145
	v_cvt_pk_bf16_f32 v249, v146, v147
.LBB0_696:
	s_or_b64 exec, exec, s[18:19]
	v_fmamk_f32 v144, v220, 0x3a800000, v215
	v_rsq_f32_e32 v144, v144
	s_nop 0
	v_pk_fma_f32 v[110:111], v[110:111], v[144:145], v[142:143] op_sel_hi:[1,0,1]
	v_pk_fma_f32 v[108:109], v[108:109], v[144:145], v[140:141] op_sel_hi:[1,0,1]
	v_pk_fma_f32 v[102:103], v[102:103], v[144:145], v[138:139] op_sel_hi:[1,0,1]
	v_pk_fma_f32 v[100:101], v[100:101], v[144:145], v[136:137] op_sel_hi:[1,0,1]
	s_nop 1
	v_mov_b32_dpp v145, v108 row_ror:1 row_mask:0xf bank_mask:0xf
	v_mov_b32_dpp v150, v108 row_ror:2 row_mask:0xf bank_mask:0xf
	v_mov_b32_dpp v146, v109 row_ror:1 row_mask:0xf bank_mask:0xf
	v_mov_b32_dpp v151, v109 row_ror:2 row_mask:0xf bank_mask:0xf
	v_mov_b32_dpp v148, v110 row_ror:1 row_mask:0xf bank_mask:0xf
	v_mov_b32_dpp v170, v110 row_ror:2 row_mask:0xf bank_mask:0xf
	v_mov_b32_dpp v149, v111 row_ror:1 row_mask:0xf bank_mask:0xf
	v_mov_b32_dpp v171, v111 row_ror:2 row_mask:0xf bank_mask:0xf
	v_mov_b32_dpp v220, v100 row_ror:1 row_mask:0xf bank_mask:0xf
	v_mov_b32_dpp v223, v100 row_ror:2 row_mask:0xf bank_mask:0xf
	v_mov_b32_dpp v222, v101 row_ror:1 row_mask:0xf bank_mask:0xf
	v_mov_b32_dpp v225, v101 row_ror:2 row_mask:0xf bank_mask:0xf
	v_mov_b32_dpp v224, v102 row_ror:1 row_mask:0xf bank_mask:0xf
	v_mov_b32_dpp v227, v102 row_ror:2 row_mask:0xf bank_mask:0xf
	v_mov_b32_dpp v226, v103 row_ror:1 row_mask:0xf bank_mask:0xf
	v_mov_b32_dpp v228, v103 row_ror:2 row_mask:0xf bank_mask:0xf
	v_or_b32_e32 v204, 32, v200
	v_cmp_le_u32_e64 s[18:19], s46, v204
	v_add_u32_e32 v147, s41, v204
	s_and_saveexec_b64 s[20:21], s[18:19]
	s_cbranch_execz .LBB0_698
	v_cndmask_b32_e64 v168, v168, v170, s[8:9]
	v_cndmask_b32_e64 v169, v169, v171, s[8:9]
	s_waitcnt vmcnt(5)
	v_pk_mul_f32 v[168:169], v[122:123], v[168:169]
	v_cndmask_b32_e64 v156, v148, v156, s[6:7]
	v_cndmask_b32_e64 v157, v149, v157, s[6:7]
	s_waitcnt vmcnt(3)
	v_pk_fma_f32 v[156:157], v[114:115], v[156:157], v[168:169]
	v_cndmask_b32_e64 v234, v235, v227, s[8:9]
	s_waitcnt vmcnt(1)
	v_pk_fma_f32 v[110:111], v[110:111], v[118:119], v[156:157]
	v_cndmask_b32_e64 v157, v146, v155, s[6:7]
	v_mul_f32_e32 v156, 0xbfb8aa3b, v111
	v_exp_f32_e32 v168, v156
	v_cndmask_b32_e64 v156, v145, v153, s[6:7]
	v_mul_f32_e32 v155, 0xbfb8aa3b, v110
	v_cndmask_b32_e64 v235, v238, v228, s[8:9]
	v_add_f32_e32 v153, 1.0, v168
	v_rcp_f32_e32 v153, v153
	v_cndmask_b32_e64 v158, v158, v150, s[8:9]
	v_cndmask_b32_e64 v159, v159, v151, s[8:9]
	v_exp_f32_e32 v155, v155
	v_cndmask_b32_e64 v230, v174, v223, s[8:9]
	v_cndmask_b32_e64 v174, v224, v175, s[6:7]
	v_cndmask_b32_e64 v175, v226, v232, s[6:7]
	v_pk_mul_f32 v[232:233], v[126:127], v[234:235]
	v_pk_mul_f32 v[158:159], v[120:121], v[158:159]
	v_pk_fma_f32 v[174:175], v[130:131], v[174:175], v[232:233]
	v_pk_fma_f32 v[156:157], v[112:113], v[156:157], v[158:159]
	s_waitcnt vmcnt(0)
	v_pk_fma_f32 v[102:103], v[102:103], v[134:135], v[174:175]
	v_pk_fma_f32 v[108:109], v[108:109], v[116:117], v[156:157]
	v_mul_f32_e32 v111, v111, v153
	v_mul_f32_e32 v103, v111, v103
	v_add_f32_e32 v111, 1.0, v155
	v_mul_f32_e32 v153, 0xbfb8aa3b, v109
	v_mul_f32_e32 v155, 0xbfb8aa3b, v108
	v_rcp_f32_e32 v111, v111
	v_exp_f32_e32 v153, v153
	v_exp_f32_e32 v155, v155
	v_cndmask_b32_e64 v231, v221, v225, s[8:9]
	v_mul_f32_e32 v110, v110, v111
	v_add_f32_e32 v111, 1.0, v153
	v_add_f32_e32 v153, 1.0, v155
	v_rcp_f32_e32 v111, v111
	v_rcp_f32_e32 v153, v153
	v_cndmask_b32_e64 v172, v220, v172, s[6:7]
	v_cndmask_b32_e64 v173, v222, v173, s[6:7]
	v_pk_mul_f32 v[230:231], v[124:125], v[230:231]
	v_mul_f32_e32 v109, v109, v111
	v_pk_fma_f32 v[172:173], v[128:129], v[172:173], v[230:231]
	v_mul_f32_e32 v108, v108, v153
	v_pk_fma_f32 v[100:101], v[100:101], v[132:133], v[172:173]
	v_mul_f32_e32 v102, v110, v102
	v_mul_f32_e32 v101, v109, v101
	v_mul_f32_e32 v100, v108, v100
	v_cvt_pk_bf16_f32 v250, v100, v101
	v_cvt_pk_bf16_f32 v251, v102, v103
.LBB0_698:
	s_or_b64 exec, exec, s[20:21]
	s_nop 1
	v_mov_b32_dpp v100, v160 row_ror:1 row_mask:0xf bank_mask:0xf
	v_mov_b32_dpp v108, v160 row_ror:2 row_mask:0xf bank_mask:0xf
	v_mov_b32_dpp v101, v161 row_ror:1 row_mask:0xf bank_mask:0xf
	v_mov_b32_dpp v110, v161 row_ror:2 row_mask:0xf bank_mask:0xf
	v_mov_b32_dpp v102, v162 row_ror:1 row_mask:0xf bank_mask:0xf
	v_mov_b32_dpp v111, v162 row_ror:2 row_mask:0xf bank_mask:0xf
	v_mov_b32_dpp v103, v163 row_ror:1 row_mask:0xf bank_mask:0xf
	v_mov_b32_dpp v153, v163 row_ror:2 row_mask:0xf bank_mask:0xf
	v_mov_b32_dpp v155, v164 row_ror:1 row_mask:0xf bank_mask:0xf
	v_mov_b32_dpp v157, v164 row_ror:2 row_mask:0xf bank_mask:0xf
	v_mov_b32_dpp v156, v165 row_ror:1 row_mask:0xf bank_mask:0xf
	v_mov_b32_dpp v159, v165 row_ror:2 row_mask:0xf bank_mask:0xf
	v_mov_b32_dpp v158, v166 row_ror:1 row_mask:0xf bank_mask:0xf
	v_mov_b32_dpp v169, v166 row_ror:2 row_mask:0xf bank_mask:0xf
	v_mov_b32_dpp v168, v167 row_ror:1 row_mask:0xf bank_mask:0xf
	v_mov_b32_dpp v172, v167 row_ror:2 row_mask:0xf bank_mask:0xf
	v_or_b32_e32 v205, 48, v200
	v_cmp_le_u32_e64 s[20:21], s46, v205
	v_add_u32_e32 v109, s41, v205
	s_and_saveexec_b64 s[22:23], s[20:21]
	s_cbranch_execz .LBB0_700
	v_cndmask_b32_e64 v151, v151, v110, s[8:9]
	v_cndmask_b32_e64 v110, v170, v111, s[8:9]
	v_cndmask_b32_e64 v111, v171, v153, s[8:9]
	s_waitcnt vmcnt(5)
	v_pk_mul_f32 v[110:111], v[122:123], v[110:111]
	v_cndmask_b32_e64 v102, v102, v148, s[6:7]
	v_cndmask_b32_e64 v103, v103, v149, s[6:7]
	s_waitcnt vmcnt(3)
	v_pk_fma_f32 v[102:103], v[114:115], v[102:103], v[110:111]
	v_cndmask_b32_e64 v150, v150, v108, s[8:9]
	s_waitcnt vmcnt(1)
	v_pk_fma_f32 v[102:103], v[162:163], v[118:119], v[102:103]
	v_pk_mul_f32 v[150:151], v[120:121], v[150:151]
	v_mul_f32_e32 v108, 0xbfb8aa3b, v103
	v_exp_f32_e32 v108, v108
	v_mul_f32_e32 v110, 0xbfb8aa3b, v102
	v_exp_f32_e32 v110, v110
	v_cndmask_b32_e64 v100, v100, v145, s[6:7]
	v_add_f32_e32 v108, 1.0, v108
	v_rcp_f32_e32 v108, v108
	v_cndmask_b32_e64 v101, v101, v146, s[6:7]
	v_pk_fma_f32 v[100:101], v[112:113], v[100:101], v[150:151]
	v_cndmask_b32_e64 v174, v223, v157, s[8:9]
	v_pk_fma_f32 v[100:101], v[160:161], v[116:117], v[100:101]
	v_mul_f32_e32 v103, v103, v108
	v_add_f32_e32 v108, 1.0, v110
	v_mul_f32_e32 v110, 0xbfb8aa3b, v101
	v_mul_f32_e32 v111, 0xbfb8aa3b, v100
	v_rcp_f32_e32 v108, v108
	v_exp_f32_e32 v110, v110
	v_exp_f32_e32 v111, v111
	v_cndmask_b32_e64 v175, v225, v159, s[8:9]
	v_mul_f32_e32 v102, v102, v108
	v_add_f32_e32 v108, 1.0, v110
	v_add_f32_e32 v110, 1.0, v111
	v_rcp_f32_e32 v108, v108
	v_rcp_f32_e32 v110, v110
	v_cndmask_b32_e64 v230, v227, v169, s[8:9]
	v_cndmask_b32_e64 v231, v228, v172, s[8:9]
	v_cndmask_b32_e64 v172, v155, v220, s[6:7]
	v_cndmask_b32_e64 v173, v156, v222, s[6:7]
	v_cndmask_b32_e64 v156, v158, v224, s[6:7]
	v_cndmask_b32_e64 v157, v168, v226, s[6:7]
	v_pk_mul_f32 v[158:159], v[124:125], v[174:175]
	v_pk_mul_f32 v[168:169], v[126:127], v[230:231]
	v_pk_fma_f32 v[158:159], v[128:129], v[172:173], v[158:159]
	v_pk_fma_f32 v[156:157], v[130:131], v[156:157], v[168:169]
	s_waitcnt vmcnt(0)
	v_pk_fma_f32 v[158:159], v[164:165], v[132:133], v[158:159]
	v_pk_fma_f32 v[156:157], v[166:167], v[134:135], v[156:157]
	v_mul_f32_e32 v101, v101, v108
	v_mul_f32_e32 v100, v100, v110
	v_mul_f32_e32 v103, v103, v157
	v_mul_f32_e32 v102, v102, v156
	v_mul_f32_e32 v101, v101, v159
	v_mul_f32_e32 v100, v100, v158
	v_cvt_pk_bf16_f32 v252, v100, v101
	v_cvt_pk_bf16_f32 v253, v102, v103
.LBB0_700:
	s_or_b64 exec, exec, s[22:23]
	v_fmamk_f32 v100, v219, 0x3a800000, v215
	v_rsq_f32_e32 v108, v100
	s_nop 0
	v_pk_fma_f32 v[94:95], v[94:95], v[108:109], v[142:143] op_sel_hi:[1,0,1]
	v_pk_fma_f32 v[92:93], v[92:93], v[108:109], v[140:141] op_sel_hi:[1,0,1]
	v_pk_fma_f32 v[90:91], v[90:91], v[108:109], v[138:139] op_sel_hi:[1,0,1]
	v_pk_fma_f32 v[88:89], v[88:89], v[108:109], v[136:137] op_sel_hi:[1,0,1]
	s_nop 1
	v_mov_b32_dpp v100, v92 row_ror:1 row_mask:0xf bank_mask:0xf
	v_mov_b32_dpp v110, v92 row_ror:2 row_mask:0xf bank_mask:0xf
	v_mov_b32_dpp v101, v93 row_ror:1 row_mask:0xf bank_mask:0xf
	v_mov_b32_dpp v145, v93 row_ror:2 row_mask:0xf bank_mask:0xf
	v_mov_b32_dpp v102, v94 row_ror:1 row_mask:0xf bank_mask:0xf
	v_mov_b32_dpp v150, v94 row_ror:2 row_mask:0xf bank_mask:0xf
	v_mov_b32_dpp v103, v95 row_ror:1 row_mask:0xf bank_mask:0xf
	v_mov_b32_dpp v151, v95 row_ror:2 row_mask:0xf bank_mask:0xf
	v_mov_b32_dpp v153, v88 row_ror:1 row_mask:0xf bank_mask:0xf
	v_mov_b32_dpp v156, v88 row_ror:2 row_mask:0xf bank_mask:0xf
	v_mov_b32_dpp v155, v89 row_ror:1 row_mask:0xf bank_mask:0xf
	v_mov_b32_dpp v158, v89 row_ror:2 row_mask:0xf bank_mask:0xf
	v_mov_b32_dpp v157, v90 row_ror:1 row_mask:0xf bank_mask:0xf
	v_mov_b32_dpp v160, v90 row_ror:2 row_mask:0xf bank_mask:0xf
	v_mov_b32_dpp v159, v91 row_ror:1 row_mask:0xf bank_mask:0xf
	v_mov_b32_dpp v161, v91 row_ror:2 row_mask:0xf bank_mask:0xf
	v_add_u32_e32 v206, 0x80, v200
	v_cmp_le_u32_e64 s[22:23], s46, v206
	v_add_u32_e32 v149, s64, v202
	v_add_u32_e32 v111, s41, v206
	s_and_saveexec_b64 s[24:25], s[22:23]
	s_cbranch_execz .LBB0_702
	ds_read_b128 v[162:165], v149 offset:288
	ds_read_b128 v[166:169], v149 offset:32
	ds_read_b128 v[170:173], v149
	ds_read_b128 v[220:223], v149 offset:256
	s_waitcnt lgkmcnt(2)
	v_cndmask_b32_e64 v146, v165, v169, s[6:7]
	v_cndmask_b32_e64 v148, v164, v168, s[6:7]
	v_cndmask_b32_e64 v168, v148, v160, s[8:9]
	v_cndmask_b32_e64 v169, v146, v161, s[8:9]
	v_cndmask_b32_e64 v167, v163, v167, s[6:7]
	v_cndmask_b32_e64 v166, v162, v166, s[6:7]
	v_cndmask_b32_e64 v164, v157, v164, s[6:7]
	v_cndmask_b32_e64 v165, v159, v165, s[6:7]
	s_waitcnt vmcnt(4)
	v_pk_mul_f32 v[168:169], v[126:127], v[168:169]
	v_cndmask_b32_e64 v166, v166, v156, s[8:9]
	v_cndmask_b32_e64 v167, v167, v158, s[8:9]
	s_waitcnt vmcnt(2)
	v_pk_fma_f32 v[164:165], v[130:131], v[164:165], v[168:169]
	s_waitcnt lgkmcnt(0)
	v_cndmask_b32_e64 v146, v223, v173, s[6:7]
	v_cndmask_b32_e64 v148, v222, v172, s[6:7]
	v_cndmask_b32_e64 v162, v153, v162, s[6:7]
	v_cndmask_b32_e64 v163, v155, v163, s[6:7]
	v_pk_mul_f32 v[166:167], v[124:125], v[166:167]
	s_waitcnt vmcnt(0)
	v_pk_fma_f32 v[90:91], v[90:91], v[134:135], v[164:165]
	v_cndmask_b32_e64 v164, v148, v150, s[8:9]
	v_cndmask_b32_e64 v165, v146, v151, s[8:9]
	v_pk_fma_f32 v[162:163], v[128:129], v[162:163], v[166:167]
	v_pk_mul_f32 v[164:165], v[122:123], v[164:165]
	v_cndmask_b32_e64 v166, v102, v222, s[6:7]
	v_cndmask_b32_e64 v167, v103, v223, s[6:7]
	v_pk_fma_f32 v[164:165], v[114:115], v[166:167], v[164:165]
	v_pk_fma_f32 v[88:89], v[88:89], v[132:133], v[162:163]
	v_pk_fma_f32 v[94:95], v[94:95], v[118:119], v[164:165]
	v_cndmask_b32_e64 v163, v221, v171, s[6:7]
	v_mul_f32_e32 v146, 0xbfb8aa3b, v95
	v_exp_f32_e32 v146, v146
	v_cndmask_b32_e64 v162, v220, v170, s[6:7]
	v_mul_f32_e32 v148, 0xbfb8aa3b, v94
	v_cndmask_b32_e64 v162, v162, v110, s[8:9]
	v_add_f32_e32 v146, 1.0, v146
	v_rcp_f32_e32 v146, v146
	v_cndmask_b32_e64 v163, v163, v145, s[8:9]
	v_exp_f32_e32 v148, v148
	v_pk_mul_f32 v[162:163], v[120:121], v[162:163]
	v_cndmask_b32_e64 v164, v100, v220, s[6:7]
	v_cndmask_b32_e64 v165, v101, v221, s[6:7]
	v_pk_fma_f32 v[162:163], v[112:113], v[164:165], v[162:163]
	v_mul_f32_e32 v95, v95, v146
	v_pk_fma_f32 v[92:93], v[92:93], v[116:117], v[162:163]
	v_mul_f32_e32 v91, v91, v95
	v_add_f32_e32 v95, 1.0, v148
	v_mul_f32_e32 v146, 0xbfb8aa3b, v93
	v_mul_f32_e32 v148, 0xbfb8aa3b, v92
	v_rcp_f32_e32 v95, v95
	v_exp_f32_e32 v146, v146
	v_exp_f32_e32 v148, v148
	v_mul_f32_e32 v94, v94, v95
	v_add_f32_e32 v95, 1.0, v146
	v_add_f32_e32 v146, 1.0, v148
	v_rcp_f32_e32 v95, v95
	v_rcp_f32_e32 v146, v146
	v_mul_f32_e32 v90, v90, v94
	v_mul_f32_e32 v93, v93, v95
	v_mul_f32_e32 v92, v92, v146
	v_mul_f32_e32 v89, v89, v93
	v_mul_f32_e32 v88, v88, v92
	v_cvt_pk_bf16_f32 v174, v88, v89
	v_cvt_pk_bf16_f32 v175, v90, v91
.LBB0_702:
	s_or_b64 exec, exec, s[24:25]
	v_fmamk_f32 v88, v218, 0x3a800000, v215
	v_rsq_f32_e32 v146, v88
	s_nop 0
	v_pk_fma_f32 v[86:87], v[86:87], v[146:147], v[142:143] op_sel_hi:[1,0,1]
	v_pk_fma_f32 v[84:85], v[84:85], v[146:147], v[140:141] op_sel_hi:[1,0,1]
	v_pk_fma_f32 v[82:83], v[82:83], v[146:147], v[138:139] op_sel_hi:[1,0,1]
	v_pk_fma_f32 v[80:81], v[80:81], v[146:147], v[136:137] op_sel_hi:[1,0,1]
	s_nop 1
	v_mov_b32_dpp v88, v84 row_ror:1 row_mask:0xf bank_mask:0xf
	v_mov_b32_dpp v92, v84 row_ror:2 row_mask:0xf bank_mask:0xf
	v_mov_b32_dpp v89, v85 row_ror:1 row_mask:0xf bank_mask:0xf
	v_mov_b32_dpp v93, v85 row_ror:2 row_mask:0xf bank_mask:0xf
	v_mov_b32_dpp v90, v86 row_ror:1 row_mask:0xf bank_mask:0xf
	v_mov_b32_dpp v94, v86 row_ror:2 row_mask:0xf bank_mask:0xf
	v_mov_b32_dpp v91, v87 row_ror:1 row_mask:0xf bank_mask:0xf
	v_mov_b32_dpp v95, v87 row_ror:2 row_mask:0xf bank_mask:0xf
	v_mov_b32_dpp v162, v80 row_ror:1 row_mask:0xf bank_mask:0xf
	v_mov_b32_dpp v164, v80 row_ror:2 row_mask:0xf bank_mask:0xf
	v_mov_b32_dpp v163, v81 row_ror:1 row_mask:0xf bank_mask:0xf
	v_mov_b32_dpp v166, v81 row_ror:2 row_mask:0xf bank_mask:0xf
	v_mov_b32_dpp v165, v82 row_ror:1 row_mask:0xf bank_mask:0xf
	v_mov_b32_dpp v168, v82 row_ror:2 row_mask:0xf bank_mask:0xf
	v_mov_b32_dpp v167, v83 row_ror:1 row_mask:0xf bank_mask:0xf
	v_mov_b32_dpp v169, v83 row_ror:2 row_mask:0xf bank_mask:0xf
	v_add_u32_e32 v207, 0x90, v200
	v_cmp_le_u32_e64 s[24:25], s46, v207
	v_add_u32_e32 v148, s41, v207
	s_and_saveexec_b64 s[26:27], s[24:25]
	s_cbranch_execz .LBB0_704
	v_cndmask_b32_e64 v150, v150, v94, s[8:9]
	v_cndmask_b32_e64 v151, v151, v95, s[8:9]
	s_waitcnt vmcnt(5)
	v_pk_mul_f32 v[150:151], v[122:123], v[150:151]
	v_cndmask_b32_e64 v102, v90, v102, s[6:7]
	v_cndmask_b32_e64 v103, v91, v103, s[6:7]
	s_waitcnt vmcnt(3)
	v_pk_fma_f32 v[102:103], v[114:115], v[102:103], v[150:151]
	v_cndmask_b32_e64 v160, v160, v168, s[8:9]
	s_waitcnt vmcnt(1)
	v_pk_fma_f32 v[86:87], v[86:87], v[118:119], v[102:103]
	v_cndmask_b32_e64 v161, v161, v169, s[8:9]
	v_mul_f32_e32 v102, 0xbfb8aa3b, v87
	v_exp_f32_e32 v102, v102
	v_cndmask_b32_e64 v170, v156, v164, s[8:9]
	v_cndmask_b32_e64 v156, v165, v157, s[6:7]
	v_cndmask_b32_e64 v157, v167, v159, s[6:7]
	v_pk_mul_f32 v[160:161], v[126:127], v[160:161]
	v_add_f32_e32 v102, 1.0, v102
	v_pk_fma_f32 v[156:157], v[130:131], v[156:157], v[160:161]
	v_rcp_f32_e32 v102, v102
	v_mul_f32_e32 v103, 0xbfb8aa3b, v86
	s_waitcnt vmcnt(0)
	v_pk_fma_f32 v[82:83], v[82:83], v[134:135], v[156:157]
	v_cndmask_b32_e64 v156, v110, v92, s[8:9]
	v_cndmask_b32_e64 v157, v145, v93, s[8:9]
	v_exp_f32_e32 v103, v103
	v_pk_mul_f32 v[156:157], v[120:121], v[156:157]
	v_cndmask_b32_e64 v100, v88, v100, s[6:7]
	v_cndmask_b32_e64 v101, v89, v101, s[6:7]
	v_pk_fma_f32 v[100:101], v[112:113], v[100:101], v[156:157]
	v_mul_f32_e32 v87, v87, v102
	v_pk_fma_f32 v[84:85], v[84:85], v[116:117], v[100:101]
	v_mul_f32_e32 v83, v87, v83
	v_add_f32_e32 v87, 1.0, v103
	v_mul_f32_e32 v100, 0xbfb8aa3b, v85
	v_mul_f32_e32 v101, 0xbfb8aa3b, v84
	v_rcp_f32_e32 v87, v87
	v_exp_f32_e32 v100, v100
	v_exp_f32_e32 v101, v101
	v_cndmask_b32_e64 v171, v158, v166, s[8:9]
	v_mul_f32_e32 v86, v86, v87
	v_add_f32_e32 v87, 1.0, v100
	v_add_f32_e32 v100, 1.0, v101
	v_rcp_f32_e32 v87, v87
	v_rcp_f32_e32 v100, v100
	v_cndmask_b32_e64 v172, v162, v153, s[6:7]
	v_cndmask_b32_e64 v173, v163, v155, s[6:7]
	v_pk_mul_f32 v[158:159], v[124:125], v[170:171]
	v_mul_f32_e32 v85, v85, v87
	v_pk_fma_f32 v[158:159], v[128:129], v[172:173], v[158:159]
	v_mul_f32_e32 v84, v84, v100
	v_pk_fma_f32 v[80:81], v[80:81], v[132:133], v[158:159]
	v_mul_f32_e32 v82, v86, v82
	v_mul_f32_e32 v81, v85, v81
	v_mul_f32_e32 v80, v84, v80
	v_cvt_pk_bf16_f32 v170, v80, v81
	v_cvt_pk_bf16_f32 v171, v82, v83
.LBB0_704:
	s_or_b64 exec, exec, s[26:27]
	v_fmamk_f32 v80, v199, 0x3a800000, v215
	v_rsq_f32_e32 v110, v80
	s_nop 0
	v_pk_fma_f32 v[78:79], v[78:79], v[110:111], v[142:143] op_sel_hi:[1,0,1]
	v_pk_fma_f32 v[76:77], v[76:77], v[110:111], v[140:141] op_sel_hi:[1,0,1]
	v_pk_fma_f32 v[74:75], v[74:75], v[110:111], v[138:139] op_sel_hi:[1,0,1]
	v_pk_fma_f32 v[72:73], v[72:73], v[110:111], v[136:137] op_sel_hi:[1,0,1]
	s_nop 1
	v_mov_b32_dpp v80, v76 row_ror:1 row_mask:0xf bank_mask:0xf
	v_mov_b32_dpp v84, v76 row_ror:2 row_mask:0xf bank_mask:0xf
	v_mov_b32_dpp v81, v77 row_ror:1 row_mask:0xf bank_mask:0xf
	v_mov_b32_dpp v85, v77 row_ror:2 row_mask:0xf bank_mask:0xf
	v_mov_b32_dpp v82, v78 row_ror:1 row_mask:0xf bank_mask:0xf
	v_mov_b32_dpp v86, v78 row_ror:2 row_mask:0xf bank_mask:0xf
	v_mov_b32_dpp v83, v79 row_ror:1 row_mask:0xf bank_mask:0xf
	v_mov_b32_dpp v87, v79 row_ror:2 row_mask:0xf bank_mask:0xf
	v_mov_b32_dpp v100, v72 row_ror:1 row_mask:0xf bank_mask:0xf
	v_mov_b32_dpp v102, v72 row_ror:2 row_mask:0xf bank_mask:0xf
	v_mov_b32_dpp v101, v73 row_ror:1 row_mask:0xf bank_mask:0xf
	v_mov_b32_dpp v138, v73 row_ror:2 row_mask:0xf bank_mask:0xf
	v_mov_b32_dpp v103, v74 row_ror:1 row_mask:0xf bank_mask:0xf
	v_mov_b32_dpp v140, v74 row_ror:2 row_mask:0xf bank_mask:0xf
	v_mov_b32_dpp v139, v75 row_ror:1 row_mask:0xf bank_mask:0xf
	v_mov_b32_dpp v141, v75 row_ror:2 row_mask:0xf bank_mask:0xf
	v_add_u32_e32 v209, 0xa0, v200
	v_cmp_le_u32_e64 s[26:27], s46, v209
	v_add_u32_e32 v136, s41, v209
	s_and_saveexec_b64 s[28:29], s[26:27]
	s_cbranch_execz .LBB0_706
	v_cndmask_b32_e64 v94, v94, v86, s[8:9]
	v_cndmask_b32_e64 v95, v95, v87, s[8:9]
	s_waitcnt vmcnt(5)
	v_pk_mul_f32 v[94:95], v[122:123], v[94:95]
	v_cndmask_b32_e64 v90, v82, v90, s[6:7]
	v_cndmask_b32_e64 v91, v83, v91, s[6:7]
	s_waitcnt vmcnt(3)
	v_pk_fma_f32 v[90:91], v[114:115], v[90:91], v[94:95]
	v_cndmask_b32_e64 v150, v168, v140, s[8:9]
	s_waitcnt vmcnt(1)
	v_pk_fma_f32 v[78:79], v[78:79], v[118:119], v[90:91]
	v_cndmask_b32_e64 v151, v169, v141, s[8:9]
	v_mul_f32_e32 v90, 0xbfb8aa3b, v79
	v_exp_f32_e32 v90, v90
	v_mul_f32_e32 v91, 0xbfb8aa3b, v78
	v_cndmask_b32_e64 v92, v92, v84, s[8:9]
	v_cndmask_b32_e64 v93, v93, v85, s[8:9]
	v_add_f32_e32 v90, 1.0, v90
	v_rcp_f32_e32 v90, v90
	v_exp_f32_e32 v91, v91
	v_cndmask_b32_e64 v158, v103, v165, s[6:7]
	v_cndmask_b32_e64 v159, v139, v167, s[6:7]
	v_pk_mul_f32 v[150:151], v[126:127], v[150:151]
	v_pk_mul_f32 v[92:93], v[120:121], v[92:93]
	v_cndmask_b32_e64 v88, v80, v88, s[6:7]
	v_cndmask_b32_e64 v89, v81, v89, s[6:7]
	v_pk_fma_f32 v[150:151], v[130:131], v[158:159], v[150:151]
	v_pk_fma_f32 v[88:89], v[112:113], v[88:89], v[92:93]
	s_waitcnt vmcnt(0)
	v_pk_fma_f32 v[74:75], v[74:75], v[134:135], v[150:151]
	v_pk_fma_f32 v[76:77], v[76:77], v[116:117], v[88:89]
	v_mul_f32_e32 v79, v79, v90
	v_mul_f32_e32 v75, v79, v75
	v_add_f32_e32 v79, 1.0, v91
	v_mul_f32_e32 v88, 0xbfb8aa3b, v77
	v_mul_f32_e32 v89, 0xbfb8aa3b, v76
	v_rcp_f32_e32 v79, v79
	v_exp_f32_e32 v88, v88
	v_exp_f32_e32 v89, v89
	v_cndmask_b32_e64 v142, v164, v102, s[8:9]
	v_mul_f32_e32 v78, v78, v79
	v_add_f32_e32 v79, 1.0, v88
	v_add_f32_e32 v88, 1.0, v89
	v_rcp_f32_e32 v79, v79
	v_rcp_f32_e32 v88, v88
	v_cndmask_b32_e64 v143, v166, v138, s[8:9]
	v_cndmask_b32_e64 v156, v100, v162, s[6:7]
	v_cndmask_b32_e64 v157, v101, v163, s[6:7]
	v_pk_mul_f32 v[142:143], v[124:125], v[142:143]
	v_mul_f32_e32 v77, v77, v79
	v_pk_fma_f32 v[142:143], v[128:129], v[156:157], v[142:143]
	v_mul_f32_e32 v76, v76, v88
	v_pk_fma_f32 v[72:73], v[72:73], v[132:133], v[142:143]
	v_mul_f32_e32 v74, v78, v74
	v_mul_f32_e32 v73, v77, v73
	v_mul_f32_e32 v72, v76, v72
	v_cvt_pk_bf16_f32 v172, v72, v73
	v_cvt_pk_bf16_f32 v173, v74, v75
.LBB0_706:
	s_or_b64 exec, exec, s[28:29]
	s_nop 1
	v_mov_b32_dpp v72, v96 row_ror:1 row_mask:0xf bank_mask:0xf
	v_mov_b32_dpp v76, v96 row_ror:2 row_mask:0xf bank_mask:0xf
	v_mov_b32_dpp v73, v97 row_ror:1 row_mask:0xf bank_mask:0xf
	v_mov_b32_dpp v77, v97 row_ror:2 row_mask:0xf bank_mask:0xf
	v_mov_b32_dpp v74, v98 row_ror:1 row_mask:0xf bank_mask:0xf
	v_mov_b32_dpp v78, v98 row_ror:2 row_mask:0xf bank_mask:0xf
	v_mov_b32_dpp v75, v99 row_ror:1 row_mask:0xf bank_mask:0xf
	v_mov_b32_dpp v79, v99 row_ror:2 row_mask:0xf bank_mask:0xf
	v_mov_b32_dpp v88, v104 row_ror:1 row_mask:0xf bank_mask:0xf
	v_mov_b32_dpp v90, v104 row_ror:2 row_mask:0xf bank_mask:0xf
	v_mov_b32_dpp v89, v105 row_ror:1 row_mask:0xf bank_mask:0xf
	v_mov_b32_dpp v92, v105 row_ror:2 row_mask:0xf bank_mask:0xf
	v_mov_b32_dpp v91, v106 row_ror:1 row_mask:0xf bank_mask:0xf
	v_mov_b32_dpp v94, v106 row_ror:2 row_mask:0xf bank_mask:0xf
	v_mov_b32_dpp v93, v107 row_ror:1 row_mask:0xf bank_mask:0xf
	v_mov_b32_dpp v95, v107 row_ror:2 row_mask:0xf bank_mask:0xf
	v_add_u32_e32 v210, 0xb0, v200
	v_cmp_le_u32_e64 s[28:29], s46, v210
	v_add_u32_e32 v137, s41, v210
	s_and_saveexec_b64 s[46:47], s[28:29]
	s_cbranch_execz .LBB0_708
	v_cndmask_b32_e64 v78, v86, v78, s[8:9]
	v_cndmask_b32_e64 v79, v87, v79, s[8:9]
	s_waitcnt vmcnt(5)
	v_pk_mul_f32 v[78:79], v[122:123], v[78:79]
	v_cndmask_b32_e64 v74, v74, v82, s[6:7]
	v_cndmask_b32_e64 v75, v75, v83, s[6:7]
	s_waitcnt vmcnt(3)
	v_pk_fma_f32 v[74:75], v[114:115], v[74:75], v[78:79]
	v_cndmask_b32_e64 v76, v84, v76, s[8:9]
	s_waitcnt vmcnt(1)
	v_pk_fma_f32 v[74:75], v[98:99], v[118:119], v[74:75]
	v_cndmask_b32_e64 v77, v85, v77, s[8:9]
	v_mul_f32_e32 v78, 0xbfb8aa3b, v75
	v_exp_f32_e32 v78, v78
	v_pk_mul_f32 v[76:77], v[120:121], v[76:77]
	v_cndmask_b32_e64 v72, v72, v80, s[6:7]
	v_cndmask_b32_e64 v73, v73, v81, s[6:7]
	v_pk_fma_f32 v[72:73], v[112:113], v[72:73], v[76:77]
	v_add_f32_e32 v76, 1.0, v78
	v_mul_f32_e32 v77, 0xbfb8aa3b, v74
	v_rcp_f32_e32 v76, v76
	v_exp_f32_e32 v77, v77
	v_pk_fma_f32 v[72:73], v[96:97], v[116:117], v[72:73]
	v_cndmask_b32_e64 v142, v102, v90, s[8:9]
	v_mul_f32_e32 v75, v75, v76
	v_add_f32_e32 v76, 1.0, v77
	v_mul_f32_e32 v77, 0xbfb8aa3b, v73
	v_mul_f32_e32 v78, 0xbfb8aa3b, v72
	v_rcp_f32_e32 v76, v76
	v_exp_f32_e32 v77, v77
	v_exp_f32_e32 v78, v78
	v_cndmask_b32_e64 v143, v138, v92, s[8:9]
	v_mul_f32_e32 v74, v74, v76
	v_add_f32_e32 v76, 1.0, v77
	v_add_f32_e32 v77, 1.0, v78
	v_rcp_f32_e32 v76, v76
	v_rcp_f32_e32 v77, v77
	v_cndmask_b32_e64 v94, v140, v94, s[8:9]
	v_cndmask_b32_e64 v95, v141, v95, s[8:9]
	v_cndmask_b32_e64 v88, v88, v100, s[6:7]
	v_cndmask_b32_e64 v89, v89, v101, s[6:7]
	v_cndmask_b32_e64 v90, v91, v103, s[6:7]
	v_cndmask_b32_e64 v91, v93, v139, s[6:7]
	v_pk_mul_f32 v[92:93], v[124:125], v[142:143]
	v_pk_mul_f32 v[94:95], v[126:127], v[94:95]
	v_pk_fma_f32 v[88:89], v[128:129], v[88:89], v[92:93]
	v_pk_fma_f32 v[90:91], v[130:131], v[90:91], v[94:95]
	s_waitcnt vmcnt(0)
	v_pk_fma_f32 v[88:89], v[104:105], v[132:133], v[88:89]
	v_pk_fma_f32 v[90:91], v[106:107], v[134:135], v[90:91]
	v_mul_f32_e32 v73, v73, v76
	v_mul_f32_e32 v72, v72, v77
	v_mul_f32_e32 v75, v75, v91
	v_mul_f32_e32 v74, v74, v90
	v_mul_f32_e32 v73, v73, v89
	v_mul_f32_e32 v72, v72, v88
	v_cvt_pk_bf16_f32 v155, v72, v73
	v_cvt_pk_bf16_f32 v160, v74, v75

.LBB0_710:
	v_mov_b32_e32 v199, v198
	v_mov_b32_e32 v104, v198
	v_mov_b32_e32 v105, v198
	v_pk_fma_f32 v[62:63], v[62:63], v[104:105], v[46:47]
	v_pk_fma_f32 v[60:61], v[60:61], v[198:199], v[44:45]
	v_pk_fma_f32 v[58:59], v[58:59], v[104:105], v[42:43]
	v_pk_fma_f32 v[56:57], v[56:57], v[198:199], v[40:41]
	s_waitcnt vmcnt(7)
	s_nop 1
	v_mov_b32_dpp v104, v60 row_ror:1 row_mask:0xf bank_mask:0xf
	v_mov_b32_dpp v112, v60 row_ror:2 row_mask:0xf bank_mask:0xf
	v_mov_b32_dpp v105, v61 row_ror:1 row_mask:0xf bank_mask:0xf
	v_mov_b32_dpp v113, v61 row_ror:2 row_mask:0xf bank_mask:0xf
	v_mov_b32_dpp v106, v62 row_ror:1 row_mask:0xf bank_mask:0xf
	v_mov_b32_dpp v114, v62 row_ror:2 row_mask:0xf bank_mask:0xf
	v_mov_b32_dpp v107, v63 row_ror:1 row_mask:0xf bank_mask:0xf
	v_mov_b32_dpp v115, v63 row_ror:2 row_mask:0xf bank_mask:0xf
	v_mov_b32_dpp v116, v56 row_ror:1 row_mask:0xf bank_mask:0xf
	v_mov_b32_dpp v118, v56 row_ror:2 row_mask:0xf bank_mask:0xf
	v_mov_b32_dpp v117, v57 row_ror:1 row_mask:0xf bank_mask:0xf
	v_mov_b32_dpp v120, v57 row_ror:2 row_mask:0xf bank_mask:0xf
	v_mov_b32_dpp v119, v58 row_ror:1 row_mask:0xf bank_mask:0xf
	v_mov_b32_dpp v122, v58 row_ror:2 row_mask:0xf bank_mask:0xf
	v_mov_b32_dpp v121, v59 row_ror:1 row_mask:0xf bank_mask:0xf
	v_mov_b32_dpp v123, v59 row_ror:2 row_mask:0xf bank_mask:0xf
	s_and_saveexec_b64 s[46:47], s[0:1]
	s_cbranch_execz .LBB0_712
	v_cndmask_b32_e64 v130, v130, v122, s[8:9]
	v_cndmask_b32_e64 v131, v131, v123, s[8:9]
	v_cndmask_b32_e64 v102, v119, v102, s[6:7]
	v_cndmask_b32_e64 v103, v121, v103, s[6:7]
	s_waitcnt vmcnt(4)
	v_pk_mul_f32 v[130:131], v[86:87], v[130:131]
	v_cndmask_b32_e64 v98, v106, v98, s[6:7]
	s_waitcnt vmcnt(2)
	v_pk_fma_f32 v[102:103], v[90:91], v[102:103], v[130:131]
	v_cndmask_b32_e64 v99, v107, v99, s[6:7]
	s_waitcnt vmcnt(0)
	v_pk_fma_f32 v[58:59], v[58:59], v[94:95], v[102:103]
	v_cndmask_b32_e64 v102, v126, v114, s[8:9]
	v_cndmask_b32_e64 v103, v127, v115, s[8:9]
	v_pk_mul_f32 v[102:103], v[78:79], v[102:103]
	v_cndmask_b32_e64 v128, v128, v118, s[8:9]
	v_pk_fma_f32 v[98:99], v[74:75], v[98:99], v[102:103]
	v_cndmask_b32_e64 v129, v129, v120, s[8:9]
	v_pk_fma_f32 v[62:63], v[62:63], v[82:83], v[98:99]
	v_cndmask_b32_e64 v100, v116, v100, s[6:7]
	v_mul_f32_e32 v98, 0xbfb8aa3b, v63
	v_exp_f32_e32 v98, v98
	v_cndmask_b32_e64 v101, v117, v101, s[6:7]
	v_pk_mul_f32 v[128:129], v[84:85], v[128:129]
	v_mul_f32_e32 v99, 0xbfb8aa3b, v62
	v_add_f32_e32 v98, 1.0, v98
	v_pk_fma_f32 v[100:101], v[88:89], v[100:101], v[128:129]
	v_rcp_f32_e32 v98, v98
	v_pk_fma_f32 v[56:57], v[56:57], v[92:93], v[100:101]
	v_cndmask_b32_e64 v100, v124, v112, s[8:9]
	v_cndmask_b32_e64 v101, v125, v113, s[8:9]
	v_exp_f32_e32 v99, v99
	v_pk_mul_f32 v[100:101], v[76:77], v[100:101]
	v_cndmask_b32_e64 v96, v104, v96, s[6:7]
	v_cndmask_b32_e64 v97, v105, v97, s[6:7]
	v_pk_fma_f32 v[96:97], v[72:73], v[96:97], v[100:101]
	v_mul_f32_e32 v63, v63, v98
	v_pk_fma_f32 v[60:61], v[60:61], v[80:81], v[96:97]
	v_mul_f32_e32 v59, v63, v59
	v_add_f32_e32 v63, 1.0, v99
	v_mul_f32_e32 v96, 0xbfb8aa3b, v61
	v_mul_f32_e32 v97, 0xbfb8aa3b, v60
	v_rcp_f32_e32 v63, v63
	v_exp_f32_e32 v96, v96
	v_exp_f32_e32 v97, v97
	v_mul_f32_e32 v62, v62, v63
	v_add_f32_e32 v63, 1.0, v96
	v_add_f32_e32 v96, 1.0, v97
	v_rcp_f32_e32 v63, v63
	v_rcp_f32_e32 v96, v96
	v_mul_f32_e32 v58, v62, v58
	v_mul_f32_e32 v61, v61, v63
	v_mul_f32_e32 v60, v60, v96
	v_mul_f32_e32 v57, v61, v57
	v_mul_f32_e32 v56, v60, v56
	v_cvt_pk_bf16_f32 v62, v56, v57
	v_cvt_pk_bf16_f32 v63, v58, v59
	v_mov_b64_e32 v[58:59], s[30:31]
	v_mad_i64_i32 v[58:59], s[0:1], v194, s67, v[58:59]
	v_lshl_add_u64 v[58:59], v[192:193], 1, v[58:59]
	v_mov_b32_e32 v60, v246
	v_mov_b32_e32 v61, v247
	global_store_dwordx4 v[58:59], v[60:63], off
.LBB0_712:
	s_or_b64 exec, exec, s[46:47]
	v_mov_b32_e32 v153, v152
	v_mov_b32_e32 v56, v152
	v_mov_b32_e32 v57, v152
	v_pk_fma_f32 v[54:55], v[54:55], v[56:57], v[46:47]
	v_pk_fma_f32 v[52:53], v[52:53], v[152:153], v[44:45]
	v_pk_fma_f32 v[50:51], v[50:51], v[56:57], v[42:43]
	v_pk_fma_f32 v[48:49], v[48:49], v[152:153], v[40:41]
	s_nop 1
	v_mov_b32_dpp v56, v52 row_ror:1 row_mask:0xf bank_mask:0xf
	v_mov_b32_dpp v60, v52 row_ror:2 row_mask:0xf bank_mask:0xf
	v_mov_b32_dpp v57, v53 row_ror:1 row_mask:0xf bank_mask:0xf
	v_mov_b32_dpp v61, v53 row_ror:2 row_mask:0xf bank_mask:0xf
	v_mov_b32_dpp v58, v54 row_ror:1 row_mask:0xf bank_mask:0xf
	v_mov_b32_dpp v62, v54 row_ror:2 row_mask:0xf bank_mask:0xf
	v_mov_b32_dpp v59, v55 row_ror:1 row_mask:0xf bank_mask:0xf
	v_mov_b32_dpp v63, v55 row_ror:2 row_mask:0xf bank_mask:0xf
	v_mov_b32_dpp v96, v48 row_ror:1 row_mask:0xf bank_mask:0xf
	v_mov_b32_dpp v98, v48 row_ror:2 row_mask:0xf bank_mask:0xf
	v_mov_b32_dpp v97, v49 row_ror:1 row_mask:0xf bank_mask:0xf
	v_mov_b32_dpp v100, v49 row_ror:2 row_mask:0xf bank_mask:0xf
	v_mov_b32_dpp v99, v50 row_ror:1 row_mask:0xf bank_mask:0xf
	v_mov_b32_dpp v102, v50 row_ror:2 row_mask:0xf bank_mask:0xf
	v_mov_b32_dpp v101, v51 row_ror:1 row_mask:0xf bank_mask:0xf
	v_mov_b32_dpp v103, v51 row_ror:2 row_mask:0xf bank_mask:0xf
	s_and_saveexec_b64 s[0:1], s[16:17]
	s_cbranch_execz .LBB0_714
	v_cndmask_b32_e64 v114, v114, v62, s[8:9]
	v_cndmask_b32_e64 v115, v115, v63, s[8:9]
	s_waitcnt vmcnt(5)
	v_pk_mul_f32 v[114:115], v[78:79], v[114:115]
	v_cndmask_b32_e64 v106, v58, v106, s[6:7]
	v_cndmask_b32_e64 v107, v59, v107, s[6:7]
	s_waitcnt vmcnt(3)
	v_pk_fma_f32 v[106:107], v[74:75], v[106:107], v[114:115]
	v_cndmask_b32_e64 v122, v122, v102, s[8:9]
	s_waitcnt vmcnt(1)
	v_pk_fma_f32 v[54:55], v[54:55], v[82:83], v[106:107]
	v_cndmask_b32_e64 v123, v123, v103, s[8:9]
	v_mul_f32_e32 v106, 0xbfb8aa3b, v55
	v_exp_f32_e32 v106, v106
	v_mul_f32_e32 v107, 0xbfb8aa3b, v54
	v_cndmask_b32_e64 v112, v112, v60, s[8:9]
	v_cndmask_b32_e64 v113, v113, v61, s[8:9]
	v_add_f32_e32 v106, 1.0, v106
	v_rcp_f32_e32 v106, v106
	v_exp_f32_e32 v107, v107
	v_cndmask_b32_e64 v124, v118, v98, s[8:9]
	v_cndmask_b32_e64 v118, v99, v119, s[6:7]
	v_cndmask_b32_e64 v119, v101, v121, s[6:7]
	v_pk_mul_f32 v[122:123], v[86:87], v[122:123]
	v_pk_mul_f32 v[112:113], v[76:77], v[112:113]
	v_cndmask_b32_e64 v104, v56, v104, s[6:7]
	v_cndmask_b32_e64 v105, v57, v105, s[6:7]
	v_pk_fma_f32 v[118:119], v[90:91], v[118:119], v[122:123]
	v_pk_fma_f32 v[104:105], v[72:73], v[104:105], v[112:113]
	s_waitcnt vmcnt(0)
	v_pk_fma_f32 v[50:51], v[50:51], v[94:95], v[118:119]
	v_pk_fma_f32 v[52:53], v[52:53], v[80:81], v[104:105]
	v_mul_f32_e32 v55, v55, v106
	v_mul_f32_e32 v51, v55, v51
	v_add_f32_e32 v55, 1.0, v107
	v_mul_f32_e32 v104, 0xbfb8aa3b, v53
	v_mul_f32_e32 v105, 0xbfb8aa3b, v52
	v_rcp_f32_e32 v55, v55
	v_exp_f32_e32 v104, v104
	v_exp_f32_e32 v105, v105
	v_cndmask_b32_e64 v125, v120, v100, s[8:9]
	v_mul_f32_e32 v54, v54, v55
	v_add_f32_e32 v55, 1.0, v104
	v_add_f32_e32 v104, 1.0, v105
	v_rcp_f32_e32 v55, v55
	v_rcp_f32_e32 v104, v104
	v_cndmask_b32_e64 v116, v96, v116, s[6:7]
	v_cndmask_b32_e64 v117, v97, v117, s[6:7]
	v_pk_mul_f32 v[120:121], v[84:85], v[124:125]
	v_mul_f32_e32 v53, v53, v55
	v_pk_fma_f32 v[116:117], v[88:89], v[116:117], v[120:121]
	v_mul_f32_e32 v52, v52, v104
	v_pk_fma_f32 v[48:49], v[48:49], v[92:93], v[116:117]
	v_mul_f32_e32 v50, v54, v50
	v_mul_f32_e32 v49, v53, v49
	v_mul_f32_e32 v48, v52, v48
	v_cvt_pk_bf16_f32 v54, v48, v49
	v_cvt_pk_bf16_f32 v55, v50, v51
	v_mov_b64_e32 v[50:51], s[30:31]
	v_mad_i64_i32 v[50:51], s[16:17], v154, s67, v[50:51]
	v_lshl_add_u64 v[50:51], v[192:193], 1, v[50:51]
	v_mov_b32_e32 v52, v248
	v_mov_b32_e32 v53, v249
	global_store_dwordx4 v[50:51], v[52:55], off
.LBB0_714:
	s_or_b64 exec, exec, s[0:1]
	v_mov_b32_e32 v145, v144
	v_mov_b32_e32 v48, v144
	v_mov_b32_e32 v49, v144
	v_pk_fma_f32 v[34:35], v[34:35], v[48:49], v[46:47]
	v_pk_fma_f32 v[32:33], v[32:33], v[144:145], v[44:45]
	v_pk_fma_f32 v[30:31], v[30:31], v[48:49], v[42:43]
	v_pk_fma_f32 v[28:29], v[28:29], v[144:145], v[40:41]
	s_nop 1
	v_mov_b32_dpp v48, v32 row_ror:1 row_mask:0xf bank_mask:0xf
	v_mov_b32_dpp v52, v32 row_ror:2 row_mask:0xf bank_mask:0xf
	v_mov_b32_dpp v49, v33 row_ror:1 row_mask:0xf bank_mask:0xf
	v_mov_b32_dpp v53, v33 row_ror:2 row_mask:0xf bank_mask:0xf
	v_mov_b32_dpp v50, v34 row_ror:1 row_mask:0xf bank_mask:0xf
	v_mov_b32_dpp v54, v34 row_ror:2 row_mask:0xf bank_mask:0xf
	v_mov_b32_dpp v51, v35 row_ror:1 row_mask:0xf bank_mask:0xf
	v_mov_b32_dpp v55, v35 row_ror:2 row_mask:0xf bank_mask:0xf
	v_mov_b32_dpp v104, v28 row_ror:1 row_mask:0xf bank_mask:0xf
	v_mov_b32_dpp v106, v28 row_ror:2 row_mask:0xf bank_mask:0xf
	v_mov_b32_dpp v105, v29 row_ror:1 row_mask:0xf bank_mask:0xf
	v_mov_b32_dpp v112, v29 row_ror:2 row_mask:0xf bank_mask:0xf
	v_mov_b32_dpp v107, v30 row_ror:1 row_mask:0xf bank_mask:0xf
	v_mov_b32_dpp v114, v30 row_ror:2 row_mask:0xf bank_mask:0xf
	v_mov_b32_dpp v113, v31 row_ror:1 row_mask:0xf bank_mask:0xf
	v_mov_b32_dpp v115, v31 row_ror:2 row_mask:0xf bank_mask:0xf
	s_and_saveexec_b64 s[0:1], s[18:19]
	s_cbranch_execz .LBB0_716
	v_cndmask_b32_e64 v62, v62, v54, s[8:9]
	v_cndmask_b32_e64 v63, v63, v55, s[8:9]
	s_waitcnt vmcnt(5)
	v_pk_mul_f32 v[62:63], v[78:79], v[62:63]
	v_cndmask_b32_e64 v58, v50, v58, s[6:7]
	v_cndmask_b32_e64 v59, v51, v59, s[6:7]
	s_waitcnt vmcnt(3)
	v_pk_fma_f32 v[58:59], v[74:75], v[58:59], v[62:63]
	v_cndmask_b32_e64 v102, v102, v114, s[8:9]
	s_waitcnt vmcnt(1)
	v_pk_fma_f32 v[34:35], v[34:35], v[82:83], v[58:59]
	v_cndmask_b32_e64 v103, v103, v115, s[8:9]
	v_mul_f32_e32 v58, 0xbfb8aa3b, v35
	v_exp_f32_e32 v58, v58
	v_mul_f32_e32 v59, 0xbfb8aa3b, v34
	v_cndmask_b32_e64 v60, v60, v52, s[8:9]
	v_cndmask_b32_e64 v61, v61, v53, s[8:9]
	v_add_f32_e32 v58, 1.0, v58
	v_rcp_f32_e32 v58, v58
	v_exp_f32_e32 v59, v59
	v_cndmask_b32_e64 v116, v98, v106, s[8:9]
	v_cndmask_b32_e64 v98, v107, v99, s[6:7]
	v_cndmask_b32_e64 v99, v113, v101, s[6:7]
	v_pk_mul_f32 v[102:103], v[86:87], v[102:103]
	v_pk_mul_f32 v[60:61], v[76:77], v[60:61]
	v_cndmask_b32_e64 v56, v48, v56, s[6:7]
	v_cndmask_b32_e64 v57, v49, v57, s[6:7]
	v_pk_fma_f32 v[98:99], v[90:91], v[98:99], v[102:103]
	v_pk_fma_f32 v[56:57], v[72:73], v[56:57], v[60:61]
	s_waitcnt vmcnt(0)
	v_pk_fma_f32 v[30:31], v[30:31], v[94:95], v[98:99]
	v_pk_fma_f32 v[32:33], v[32:33], v[80:81], v[56:57]
	v_mul_f32_e32 v35, v35, v58
	v_mul_f32_e32 v31, v35, v31
	v_add_f32_e32 v35, 1.0, v59
	v_mul_f32_e32 v56, 0xbfb8aa3b, v33
	v_mul_f32_e32 v57, 0xbfb8aa3b, v32
	v_rcp_f32_e32 v35, v35
	v_exp_f32_e32 v56, v56
	v_exp_f32_e32 v57, v57
	v_cndmask_b32_e64 v117, v100, v112, s[8:9]
	v_mul_f32_e32 v34, v34, v35
	v_add_f32_e32 v35, 1.0, v56
	v_add_f32_e32 v56, 1.0, v57
	v_rcp_f32_e32 v35, v35
	v_rcp_f32_e32 v56, v56
	v_cndmask_b32_e64 v96, v104, v96, s[6:7]
	v_cndmask_b32_e64 v97, v105, v97, s[6:7]
	v_pk_mul_f32 v[100:101], v[84:85], v[116:117]
	v_mul_f32_e32 v33, v33, v35
	v_pk_fma_f32 v[96:97], v[88:89], v[96:97], v[100:101]
	v_mul_f32_e32 v32, v32, v56
	v_pk_fma_f32 v[28:29], v[28:29], v[92:93], v[96:97]
	v_mul_f32_e32 v30, v34, v30
	v_mul_f32_e32 v29, v33, v29
	v_mul_f32_e32 v28, v32, v28
	v_cvt_pk_bf16_f32 v34, v28, v29
	v_cvt_pk_bf16_f32 v35, v30, v31
	v_mov_b64_e32 v[30:31], s[30:31]
	v_mad_i64_i32 v[30:31], s[16:17], v147, s67, v[30:31]
	v_lshl_add_u64 v[30:31], v[192:193], 1, v[30:31]
	v_mov_b32_e32 v32, v250
	v_mov_b32_e32 v33, v251
	global_store_dwordx4 v[30:31], v[32:35], off
.LBB0_716:
	s_or_b64 exec, exec, s[0:1]
	s_nop 1
	v_mov_b32_dpp v28, v64 row_ror:1 row_mask:0xf bank_mask:0xf
	v_mov_b32_dpp v32, v64 row_ror:2 row_mask:0xf bank_mask:0xf
	v_mov_b32_dpp v29, v65 row_ror:1 row_mask:0xf bank_mask:0xf
	v_mov_b32_dpp v33, v65 row_ror:2 row_mask:0xf bank_mask:0xf
	v_mov_b32_dpp v30, v66 row_ror:1 row_mask:0xf bank_mask:0xf
	v_mov_b32_dpp v34, v66 row_ror:2 row_mask:0xf bank_mask:0xf
	v_mov_b32_dpp v31, v67 row_ror:1 row_mask:0xf bank_mask:0xf
	v_mov_b32_dpp v35, v67 row_ror:2 row_mask:0xf bank_mask:0xf
	v_mov_b32_dpp v56, v68 row_ror:1 row_mask:0xf bank_mask:0xf
	v_mov_b32_dpp v58, v68 row_ror:2 row_mask:0xf bank_mask:0xf
	v_mov_b32_dpp v57, v69 row_ror:1 row_mask:0xf bank_mask:0xf
	v_mov_b32_dpp v60, v69 row_ror:2 row_mask:0xf bank_mask:0xf
	v_mov_b32_dpp v59, v70 row_ror:1 row_mask:0xf bank_mask:0xf
	v_mov_b32_dpp v62, v70 row_ror:2 row_mask:0xf bank_mask:0xf
	v_mov_b32_dpp v61, v71 row_ror:1 row_mask:0xf bank_mask:0xf
	v_mov_b32_dpp v63, v71 row_ror:2 row_mask:0xf bank_mask:0xf
	s_and_saveexec_b64 s[0:1], s[20:21]
	s_cbranch_execz .LBB0_718
	v_cndmask_b32_e64 v34, v54, v34, s[8:9]
	v_cndmask_b32_e64 v35, v55, v35, s[8:9]
	s_waitcnt vmcnt(5)
	v_pk_mul_f32 v[34:35], v[78:79], v[34:35]
	v_cndmask_b32_e64 v30, v30, v50, s[6:7]
	v_cndmask_b32_e64 v31, v31, v51, s[6:7]
	s_waitcnt vmcnt(3)
	v_pk_fma_f32 v[30:31], v[74:75], v[30:31], v[34:35]
	v_cndmask_b32_e64 v32, v52, v32, s[8:9]
	s_waitcnt vmcnt(1)
	v_pk_fma_f32 v[30:31], v[66:67], v[82:83], v[30:31]
	v_cndmask_b32_e64 v33, v53, v33, s[8:9]
	v_mul_f32_e32 v34, 0xbfb8aa3b, v31
	v_exp_f32_e32 v34, v34
	v_pk_mul_f32 v[32:33], v[76:77], v[32:33]
	v_cndmask_b32_e64 v28, v28, v48, s[6:7]
	v_cndmask_b32_e64 v29, v29, v49, s[6:7]
	v_pk_fma_f32 v[28:29], v[72:73], v[28:29], v[32:33]
	v_add_f32_e32 v32, 1.0, v34
	v_mul_f32_e32 v33, 0xbfb8aa3b, v30
	v_rcp_f32_e32 v32, v32
	v_exp_f32_e32 v33, v33
	v_pk_fma_f32 v[28:29], v[64:65], v[80:81], v[28:29]
	v_cndmask_b32_e64 v96, v106, v58, s[8:9]
	v_mul_f32_e32 v31, v31, v32
	v_add_f32_e32 v32, 1.0, v33
	v_mul_f32_e32 v33, 0xbfb8aa3b, v29
	v_mul_f32_e32 v34, 0xbfb8aa3b, v28
	v_rcp_f32_e32 v32, v32
	v_exp_f32_e32 v33, v33
	v_exp_f32_e32 v34, v34
	v_cndmask_b32_e64 v97, v112, v60, s[8:9]
	v_mul_f32_e32 v30, v30, v32
	v_add_f32_e32 v32, 1.0, v33
	v_add_f32_e32 v33, 1.0, v34
	v_rcp_f32_e32 v32, v32
	v_rcp_f32_e32 v33, v33
	v_cndmask_b32_e64 v62, v114, v62, s[8:9]
	v_cndmask_b32_e64 v63, v115, v63, s[8:9]
	v_cndmask_b32_e64 v56, v56, v104, s[6:7]
	v_cndmask_b32_e64 v57, v57, v105, s[6:7]
	v_cndmask_b32_e64 v58, v59, v107, s[6:7]
	v_cndmask_b32_e64 v59, v61, v113, s[6:7]
	v_pk_mul_f32 v[60:61], v[84:85], v[96:97]
	v_pk_mul_f32 v[62:63], v[86:87], v[62:63]
	v_pk_fma_f32 v[56:57], v[88:89], v[56:57], v[60:61]
	v_pk_fma_f32 v[58:59], v[90:91], v[58:59], v[62:63]
	s_waitcnt vmcnt(0)
	v_pk_fma_f32 v[56:57], v[68:69], v[92:93], v[56:57]
	v_pk_fma_f32 v[58:59], v[70:71], v[94:95], v[58:59]
	v_mul_f32_e32 v29, v29, v32
	v_mul_f32_e32 v28, v28, v33
	v_mul_f32_e32 v31, v31, v59
	v_mul_f32_e32 v30, v30, v58
	v_mul_f32_e32 v29, v29, v57
	v_mul_f32_e32 v28, v28, v56
	v_cvt_pk_bf16_f32 v58, v28, v29
	v_cvt_pk_bf16_f32 v59, v30, v31
	v_mov_b64_e32 v[30:31], s[30:31]
	v_mad_i64_i32 v[30:31], s[16:17], v109, s67, v[30:31]
	v_lshl_add_u64 v[30:31], v[192:193], 1, v[30:31]
	v_mov_b32_e32 v56, v252
	v_mov_b32_e32 v57, v253
	global_store_dwordx4 v[30:31], v[56:59], off
.LBB0_718:
	s_or_b64 exec, exec, s[0:1]
	v_mov_b32_e32 v109, v108
	v_mov_b32_e32 v28, v108
	v_mov_b32_e32 v29, v108
	v_pk_fma_f32 v[22:23], v[22:23], v[28:29], v[46:47]
	v_pk_fma_f32 v[20:21], v[20:21], v[108:109], v[44:45]
	v_pk_fma_f32 v[18:19], v[18:19], v[28:29], v[42:43]
	v_pk_fma_f32 v[16:17], v[16:17], v[108:109], v[40:41]
	s_nop 1
	v_mov_b32_dpp v28, v20 row_ror:1 row_mask:0xf bank_mask:0xf
	v_mov_b32_dpp v32, v20 row_ror:2 row_mask:0xf bank_mask:0xf
	v_mov_b32_dpp v29, v21 row_ror:1 row_mask:0xf bank_mask:0xf
	v_mov_b32_dpp v33, v21 row_ror:2 row_mask:0xf bank_mask:0xf
	v_mov_b32_dpp v30, v22 row_ror:1 row_mask:0xf bank_mask:0xf
	v_mov_b32_dpp v34, v22 row_ror:2 row_mask:0xf bank_mask:0xf
	v_mov_b32_dpp v31, v23 row_ror:1 row_mask:0xf bank_mask:0xf
	v_mov_b32_dpp v35, v23 row_ror:2 row_mask:0xf bank_mask:0xf
	v_mov_b32_dpp v48, v16 row_ror:1 row_mask:0xf bank_mask:0xf
	v_mov_b32_dpp v50, v16 row_ror:2 row_mask:0xf bank_mask:0xf
	v_mov_b32_dpp v49, v17 row_ror:1 row_mask:0xf bank_mask:0xf
	v_mov_b32_dpp v52, v17 row_ror:2 row_mask:0xf bank_mask:0xf
	v_mov_b32_dpp v51, v18 row_ror:1 row_mask:0xf bank_mask:0xf
	v_mov_b32_dpp v54, v18 row_ror:2 row_mask:0xf bank_mask:0xf
	v_mov_b32_dpp v53, v19 row_ror:1 row_mask:0xf bank_mask:0xf
	v_mov_b32_dpp v55, v19 row_ror:2 row_mask:0xf bank_mask:0xf
	s_and_saveexec_b64 s[0:1], s[22:23]
	s_cbranch_execz .LBB0_720
	ds_read_b128 v[56:59], v149 offset:304
	ds_read_b128 v[60:63], v149 offset:48
	ds_read_b128 v[64:67], v149 offset:16
	ds_read_b128 v[68:71], v149 offset:272
	s_waitcnt lgkmcnt(2)
	v_cndmask_b32_e64 v63, v59, v63, s[6:7]
	v_cndmask_b32_e64 v62, v58, v62, s[6:7]
	v_cndmask_b32_e64 v62, v62, v54, s[8:9]
	v_cndmask_b32_e64 v63, v63, v55, s[8:9]
	v_cndmask_b32_e64 v58, v51, v58, s[6:7]
	v_cndmask_b32_e64 v59, v53, v59, s[6:7]
	s_waitcnt vmcnt(4)
	v_pk_mul_f32 v[62:63], v[86:87], v[62:63]
	v_cndmask_b32_e64 v61, v57, v61, s[6:7]
	v_cndmask_b32_e64 v60, v56, v60, s[6:7]
	s_waitcnt vmcnt(2)
	v_pk_fma_f32 v[58:59], v[90:91], v[58:59], v[62:63]
	v_cndmask_b32_e64 v60, v60, v50, s[8:9]
	v_cndmask_b32_e64 v61, v61, v52, s[8:9]
	s_waitcnt vmcnt(0)
	v_pk_fma_f32 v[18:19], v[18:19], v[94:95], v[58:59]
	s_waitcnt lgkmcnt(0)
	v_cndmask_b32_e64 v59, v71, v67, s[6:7]
	v_cndmask_b32_e64 v58, v70, v66, s[6:7]
	v_cndmask_b32_e64 v56, v48, v56, s[6:7]
	v_cndmask_b32_e64 v57, v49, v57, s[6:7]
	v_pk_mul_f32 v[60:61], v[84:85], v[60:61]
	v_cndmask_b32_e64 v58, v58, v34, s[8:9]
	v_cndmask_b32_e64 v59, v59, v35, s[8:9]
	v_pk_fma_f32 v[56:57], v[88:89], v[56:57], v[60:61]
	v_pk_mul_f32 v[58:59], v[78:79], v[58:59]
	v_cndmask_b32_e64 v60, v30, v70, s[6:7]
	v_cndmask_b32_e64 v61, v31, v71, s[6:7]
	v_pk_fma_f32 v[58:59], v[74:75], v[60:61], v[58:59]
	v_pk_fma_f32 v[16:17], v[16:17], v[92:93], v[56:57]
	v_pk_fma_f32 v[22:23], v[22:23], v[82:83], v[58:59]
	v_cndmask_b32_e64 v57, v69, v65, s[6:7]
	v_mul_f32_e32 v58, 0xbfb8aa3b, v23
	v_exp_f32_e32 v60, v58
	v_cndmask_b32_e64 v56, v68, v64, s[6:7]
	v_cndmask_b32_e64 v56, v56, v32, s[8:9]
	v_cndmask_b32_e64 v57, v57, v33, s[8:9]
	v_pk_mul_f32 v[56:57], v[76:77], v[56:57]
	v_cndmask_b32_e64 v58, v28, v68, s[6:7]
	v_cndmask_b32_e64 v59, v29, v69, s[6:7]
	v_pk_fma_f32 v[56:57], v[72:73], v[58:59], v[56:57]
	v_add_f32_e32 v58, 1.0, v60
	v_rcp_f32_e32 v58, v58
	v_mul_f32_e32 v59, 0xbfb8aa3b, v22
	v_exp_f32_e32 v59, v59
	v_pk_fma_f32 v[20:21], v[20:21], v[80:81], v[56:57]
	v_mul_f32_e32 v23, v23, v58
	v_mul_f32_e32 v19, v19, v23
	v_add_f32_e32 v23, 1.0, v59
	v_mul_f32_e32 v56, 0xbfb8aa3b, v21
	v_mul_f32_e32 v57, 0xbfb8aa3b, v20
	v_rcp_f32_e32 v23, v23
	v_exp_f32_e32 v56, v56
	v_exp_f32_e32 v57, v57
	v_mul_f32_e32 v22, v22, v23
	v_add_f32_e32 v23, 1.0, v56
	v_add_f32_e32 v56, 1.0, v57
	v_rcp_f32_e32 v23, v23
	v_rcp_f32_e32 v56, v56
	v_mul_f32_e32 v18, v18, v22
	v_mul_f32_e32 v21, v21, v23
	v_mul_f32_e32 v20, v20, v56
	v_mul_f32_e32 v17, v17, v21
	v_mul_f32_e32 v16, v16, v20
	v_cvt_pk_bf16_f32 v22, v16, v17
	v_cvt_pk_bf16_f32 v23, v18, v19
	v_mov_b64_e32 v[18:19], s[30:31]
	v_mad_i64_i32 v[18:19], s[16:17], v111, s67, v[18:19]
	v_lshl_add_u64 v[18:19], v[192:193], 1, v[18:19]
	v_mov_b32_e32 v20, v174
	v_mov_b32_e32 v21, v175
	global_store_dwordx4 v[18:19], v[20:23], off
.LBB0_720:
	s_or_b64 exec, exec, s[0:1]
	v_mov_b32_e32 v147, v146
	v_mov_b32_e32 v16, v146
	v_mov_b32_e32 v17, v146
	v_pk_fma_f32 v[14:15], v[14:15], v[16:17], v[46:47]
	v_pk_fma_f32 v[12:13], v[12:13], v[146:147], v[44:45]
	v_pk_fma_f32 v[10:11], v[10:11], v[16:17], v[42:43]
	v_pk_fma_f32 v[8:9], v[8:9], v[146:147], v[40:41]
	s_nop 1
	v_mov_b32_dpp v16, v12 row_ror:1 row_mask:0xf bank_mask:0xf
	v_mov_b32_dpp v20, v12 row_ror:2 row_mask:0xf bank_mask:0xf
	v_mov_b32_dpp v17, v13 row_ror:1 row_mask:0xf bank_mask:0xf
	v_mov_b32_dpp v21, v13 row_ror:2 row_mask:0xf bank_mask:0xf
	v_mov_b32_dpp v18, v14 row_ror:1 row_mask:0xf bank_mask:0xf
	v_mov_b32_dpp v22, v14 row_ror:2 row_mask:0xf bank_mask:0xf
	v_mov_b32_dpp v19, v15 row_ror:1 row_mask:0xf bank_mask:0xf
	v_mov_b32_dpp v23, v15 row_ror:2 row_mask:0xf bank_mask:0xf
	v_mov_b32_dpp v56, v8 row_ror:1 row_mask:0xf bank_mask:0xf
	v_mov_b32_dpp v58, v8 row_ror:2 row_mask:0xf bank_mask:0xf
	v_mov_b32_dpp v57, v9 row_ror:1 row_mask:0xf bank_mask:0xf
	v_mov_b32_dpp v60, v9 row_ror:2 row_mask:0xf bank_mask:0xf
	v_mov_b32_dpp v59, v10 row_ror:1 row_mask:0xf bank_mask:0xf
	v_mov_b32_dpp v62, v10 row_ror:2 row_mask:0xf bank_mask:0xf
	v_mov_b32_dpp v61, v11 row_ror:1 row_mask:0xf bank_mask:0xf
	v_mov_b32_dpp v63, v11 row_ror:2 row_mask:0xf bank_mask:0xf
	s_and_saveexec_b64 s[0:1], s[24:25]
	s_cbranch_execz .LBB0_722
	v_cndmask_b32_e64 v34, v34, v22, s[8:9]
	v_cndmask_b32_e64 v35, v35, v23, s[8:9]
	s_waitcnt vmcnt(5)
	v_pk_mul_f32 v[34:35], v[78:79], v[34:35]
	v_cndmask_b32_e64 v30, v18, v30, s[6:7]
	v_cndmask_b32_e64 v31, v19, v31, s[6:7]
	s_waitcnt vmcnt(3)
	v_pk_fma_f32 v[30:31], v[74:75], v[30:31], v[34:35]
	v_cndmask_b32_e64 v54, v54, v62, s[8:9]
	s_waitcnt vmcnt(1)
	v_pk_fma_f32 v[14:15], v[14:15], v[82:83], v[30:31]
	v_cndmask_b32_e64 v55, v55, v63, s[8:9]
	v_mul_f32_e32 v30, 0xbfb8aa3b, v15
	v_exp_f32_e32 v30, v30
	v_mul_f32_e32 v31, 0xbfb8aa3b, v14
	v_cndmask_b32_e64 v32, v32, v20, s[8:9]
	v_cndmask_b32_e64 v33, v33, v21, s[8:9]
	v_add_f32_e32 v30, 1.0, v30
	v_rcp_f32_e32 v30, v30
	v_exp_f32_e32 v31, v31
	v_cndmask_b32_e64 v64, v50, v58, s[8:9]
	v_cndmask_b32_e64 v50, v59, v51, s[6:7]
	v_cndmask_b32_e64 v51, v61, v53, s[6:7]
	v_pk_mul_f32 v[54:55], v[86:87], v[54:55]
	v_pk_mul_f32 v[32:33], v[76:77], v[32:33]
	v_cndmask_b32_e64 v28, v16, v28, s[6:7]
	v_cndmask_b32_e64 v29, v17, v29, s[6:7]
	v_pk_fma_f32 v[50:51], v[90:91], v[50:51], v[54:55]
	v_pk_fma_f32 v[28:29], v[72:73], v[28:29], v[32:33]
	s_waitcnt vmcnt(0)
	v_pk_fma_f32 v[10:11], v[10:11], v[94:95], v[50:51]
	v_pk_fma_f32 v[12:13], v[12:13], v[80:81], v[28:29]
	v_mul_f32_e32 v15, v15, v30
	v_mul_f32_e32 v11, v15, v11
	v_add_f32_e32 v15, 1.0, v31
	v_mul_f32_e32 v28, 0xbfb8aa3b, v13
	v_mul_f32_e32 v29, 0xbfb8aa3b, v12
	v_rcp_f32_e32 v15, v15
	v_exp_f32_e32 v28, v28
	v_exp_f32_e32 v29, v29
	v_cndmask_b32_e64 v65, v52, v60, s[8:9]
	v_mul_f32_e32 v14, v14, v15
	v_add_f32_e32 v15, 1.0, v28
	v_add_f32_e32 v28, 1.0, v29
	v_rcp_f32_e32 v15, v15
	v_rcp_f32_e32 v28, v28
	v_cndmask_b32_e64 v48, v56, v48, s[6:7]
	v_cndmask_b32_e64 v49, v57, v49, s[6:7]
	v_pk_mul_f32 v[52:53], v[84:85], v[64:65]
	v_mul_f32_e32 v13, v13, v15
	v_pk_fma_f32 v[48:49], v[88:89], v[48:49], v[52:53]
	v_mul_f32_e32 v12, v12, v28
	v_pk_fma_f32 v[8:9], v[8:9], v[92:93], v[48:49]
	v_mul_f32_e32 v10, v14, v10
	v_mul_f32_e32 v9, v13, v9
	v_mul_f32_e32 v8, v12, v8
	v_cvt_pk_bf16_f32 v14, v8, v9
	v_cvt_pk_bf16_f32 v15, v10, v11
	v_mov_b64_e32 v[10:11], s[30:31]
	v_mad_i64_i32 v[10:11], s[16:17], v148, s67, v[10:11]
	v_lshl_add_u64 v[10:11], v[192:193], 1, v[10:11]
	v_mov_b32_e32 v12, v170
	v_mov_b32_e32 v13, v171
	global_store_dwordx4 v[10:11], v[12:15], off
.LBB0_722:
	s_or_b64 exec, exec, s[0:1]
	v_mov_b32_e32 v111, v110
	v_mov_b32_e32 v8, v110
	v_mov_b32_e32 v9, v110
	v_pk_fma_f32 v[6:7], v[6:7], v[8:9], v[46:47]
	v_pk_fma_f32 v[4:5], v[4:5], v[110:111], v[44:45]
	v_pk_fma_f32 v[2:3], v[2:3], v[8:9], v[42:43]
	v_pk_fma_f32 v[0:1], v[0:1], v[110:111], v[40:41]
	s_nop 1
	v_mov_b32_dpp v8, v4 row_ror:1 row_mask:0xf bank_mask:0xf
	v_mov_b32_dpp v12, v4 row_ror:2 row_mask:0xf bank_mask:0xf
	v_mov_b32_dpp v9, v5 row_ror:1 row_mask:0xf bank_mask:0xf
	v_mov_b32_dpp v13, v5 row_ror:2 row_mask:0xf bank_mask:0xf
	v_mov_b32_dpp v10, v6 row_ror:1 row_mask:0xf bank_mask:0xf
	v_mov_b32_dpp v14, v6 row_ror:2 row_mask:0xf bank_mask:0xf
	v_mov_b32_dpp v11, v7 row_ror:1 row_mask:0xf bank_mask:0xf
	v_mov_b32_dpp v15, v7 row_ror:2 row_mask:0xf bank_mask:0xf
	v_mov_b32_dpp v28, v0 row_ror:1 row_mask:0xf bank_mask:0xf
	v_mov_b32_dpp v32, v0 row_ror:2 row_mask:0xf bank_mask:0xf
	v_mov_b32_dpp v29, v1 row_ror:1 row_mask:0xf bank_mask:0xf
	v_mov_b32_dpp v33, v1 row_ror:2 row_mask:0xf bank_mask:0xf
	v_mov_b32_dpp v30, v2 row_ror:1 row_mask:0xf bank_mask:0xf
	v_mov_b32_dpp v34, v2 row_ror:2 row_mask:0xf bank_mask:0xf
	v_mov_b32_dpp v31, v3 row_ror:1 row_mask:0xf bank_mask:0xf
	v_mov_b32_dpp v35, v3 row_ror:2 row_mask:0xf bank_mask:0xf
	s_and_saveexec_b64 s[0:1], s[26:27]
	s_cbranch_execz .LBB0_724
	v_cndmask_b32_e64 v22, v22, v14, s[8:9]
	v_cndmask_b32_e64 v23, v23, v15, s[8:9]
	s_waitcnt vmcnt(5)
	v_pk_mul_f32 v[22:23], v[78:79], v[22:23]
	v_cndmask_b32_e64 v18, v10, v18, s[6:7]
	v_cndmask_b32_e64 v19, v11, v19, s[6:7]
	s_waitcnt vmcnt(3)
	v_pk_fma_f32 v[18:19], v[74:75], v[18:19], v[22:23]
	v_cndmask_b32_e64 v42, v62, v34, s[8:9]
	s_waitcnt vmcnt(1)
	v_pk_fma_f32 v[6:7], v[6:7], v[82:83], v[18:19]
	v_cndmask_b32_e64 v43, v63, v35, s[8:9]
	v_mul_f32_e32 v18, 0xbfb8aa3b, v7
	v_exp_f32_e32 v18, v18
	v_mul_f32_e32 v19, 0xbfb8aa3b, v6
	v_cndmask_b32_e64 v20, v20, v12, s[8:9]
	v_cndmask_b32_e64 v21, v21, v13, s[8:9]
	v_add_f32_e32 v18, 1.0, v18
	v_rcp_f32_e32 v18, v18
	v_exp_f32_e32 v19, v19
	v_cndmask_b32_e64 v46, v30, v59, s[6:7]
	v_cndmask_b32_e64 v47, v31, v61, s[6:7]
	v_pk_mul_f32 v[42:43], v[86:87], v[42:43]
	v_pk_mul_f32 v[20:21], v[76:77], v[20:21]
	v_cndmask_b32_e64 v16, v8, v16, s[6:7]
	v_cndmask_b32_e64 v17, v9, v17, s[6:7]
	v_pk_fma_f32 v[42:43], v[90:91], v[46:47], v[42:43]
	v_pk_fma_f32 v[16:17], v[72:73], v[16:17], v[20:21]
	s_waitcnt vmcnt(0)
	v_pk_fma_f32 v[2:3], v[2:3], v[94:95], v[42:43]
	v_pk_fma_f32 v[4:5], v[4:5], v[80:81], v[16:17]
	v_mul_f32_e32 v7, v7, v18
	v_mul_f32_e32 v3, v7, v3
	v_add_f32_e32 v7, 1.0, v19
	v_mul_f32_e32 v16, 0xbfb8aa3b, v5
	v_mul_f32_e32 v17, 0xbfb8aa3b, v4
	v_rcp_f32_e32 v7, v7
	v_exp_f32_e32 v16, v16
	v_exp_f32_e32 v17, v17
	v_cndmask_b32_e64 v40, v58, v32, s[8:9]
	v_mul_f32_e32 v6, v6, v7
	v_add_f32_e32 v7, 1.0, v16
	v_add_f32_e32 v16, 1.0, v17
	v_rcp_f32_e32 v7, v7
	v_rcp_f32_e32 v16, v16
	v_cndmask_b32_e64 v41, v60, v33, s[8:9]
	v_cndmask_b32_e64 v44, v28, v56, s[6:7]
	v_cndmask_b32_e64 v45, v29, v57, s[6:7]
	v_pk_mul_f32 v[40:41], v[84:85], v[40:41]
	v_mul_f32_e32 v5, v5, v7
	v_pk_fma_f32 v[40:41], v[88:89], v[44:45], v[40:41]
	v_mul_f32_e32 v4, v4, v16
	v_pk_fma_f32 v[0:1], v[0:1], v[92:93], v[40:41]
	v_mul_f32_e32 v2, v6, v2
	v_mul_f32_e32 v1, v5, v1
	v_mul_f32_e32 v0, v4, v0
	v_cvt_pk_bf16_f32 v6, v0, v1
	v_cvt_pk_bf16_f32 v7, v2, v3
	v_mov_b64_e32 v[2:3], s[30:31]
	v_mad_i64_i32 v[2:3], s[16:17], v136, s67, v[2:3]
	v_lshl_add_u64 v[2:3], v[192:193], 1, v[2:3]
	v_mov_b32_e32 v4, v172
	v_mov_b32_e32 v5, v173
	global_store_dwordx4 v[2:3], v[4:7], off
.LBB0_724:
	s_or_b64 exec, exec, s[0:1]
	s_nop 1
	v_mov_b32_dpp v0, v24 row_ror:1 row_mask:0xf bank_mask:0xf
	v_mov_b32_dpp v4, v24 row_ror:2 row_mask:0xf bank_mask:0xf
	v_mov_b32_dpp v1, v25 row_ror:1 row_mask:0xf bank_mask:0xf
	v_mov_b32_dpp v5, v25 row_ror:2 row_mask:0xf bank_mask:0xf
	v_mov_b32_dpp v2, v26 row_ror:1 row_mask:0xf bank_mask:0xf
	v_mov_b32_dpp v6, v26 row_ror:2 row_mask:0xf bank_mask:0xf
	v_mov_b32_dpp v3, v27 row_ror:1 row_mask:0xf bank_mask:0xf
	v_mov_b32_dpp v7, v27 row_ror:2 row_mask:0xf bank_mask:0xf
	v_mov_b32_dpp v16, v36 row_ror:1 row_mask:0xf bank_mask:0xf
	v_mov_b32_dpp v20, v36 row_ror:2 row_mask:0xf bank_mask:0xf
	v_mov_b32_dpp v17, v37 row_ror:1 row_mask:0xf bank_mask:0xf
	v_mov_b32_dpp v21, v37 row_ror:2 row_mask:0xf bank_mask:0xf
	v_mov_b32_dpp v18, v38 row_ror:1 row_mask:0xf bank_mask:0xf
	v_mov_b32_dpp v22, v38 row_ror:2 row_mask:0xf bank_mask:0xf
	v_mov_b32_dpp v19, v39 row_ror:1 row_mask:0xf bank_mask:0xf
	v_mov_b32_dpp v23, v39 row_ror:2 row_mask:0xf bank_mask:0xf
	s_and_saveexec_b64 s[0:1], s[28:29]
	s_cbranch_execz .LBB0_726
	v_cndmask_b32_e64 v6, v14, v6, s[8:9]
	v_cndmask_b32_e64 v7, v15, v7, s[8:9]
	s_waitcnt vmcnt(5)
	v_pk_mul_f32 v[6:7], v[78:79], v[6:7]
	v_cndmask_b32_e64 v2, v2, v10, s[6:7]
	v_cndmask_b32_e64 v3, v3, v11, s[6:7]
	s_waitcnt vmcnt(3)
	v_pk_fma_f32 v[2:3], v[74:75], v[2:3], v[6:7]
	v_cndmask_b32_e64 v4, v12, v4, s[8:9]
	s_waitcnt vmcnt(1)
	v_pk_fma_f32 v[2:3], v[26:27], v[82:83], v[2:3]
	v_cndmask_b32_e64 v5, v13, v5, s[8:9]
	v_mul_f32_e32 v6, 0xbfb8aa3b, v3
	v_exp_f32_e32 v6, v6
	v_pk_mul_f32 v[4:5], v[76:77], v[4:5]
	v_cndmask_b32_e64 v0, v0, v8, s[6:7]
	v_cndmask_b32_e64 v1, v1, v9, s[6:7]
	v_pk_fma_f32 v[0:1], v[72:73], v[0:1], v[4:5]
	v_add_f32_e32 v4, 1.0, v6
	v_mul_f32_e32 v5, 0xbfb8aa3b, v2
	v_rcp_f32_e32 v4, v4
	v_exp_f32_e32 v5, v5
	v_pk_fma_f32 v[0:1], v[24:25], v[80:81], v[0:1]
	v_cndmask_b32_e64 v20, v32, v20, s[8:9]
	v_mul_f32_e32 v3, v3, v4
	v_add_f32_e32 v4, 1.0, v5
	v_mul_f32_e32 v5, 0xbfb8aa3b, v1
	v_mul_f32_e32 v6, 0xbfb8aa3b, v0
	v_rcp_f32_e32 v4, v4
	v_exp_f32_e32 v5, v5
	v_exp_f32_e32 v6, v6
	v_cndmask_b32_e64 v21, v33, v21, s[8:9]
	v_mul_f32_e32 v2, v2, v4
	v_add_f32_e32 v4, 1.0, v5
	v_add_f32_e32 v5, 1.0, v6
	v_rcp_f32_e32 v4, v4
	v_rcp_f32_e32 v5, v5
	v_cndmask_b32_e64 v22, v34, v22, s[8:9]
	v_cndmask_b32_e64 v23, v35, v23, s[8:9]
	v_pk_mul_f32 v[20:21], v[84:85], v[20:21]
	v_pk_mul_f32 v[22:23], v[86:87], v[22:23]
	v_cndmask_b32_e64 v16, v16, v28, s[6:7]
	v_cndmask_b32_e64 v17, v17, v29, s[6:7]
	v_cndmask_b32_e64 v18, v18, v30, s[6:7]
	v_cndmask_b32_e64 v19, v19, v31, s[6:7]
	v_pk_fma_f32 v[18:19], v[90:91], v[18:19], v[22:23]
	v_pk_fma_f32 v[16:17], v[88:89], v[16:17], v[20:21]
	s_waitcnt vmcnt(0)
	v_pk_fma_f32 v[18:19], v[38:39], v[94:95], v[18:19]
	v_pk_fma_f32 v[16:17], v[36:37], v[92:93], v[16:17]
	v_mul_f32_e32 v1, v1, v4
	v_mul_f32_e32 v0, v0, v5
	v_mul_f32_e32 v3, v3, v19
	v_mul_f32_e32 v2, v2, v18
	v_mul_f32_e32 v1, v1, v17
	v_mul_f32_e32 v0, v0, v16
	v_cvt_pk_bf16_f32 v18, v0, v1
	v_cvt_pk_bf16_f32 v19, v2, v3
	v_mov_b64_e32 v[2:3], s[30:31]
	v_mad_i64_i32 v[2:3], s[16:17], v137, s67, v[2:3]
	v_lshl_add_u64 v[2:3], v[192:193], 1, v[2:3]
	v_mov_b32_e32 v16, v155
	v_mov_b32_e32 v17, v160
	global_store_dwordx4 v[2:3], v[16:19], off

.Lsprio_p11:
.LBB0_806:
	ds_read_b128 v[144:147], v161
	ds_read_b128 v[148:151], v161 offset:1024
	ds_read_b128 v[152:155], v161 offset:2048
	ds_read_b128 v[164:167], v161 offset:3072
	ds_read_b128 v[168:171], v162
	ds_read_b128 v[172:175], v162 offset:1024
	ds_read_b128 v[176:179], v162 offset:2048
	ds_read_b128 v[180:183], v162 offset:3072
	s_add_u32 s28, s26, 0xfff50080
	s_addc_u32 s29, s27, -1
	s_cmp_eq_u32 s55, 40
	s_cselect_b32 s35, s5, s29
	s_cselect_b32 s34, s4, s28
	s_cselect_b32 s29, s25, s54
	s_cselect_b32 s28, s24, s53
	s_add_i32 m0, s37, 0xc000
	ds_read_b128 v[184:187], v163
	ds_read_b128 v[188:191], v163 offset:1024
	ds_read_b128 v[192:195], v163 offset:2048
	ds_read_b128 v[196:199], v163 offset:3072
	ds_read_b128 v[200:203], v163 offset:4096
	ds_read_b128 v[204:207], v163 offset:5120
	ds_read_b128 v[208:211], v163 offset:6144
	ds_read_b128 v[212:215], v163 offset:7168
	global_load_lds_dwordx4 v136, s[26:27]
	s_add_i32 m0, s37, 0xe000
	s_nop 0
	global_load_lds_dwordx4 v138, s[26:27]
	s_waitcnt vmcnt(8)
	s_waitcnt lgkmcnt(0)
	s_barrier
	s_waitcnt lgkmcnt(0)
	v_mfma_f32_16x16x32_bf16 v[124:127], v[144:147], v[184:187], v[124:127]
	v_mfma_f32_16x16x32_bf16 v[120:123], v[152:155], v[184:187], v[120:123]
	v_mfma_f32_16x16x32_bf16 v[108:111], v[144:147], v[192:195], v[108:111]
	v_mfma_f32_16x16x32_bf16 v[104:107], v[152:155], v[192:195], v[104:107]
	v_mfma_f32_16x16x32_bf16 v[92:95], v[144:147], v[200:203], v[92:95]
	v_mfma_f32_16x16x32_bf16 v[88:91], v[152:155], v[200:203], v[88:91]
	v_mfma_f32_16x16x32_bf16 v[76:79], v[144:147], v[208:211], v[76:79]
	v_mfma_f32_16x16x32_bf16 v[72:75], v[152:155], v[208:211], v[72:75]
	v_mfma_f32_16x16x32_bf16 v[124:127], v[148:151], v[188:191], v[124:127]
	v_mfma_f32_16x16x32_bf16 v[120:123], v[164:167], v[188:191], v[120:123]
	v_mfma_f32_16x16x32_bf16 v[108:111], v[148:151], v[196:199], v[108:111]
	v_mfma_f32_16x16x32_bf16 v[104:107], v[164:167], v[196:199], v[104:107]
	v_mfma_f32_16x16x32_bf16 v[92:95], v[148:151], v[204:207], v[92:95]
	v_mfma_f32_16x16x32_bf16 v[88:91], v[164:167], v[204:207], v[88:91]
	v_mfma_f32_16x16x32_bf16 v[76:79], v[148:151], v[212:215], v[76:79]
	v_mfma_f32_16x16x32_bf16 v[72:75], v[164:167], v[212:215], v[72:75]
	v_mfma_f32_16x16x32_bf16 v[116:119], v[168:171], v[184:187], v[116:119]
	v_mfma_f32_16x16x32_bf16 v[112:115], v[176:179], v[184:187], v[112:115]
	v_mfma_f32_16x16x32_bf16 v[100:103], v[168:171], v[192:195], v[100:103]
	v_mfma_f32_16x16x32_bf16 v[96:99], v[176:179], v[192:195], v[96:99]
	v_mfma_f32_16x16x32_bf16 v[84:87], v[168:171], v[200:203], v[84:87]
	v_mfma_f32_16x16x32_bf16 v[80:83], v[176:179], v[200:203], v[80:83]
	v_mfma_f32_16x16x32_bf16 v[68:71], v[168:171], v[208:211], v[68:71]
	v_mfma_f32_16x16x32_bf16 v[64:67], v[176:179], v[208:211], v[64:67]
	v_mfma_f32_16x16x32_bf16 v[116:119], v[172:175], v[188:191], v[116:119]
	v_mfma_f32_16x16x32_bf16 v[112:115], v[180:183], v[188:191], v[112:115]
	v_mfma_f32_16x16x32_bf16 v[100:103], v[172:175], v[196:199], v[100:103]
	v_mfma_f32_16x16x32_bf16 v[96:99], v[180:183], v[196:199], v[96:99]
	v_mfma_f32_16x16x32_bf16 v[84:87], v[172:175], v[204:207], v[84:87]
	v_mfma_f32_16x16x32_bf16 v[80:83], v[180:183], v[204:207], v[80:83]
	v_mfma_f32_16x16x32_bf16 v[68:71], v[172:175], v[212:215], v[68:71]
	v_mfma_f32_16x16x32_bf16 v[64:67], v[180:183], v[212:215], v[64:67]
	s_barrier
	s_add_i32 s56, s47, s36
	v_lshl_add_u64 v[156:157], s[28:29], 0, v[130:131]
	s_mov_b32 m0, s56
	ds_read_b128 v[184:187], v163 offset:16384
	ds_read_b128 v[188:191], v163 offset:17408
	ds_read_b128 v[192:195], v163 offset:18432
	ds_read_b128 v[196:199], v163 offset:19456
	ds_read_b128 v[200:203], v163 offset:20480
	ds_read_b128 v[204:207], v163 offset:21504
	ds_read_b128 v[208:211], v163 offset:22528
	ds_read_b128 v[212:215], v163 offset:23552
	global_load_lds_dwordx4 v130, s[28:29]
	s_add_i32 m0, s56, 0x2000
	s_add_u32 s56, s28, 0xb0000
	v_lshl_add_u64 v[216:217], s[28:29], 0, v[134:135]
	s_addc_u32 s57, s29, 0
	s_add_i32 s58, s48, s36
	global_load_lds_dwordx4 v134, s[28:29]
	s_mov_b32 m0, s58
	v_lshl_add_u64 v[220:221], s[34:35], 0, v[132:133]
	global_load_lds_dwordx4 v130, s[56:57]
	s_add_i32 m0, s58, 0x2000
	s_nop 0
	global_load_lds_dwordx4 v134, s[56:57]
	v_lshl_add_u64 v[218:219], s[34:35], 0, v[128:129]
	s_mov_b32 m0, s37
	s_nop 0
	global_load_lds_dwordx4 v128, s[34:35]
	s_mov_b32 m0, s38
	s_nop 0
	global_load_lds_dwordx4 v132, s[34:35]
	s_waitcnt vmcnt(8)
	s_waitcnt lgkmcnt(0)
	s_barrier
	s_waitcnt lgkmcnt(0)
	v_mfma_f32_16x16x32_bf16 v[60:63], v[144:147], v[184:187], v[60:63]
	v_mfma_f32_16x16x32_bf16 v[56:59], v[152:155], v[184:187], v[56:59]
	v_mfma_f32_16x16x32_bf16 v[44:47], v[144:147], v[192:195], v[44:47]
	v_mfma_f32_16x16x32_bf16 v[40:43], v[152:155], v[192:195], v[40:43]
	v_mfma_f32_16x16x32_bf16 v[28:31], v[144:147], v[200:203], v[28:31]
	v_mfma_f32_16x16x32_bf16 v[24:27], v[152:155], v[200:203], v[24:27]
	v_mfma_f32_16x16x32_bf16 v[12:15], v[144:147], v[208:211], v[12:15]
	v_mfma_f32_16x16x32_bf16 v[8:11], v[152:155], v[208:211], v[8:11]
	v_mfma_f32_16x16x32_bf16 v[60:63], v[148:151], v[188:191], v[60:63]
	v_mfma_f32_16x16x32_bf16 v[56:59], v[164:167], v[188:191], v[56:59]
	v_mfma_f32_16x16x32_bf16 v[44:47], v[148:151], v[196:199], v[44:47]
	v_mfma_f32_16x16x32_bf16 v[40:43], v[164:167], v[196:199], v[40:43]
	v_mfma_f32_16x16x32_bf16 v[28:31], v[148:151], v[204:207], v[28:31]
	v_mfma_f32_16x16x32_bf16 v[24:27], v[164:167], v[204:207], v[24:27]
	v_mfma_f32_16x16x32_bf16 v[12:15], v[148:151], v[212:215], v[12:15]
	v_mfma_f32_16x16x32_bf16 v[8:11], v[164:167], v[212:215], v[8:11]
	v_mfma_f32_16x16x32_bf16 v[52:55], v[168:171], v[184:187], v[52:55]
	v_mfma_f32_16x16x32_bf16 v[48:51], v[176:179], v[184:187], v[48:51]
	v_mfma_f32_16x16x32_bf16 v[36:39], v[168:171], v[192:195], v[36:39]
	v_mfma_f32_16x16x32_bf16 v[32:35], v[176:179], v[192:195], v[32:35]
	v_mfma_f32_16x16x32_bf16 v[20:23], v[168:171], v[200:203], v[20:23]
	v_mfma_f32_16x16x32_bf16 v[16:19], v[176:179], v[200:203], v[16:19]
	v_mfma_f32_16x16x32_bf16 v[4:7], v[168:171], v[208:211], v[4:7]
	v_mfma_f32_16x16x32_bf16 v[0:3], v[176:179], v[208:211], v[0:3]
	v_mfma_f32_16x16x32_bf16 v[52:55], v[172:175], v[188:191], v[52:55]
	v_mfma_f32_16x16x32_bf16 v[48:51], v[180:183], v[188:191], v[48:51]
	v_mfma_f32_16x16x32_bf16 v[36:39], v[172:175], v[196:199], v[36:39]
	v_mfma_f32_16x16x32_bf16 v[32:35], v[180:183], v[196:199], v[32:35]
	v_mfma_f32_16x16x32_bf16 v[20:23], v[172:175], v[204:207], v[20:23]
	v_mfma_f32_16x16x32_bf16 v[16:19], v[180:183], v[204:207], v[16:19]
	v_mfma_f32_16x16x32_bf16 v[4:7], v[172:175], v[212:215], v[4:7]
	v_mfma_f32_16x16x32_bf16 v[0:3], v[180:183], v[212:215], v[0:3]
	s_barrier
	s_add_i32 s56, 0, 0x18000
	s_add_i32 s57, 0, 0x1c000
	v_add_u32_e32 v164, s56, v159
	v_add_u32_e32 v180, s57, v159
	ds_read_b128 v[144:147], v164
	ds_read_b128 v[148:151], v164 offset:1024
	ds_read_b128 v[152:155], v164 offset:2048
	ds_read_b128 v[164:167], v164 offset:3072
	ds_read_b128 v[168:171], v180
	ds_read_b128 v[172:175], v180 offset:1024
	ds_read_b128 v[176:179], v180 offset:2048
	ds_read_b128 v[180:183], v180 offset:3072
	s_add_u32 s34, s34, 0xb0000
	s_addc_u32 s35, s35, 0
	s_mov_b32 m0, s39
	ds_read_b128 v[184:187], v163 offset:32768
	ds_read_b128 v[188:191], v163 offset:33792
	ds_read_b128 v[192:195], v163 offset:34816
	ds_read_b128 v[196:199], v163 offset:35840
	ds_read_b128 v[200:203], v163 offset:36864
	ds_read_b128 v[204:207], v163 offset:37888
	ds_read_b128 v[208:211], v163 offset:38912
	ds_read_b128 v[212:215], v163 offset:39936
	global_load_lds_dwordx4 v128, s[34:35]
	s_mov_b32 m0, s40
	s_nop 0
	global_load_lds_dwordx4 v132, s[34:35]
	s_waitcnt vmcnt(8)
	s_waitcnt lgkmcnt(0)
	s_barrier
	s_waitcnt lgkmcnt(0)
	v_mfma_f32_16x16x32_bf16 v[124:127], v[144:147], v[184:187], v[124:127]
	v_mfma_f32_16x16x32_bf16 v[120:123], v[152:155], v[184:187], v[120:123]
	v_mfma_f32_16x16x32_bf16 v[108:111], v[144:147], v[192:195], v[108:111]
	v_mfma_f32_16x16x32_bf16 v[104:107], v[152:155], v[192:195], v[104:107]
	v_mfma_f32_16x16x32_bf16 v[92:95], v[144:147], v[200:203], v[92:95]
	v_mfma_f32_16x16x32_bf16 v[88:91], v[152:155], v[200:203], v[88:91]
	v_mfma_f32_16x16x32_bf16 v[76:79], v[144:147], v[208:211], v[76:79]
	v_mfma_f32_16x16x32_bf16 v[72:75], v[152:155], v[208:211], v[72:75]
	v_mfma_f32_16x16x32_bf16 v[124:127], v[148:151], v[188:191], v[124:127]
	v_mfma_f32_16x16x32_bf16 v[120:123], v[164:167], v[188:191], v[120:123]
	v_mfma_f32_16x16x32_bf16 v[108:111], v[148:151], v[196:199], v[108:111]
	v_mfma_f32_16x16x32_bf16 v[104:107], v[164:167], v[196:199], v[104:107]
	v_mfma_f32_16x16x32_bf16 v[92:95], v[148:151], v[204:207], v[92:95]
	v_mfma_f32_16x16x32_bf16 v[88:91], v[164:167], v[204:207], v[88:91]
	v_mfma_f32_16x16x32_bf16 v[76:79], v[148:151], v[212:215], v[76:79]
	v_mfma_f32_16x16x32_bf16 v[72:75], v[164:167], v[212:215], v[72:75]
	v_mfma_f32_16x16x32_bf16 v[116:119], v[168:171], v[184:187], v[116:119]
	v_mfma_f32_16x16x32_bf16 v[112:115], v[176:179], v[184:187], v[112:115]
	v_mfma_f32_16x16x32_bf16 v[100:103], v[168:171], v[192:195], v[100:103]
	v_mfma_f32_16x16x32_bf16 v[96:99], v[176:179], v[192:195], v[96:99]
	v_mfma_f32_16x16x32_bf16 v[84:87], v[168:171], v[200:203], v[84:87]
	v_mfma_f32_16x16x32_bf16 v[80:83], v[176:179], v[200:203], v[80:83]
	v_mfma_f32_16x16x32_bf16 v[68:71], v[168:171], v[208:211], v[68:71]
	v_mfma_f32_16x16x32_bf16 v[64:67], v[176:179], v[208:211], v[64:67]
	v_mfma_f32_16x16x32_bf16 v[116:119], v[172:175], v[188:191], v[116:119]
	v_mfma_f32_16x16x32_bf16 v[112:115], v[180:183], v[188:191], v[112:115]
	v_mfma_f32_16x16x32_bf16 v[100:103], v[172:175], v[196:199], v[100:103]
	v_mfma_f32_16x16x32_bf16 v[96:99], v[180:183], v[196:199], v[96:99]
	v_mfma_f32_16x16x32_bf16 v[84:87], v[172:175], v[204:207], v[84:87]
	v_mfma_f32_16x16x32_bf16 v[80:83], v[180:183], v[204:207], v[80:83]
	v_mfma_f32_16x16x32_bf16 v[68:71], v[172:175], v[212:215], v[68:71]
	v_mfma_f32_16x16x32_bf16 v[64:67], v[180:183], v[212:215], v[64:67]
	s_barrier
	s_add_i32 s34, s56, s36
	v_lshl_add_u64 v[156:157], v[156:157], 0, s[10:11]
	s_mov_b32 m0, s34
	ds_read_b128 v[184:187], v163 offset:49152
	ds_read_b128 v[188:191], v163 offset:50176
	ds_read_b128 v[192:195], v163 offset:51200
	ds_read_b128 v[196:199], v163 offset:52224
	ds_read_b128 v[200:203], v163 offset:53248
	ds_read_b128 v[204:207], v163 offset:54272
	ds_read_b128 v[208:211], v163 offset:55296
	ds_read_b128 v[212:215], v163 offset:56320
	global_load_lds_dwordx4 v[156:157], off
	s_add_i32 m0, s34, 0x2000
	s_add_u32 s28, s28, 0xb0080
	v_lshl_add_u64 v[216:217], v[216:217], 0, s[10:11]
	s_addc_u32 s29, s29, 0
	s_add_i32 s34, s57, s36
	global_load_lds_dwordx4 v[216:217], off
	s_mov_b32 m0, s34
	s_nop 0
	global_load_lds_dwordx4 v130, s[28:29]
	s_add_i32 m0, s34, 0x2000
	s_nop 0
	global_load_lds_dwordx4 v134, s[28:29]
	v_lshl_add_u64 v[218:219], v[218:219], 0, s[10:11]
	s_mov_b32 m0, s44
	s_nop 0
	global_load_lds_dwordx4 v[218:219], off
	v_lshl_add_u64 v[220:221], v[220:221], 0, s[10:11]
	s_mov_b32 m0, s45
	s_nop 0
	global_load_lds_dwordx4 v[220:221], off
	s_waitcnt vmcnt(8)
	s_waitcnt lgkmcnt(0)
	s_barrier
	s_waitcnt lgkmcnt(0)
	v_mfma_f32_16x16x32_bf16 v[60:63], v[144:147], v[184:187], v[60:63]
	v_mfma_f32_16x16x32_bf16 v[56:59], v[152:155], v[184:187], v[56:59]
	v_mfma_f32_16x16x32_bf16 v[44:47], v[144:147], v[192:195], v[44:47]
	v_mfma_f32_16x16x32_bf16 v[40:43], v[152:155], v[192:195], v[40:43]
	v_mfma_f32_16x16x32_bf16 v[28:31], v[144:147], v[200:203], v[28:31]
	v_mfma_f32_16x16x32_bf16 v[24:27], v[152:155], v[200:203], v[24:27]
	v_mfma_f32_16x16x32_bf16 v[12:15], v[144:147], v[208:211], v[12:15]
	v_mfma_f32_16x16x32_bf16 v[8:11], v[152:155], v[208:211], v[8:11]
	v_mfma_f32_16x16x32_bf16 v[60:63], v[148:151], v[188:191], v[60:63]
	s_add_i32 s55, s55, 2
	s_add_u32 s26, s26, 0x100
	s_addc_u32 s27, s27, 0
	s_add_u32 s53, s53, 0x100
	s_addc_u32 s54, s54, 0
	s_cmp_gt_u32 s55, 41
	v_mfma_f32_16x16x32_bf16 v[56:59], v[164:167], v[188:191], v[56:59]
	v_mfma_f32_16x16x32_bf16 v[44:47], v[148:151], v[196:199], v[44:47]
	v_mfma_f32_16x16x32_bf16 v[40:43], v[164:167], v[196:199], v[40:43]
	v_mfma_f32_16x16x32_bf16 v[28:31], v[148:151], v[204:207], v[28:31]
	v_mfma_f32_16x16x32_bf16 v[24:27], v[164:167], v[204:207], v[24:27]
	v_mfma_f32_16x16x32_bf16 v[12:15], v[148:151], v[212:215], v[12:15]
	v_mfma_f32_16x16x32_bf16 v[8:11], v[164:167], v[212:215], v[8:11]
	v_mfma_f32_16x16x32_bf16 v[52:55], v[168:171], v[184:187], v[52:55]
	v_mfma_f32_16x16x32_bf16 v[48:51], v[176:179], v[184:187], v[48:51]
	v_mfma_f32_16x16x32_bf16 v[36:39], v[168:171], v[192:195], v[36:39]
	v_mfma_f32_16x16x32_bf16 v[32:35], v[176:179], v[192:195], v[32:35]
	v_mfma_f32_16x16x32_bf16 v[20:23], v[168:171], v[200:203], v[20:23]
	v_mfma_f32_16x16x32_bf16 v[16:19], v[176:179], v[200:203], v[16:19]
	v_mfma_f32_16x16x32_bf16 v[4:7], v[168:171], v[208:211], v[4:7]
	v_mfma_f32_16x16x32_bf16 v[0:3], v[176:179], v[208:211], v[0:3]
	v_mfma_f32_16x16x32_bf16 v[52:55], v[172:175], v[188:191], v[52:55]
	v_mfma_f32_16x16x32_bf16 v[48:51], v[180:183], v[188:191], v[48:51]
	v_mfma_f32_16x16x32_bf16 v[36:39], v[172:175], v[196:199], v[36:39]
	v_mfma_f32_16x16x32_bf16 v[32:35], v[180:183], v[196:199], v[32:35]
	v_mfma_f32_16x16x32_bf16 v[20:23], v[172:175], v[204:207], v[20:23]
	v_mfma_f32_16x16x32_bf16 v[16:19], v[180:183], v[204:207], v[16:19]
	v_mfma_f32_16x16x32_bf16 v[4:7], v[172:175], v[212:215], v[4:7]
	v_mfma_f32_16x16x32_bf16 v[0:3], v[180:183], v[212:215], v[0:3]
	s_barrier
	s_cbranch_scc0 .LBB0_806
	s_setprio 0
	s_and_b64 vcc, exec, s[12:13]
	s_cbranch_vccz .LBB0_809
	s_barrier
